# 64-deep k-chunk operand sets with the barrier at mid-step: every fragment prefetched half a step ahead (no late reads), next set requested right after the barrier; FFN-up, FFN-down, out-proj
# speedup vs baseline: 1.0015x; 1.0015x over previous
.Lhw_outproj_tloop:
	s_cmpk_gt_u32 s16, 47
	s_cbranch_scc1 .Lhw_outproj_exit
	v_readlane_b32 s6, v246, 16
	s_lshr_b32 s2, s16, 2
	s_and_b32 s15, s16, 3
	s_add_i32 s6, s6, s2
	s_lshl_b32 s6, s6, 7
	s_lshl_b32 s15, s15, 8
	s_mul_i32 vcc_lo, s6, 0x800
	s_add_u32 s66, s42, vcc_lo
	s_addc_u32 s67, s43, 0
	s_mul_i32 vcc_lo, s15, 0x800
	s_add_u32 s62, s46, vcc_lo
	s_addc_u32 s63, s47, 0
	s_add_u32 s18, s62, 0x40000
	s_addc_u32 s19, s63, 0
	s_barrier
	s_sub_u32 s66, s66, 64
	s_subb_u32 s67, s67, 0
	s_sub_u32 s62, s62, 64
	s_subb_u32 s63, s63, 0
	s_sub_u32 s18, s18, 64
	s_subb_u32 s19, s19, 0
	s_add_u32 m0, s65, 0x0
	s_nop 0
	global_load_lds_dwordx4 v242, s[66:67]
	s_add_u32 m0, s65, 0x1000
	s_nop 0
	global_load_lds_dwordx4 v243, s[66:67]
	s_add_u32 m0, s65, 0x2000
	s_nop 0
	global_load_lds_dwordx4 v242, s[62:63]
	s_add_u32 m0, s65, 0x3000
	s_nop 0
	global_load_lds_dwordx4 v243, s[62:63]
	s_add_u32 m0, s65, 0x4000
	s_nop 0
	global_load_lds_dwordx4 v242, s[18:19]
	s_add_u32 m0, s65, 0x5000
	s_nop 0
	global_load_lds_dwordx4 v243, s[18:19]
	s_add_u32 s66, s66, 64
	s_addc_u32 s67, s67, 0
	s_add_u32 s62, s62, 64
	s_addc_u32 s63, s63, 0
	s_add_u32 s18, s18, 64
	s_addc_u32 s19, s19, 0
	s_add_u32 m0, s65, 0x6000
	s_nop 0
	global_load_lds_dwordx4 v160, s[66:67]
	s_add_u32 m0, s65, 0x7000
	s_nop 0
	global_load_lds_dwordx4 v161, s[66:67]
	s_add_u32 m0, s65, 0x8000
	s_nop 0
	global_load_lds_dwordx4 v160, s[62:63]
	s_add_u32 m0, s65, 0x9000
	s_nop 0
	global_load_lds_dwordx4 v161, s[62:63]
	s_add_u32 m0, s65, 0xa000
	s_nop 0
	global_load_lds_dwordx4 v160, s[18:19]
	s_add_u32 m0, s65, 0xb000
	s_nop 0
	global_load_lds_dwordx4 v161, s[18:19]
	s_add_u32 s66, s66, 64
	s_addc_u32 s67, s67, 0
	s_add_u32 s62, s62, 64
	s_addc_u32 s63, s63, 0
	s_add_u32 s18, s18, 64
	s_addc_u32 s19, s19, 0
	s_add_u32 m0, s65, 0xc000
	s_nop 0
	global_load_lds_dwordx4 v242, s[66:67]
	s_add_u32 m0, s65, 0xd000
	s_nop 0
	global_load_lds_dwordx4 v243, s[66:67]
	s_add_u32 m0, s65, 0xe000
	s_nop 0
	global_load_lds_dwordx4 v242, s[62:63]
	s_add_u32 m0, s65, 0xf000
	s_nop 0
	global_load_lds_dwordx4 v243, s[62:63]
	s_add_u32 m0, s65, 0x10000
	s_nop 0
	global_load_lds_dwordx4 v242, s[18:19]
	s_add_u32 m0, s65, 0x11000
	s_nop 0
	global_load_lds_dwordx4 v243, s[18:19]
	s_add_u32 s66, s66, 64
	s_addc_u32 s67, s67, 0
	s_add_u32 s62, s62, 64
	s_addc_u32 s63, s63, 0
	s_add_u32 s18, s18, 64
	s_addc_u32 s19, s19, 0
	v_mov_b32_e32 v2, 0
	v_mov_b32_e32 v3, 0
	v_mov_b32_e32 v4, 0
	v_mov_b32_e32 v5, 0
	v_mov_b32_e32 v6, 0
	v_mov_b32_e32 v7, 0
	v_mov_b32_e32 v8, 0
	v_mov_b32_e32 v9, 0
	v_mov_b32_e32 v10, 0
	v_mov_b32_e32 v11, 0
	v_mov_b32_e32 v12, 0
	v_mov_b32_e32 v13, 0
	v_mov_b32_e32 v14, 0
	v_mov_b32_e32 v15, 0
	v_mov_b32_e32 v16, 0
	v_mov_b32_e32 v17, 0
	v_mov_b32_e32 v18, 0
	v_mov_b32_e32 v19, 0
	v_mov_b32_e32 v20, 0
	v_mov_b32_e32 v21, 0
	v_mov_b32_e32 v22, 0
	v_mov_b32_e32 v23, 0
	v_mov_b32_e32 v24, 0
	v_mov_b32_e32 v25, 0
	v_mov_b32_e32 v26, 0
	v_mov_b32_e32 v27, 0
	v_mov_b32_e32 v28, 0
	v_mov_b32_e32 v29, 0
	v_mov_b32_e32 v30, 0
	v_mov_b32_e32 v31, 0
	v_mov_b32_e32 v32, 0
	v_mov_b32_e32 v33, 0
	v_mov_b32_e32 v34, 0
	v_mov_b32_e32 v35, 0
	v_mov_b32_e32 v36, 0
	v_mov_b32_e32 v37, 0
	v_mov_b32_e32 v38, 0
	v_mov_b32_e32 v39, 0
	v_mov_b32_e32 v40, 0
	v_mov_b32_e32 v41, 0
	v_mov_b32_e32 v42, 0
	v_mov_b32_e32 v43, 0
	v_mov_b32_e32 v44, 0
	v_mov_b32_e32 v45, 0
	v_mov_b32_e32 v46, 0
	v_mov_b32_e32 v47, 0
	v_mov_b32_e32 v48, 0
	v_mov_b32_e32 v49, 0
	v_mov_b32_e32 v50, 0
	v_mov_b32_e32 v51, 0
	v_mov_b32_e32 v52, 0
	v_mov_b32_e32 v53, 0
	v_mov_b32_e32 v54, 0
	v_mov_b32_e32 v55, 0
	v_mov_b32_e32 v56, 0
	v_mov_b32_e32 v57, 0
	v_mov_b32_e32 v58, 0
	v_mov_b32_e32 v59, 0
	v_mov_b32_e32 v60, 0
	v_mov_b32_e32 v61, 0
	v_mov_b32_e32 v62, 0
	v_mov_b32_e32 v63, 0
	v_mov_b32_e32 v64, 0
	v_mov_b32_e32 v65, 0
	v_mov_b32_e32 v66, 0
	v_mov_b32_e32 v67, 0
	v_mov_b32_e32 v68, 0
	v_mov_b32_e32 v69, 0
	v_mov_b32_e32 v70, 0
	v_mov_b32_e32 v71, 0
	v_mov_b32_e32 v72, 0
	v_mov_b32_e32 v73, 0
	v_mov_b32_e32 v74, 0
	v_mov_b32_e32 v75, 0
	v_mov_b32_e32 v76, 0
	v_mov_b32_e32 v77, 0
	v_mov_b32_e32 v78, 0
	v_mov_b32_e32 v79, 0
	v_mov_b32_e32 v80, 0
	v_mov_b32_e32 v81, 0
	v_mov_b32_e32 v82, 0
	v_mov_b32_e32 v83, 0
	v_mov_b32_e32 v84, 0
	v_mov_b32_e32 v85, 0
	v_mov_b32_e32 v86, 0
	v_mov_b32_e32 v87, 0
	v_mov_b32_e32 v88, 0
	v_mov_b32_e32 v89, 0
	v_mov_b32_e32 v90, 0
	v_mov_b32_e32 v91, 0
	v_mov_b32_e32 v92, 0
	v_mov_b32_e32 v93, 0
	v_mov_b32_e32 v94, 0
	v_mov_b32_e32 v95, 0
	v_mov_b32_e32 v96, 0
	v_mov_b32_e32 v97, 0
	v_mov_b32_e32 v98, 0
	v_mov_b32_e32 v99, 0
	v_mov_b32_e32 v100, 0
	v_mov_b32_e32 v101, 0
	v_mov_b32_e32 v102, 0
	v_mov_b32_e32 v103, 0
	v_mov_b32_e32 v104, 0
	v_mov_b32_e32 v105, 0
	v_mov_b32_e32 v106, 0
	v_mov_b32_e32 v107, 0
	v_mov_b32_e32 v108, 0
	v_mov_b32_e32 v109, 0
	v_mov_b32_e32 v110, 0
	v_mov_b32_e32 v111, 0
	v_mov_b32_e32 v112, 0
	v_mov_b32_e32 v113, 0
	v_mov_b32_e32 v114, 0
	v_mov_b32_e32 v115, 0
	v_mov_b32_e32 v116, 0
	v_mov_b32_e32 v117, 0
	v_mov_b32_e32 v118, 0
	v_mov_b32_e32 v119, 0
	v_mov_b32_e32 v120, 0
	v_mov_b32_e32 v121, 0
	v_mov_b32_e32 v122, 0
	v_mov_b32_e32 v123, 0
	v_mov_b32_e32 v124, 0
	v_mov_b32_e32 v125, 0
	v_mov_b32_e32 v126, 0
	v_mov_b32_e32 v127, 0
	v_mov_b32_e32 v128, 0
	v_mov_b32_e32 v129, 0
	s_waitcnt vmcnt(6)
	s_barrier
	ds_read_b128 v[130:133], v154 offset:24592
	ds_read_b128 v[138:141], v158 offset:32784
	ds_read_b128 v[146:149], v238 offset:24592
	ds_read_b128 v[134:137], v155 offset:16
	ds_read_b128 v[142:145], v159 offset:8208
	ds_read_b128 v[150:153], v239 offset:16
	s_mov_b32 s59, 5
.Lhw_outproj_loop:
	s_waitcnt lgkmcnt(4)
	v_mfma_f32_32x32x16_bf16 v[2:17], v[130:133], v[138:141], v[2:17]
	ds_read_b128 v[212:215], v156 offset:24592
	s_waitcnt lgkmcnt(2)
	v_mfma_f32_32x32x16_bf16 v[18:33], v[130:133], v[142:145], v[18:33]
	ds_read_b128 v[220:223], v236 offset:32784
	v_mfma_f32_32x32x16_bf16 v[34:49], v[134:137], v[138:141], v[34:49]
	ds_read_b128 v[228:231], v240 offset:24592
	v_mfma_f32_32x32x16_bf16 v[50:65], v[134:137], v[142:145], v[50:65]
	ds_read_b128 v[216:219], v157 offset:16
	v_mfma_f32_32x32x16_bf16 v[66:81], v[130:133], v[146:149], v[66:81]
	ds_read_b128 v[224:227], v237 offset:8208
	s_waitcnt lgkmcnt(5)
	v_mfma_f32_32x32x16_bf16 v[82:97], v[130:133], v[150:153], v[82:97]
	ds_read_b128 v[232:235], v241 offset:16
	v_mfma_f32_32x32x16_bf16 v[98:113], v[134:137], v[146:149], v[98:113]
	v_mfma_f32_32x32x16_bf16 v[114:129], v[134:137], v[150:153], v[114:129]
	s_waitcnt vmcnt(0) lgkmcnt(0)
	s_barrier
	v_mfma_f32_32x32x16_bf16 v[2:17], v[212:215], v[220:223], v[2:17]
	s_add_u32 m0, s65, 0x0
	ds_read_b128 v[130:133], v155 offset:24592
	global_load_lds_dwordx4 v160, s[66:67]
	v_mfma_f32_32x32x16_bf16 v[18:33], v[212:215], v[224:227], v[18:33]
	s_add_u32 m0, s65, 0x1000
	ds_read_b128 v[138:141], v159 offset:32784
	global_load_lds_dwordx4 v161, s[66:67]
	v_mfma_f32_32x32x16_bf16 v[34:49], v[216:219], v[220:223], v[34:49]
	s_add_u32 m0, s65, 0x2000
	ds_read_b128 v[146:149], v239 offset:24592
	global_load_lds_dwordx4 v160, s[62:63]
	v_mfma_f32_32x32x16_bf16 v[50:65], v[216:219], v[224:227], v[50:65]
	s_add_u32 m0, s65, 0x3000
	ds_read_b128 v[134:137], v154 offset:49168
	global_load_lds_dwordx4 v161, s[62:63]
	v_mfma_f32_32x32x16_bf16 v[66:81], v[212:215], v[228:231], v[66:81]
	s_add_u32 m0, s65, 0x4000
	ds_read_b128 v[142:145], v158 offset:57360
	global_load_lds_dwordx4 v160, s[18:19]
	v_mfma_f32_32x32x16_bf16 v[82:97], v[212:215], v[232:235], v[82:97]
	s_add_u32 m0, s65, 0x5000
	ds_read_b128 v[150:153], v238 offset:49168
	global_load_lds_dwordx4 v161, s[18:19]
	v_mfma_f32_32x32x16_bf16 v[98:113], v[216:219], v[228:231], v[98:113]
	s_add_u32 s66, s66, 64
	s_addc_u32 s67, s67, 0
	s_add_u32 s62, s62, 64
	s_addc_u32 s63, s63, 0
	v_mfma_f32_32x32x16_bf16 v[114:129], v[216:219], v[232:235], v[114:129]
	s_add_u32 s18, s18, 64
	s_addc_u32 s19, s19, 0
	s_waitcnt lgkmcnt(4)
	v_mfma_f32_32x32x16_bf16 v[2:17], v[130:133], v[138:141], v[2:17]
	ds_read_b128 v[212:215], v157 offset:24592
	s_waitcnt lgkmcnt(2)
	v_mfma_f32_32x32x16_bf16 v[18:33], v[130:133], v[142:145], v[18:33]
	ds_read_b128 v[220:223], v237 offset:32784
	v_mfma_f32_32x32x16_bf16 v[34:49], v[134:137], v[138:141], v[34:49]
	ds_read_b128 v[228:231], v241 offset:24592
	v_mfma_f32_32x32x16_bf16 v[50:65], v[134:137], v[142:145], v[50:65]
	ds_read_b128 v[216:219], v156 offset:49168
	v_mfma_f32_32x32x16_bf16 v[66:81], v[130:133], v[146:149], v[66:81]
	ds_read_b128 v[224:227], v236 offset:57360
	s_waitcnt lgkmcnt(5)
	v_mfma_f32_32x32x16_bf16 v[82:97], v[130:133], v[150:153], v[82:97]
	ds_read_b128 v[232:235], v240 offset:49168
	v_mfma_f32_32x32x16_bf16 v[98:113], v[134:137], v[146:149], v[98:113]
	v_mfma_f32_32x32x16_bf16 v[114:129], v[134:137], v[150:153], v[114:129]
	s_waitcnt vmcnt(0) lgkmcnt(0)
	s_barrier
	v_mfma_f32_32x32x16_bf16 v[2:17], v[212:215], v[220:223], v[2:17]
	s_add_u32 m0, s65, 0x6000
	ds_read_b128 v[130:133], v154 offset:16
	global_load_lds_dwordx4 v242, s[66:67]
	v_mfma_f32_32x32x16_bf16 v[18:33], v[212:215], v[224:227], v[18:33]
	s_add_u32 m0, s65, 0x7000
	ds_read_b128 v[138:141], v158 offset:8208
	global_load_lds_dwordx4 v243, s[66:67]
	v_mfma_f32_32x32x16_bf16 v[34:49], v[216:219], v[220:223], v[34:49]
	s_add_u32 m0, s65, 0x8000
	ds_read_b128 v[146:149], v238 offset:16
	global_load_lds_dwordx4 v242, s[62:63]
	v_mfma_f32_32x32x16_bf16 v[50:65], v[216:219], v[224:227], v[50:65]
	s_add_u32 m0, s65, 0x9000
	ds_read_b128 v[134:137], v155 offset:49168
	global_load_lds_dwordx4 v243, s[62:63]
	v_mfma_f32_32x32x16_bf16 v[66:81], v[212:215], v[228:231], v[66:81]
	s_add_u32 m0, s65, 0xa000
	ds_read_b128 v[142:145], v159 offset:57360
	global_load_lds_dwordx4 v242, s[18:19]
	v_mfma_f32_32x32x16_bf16 v[82:97], v[212:215], v[232:235], v[82:97]
	s_add_u32 m0, s65, 0xb000
	ds_read_b128 v[150:153], v239 offset:49168
	global_load_lds_dwordx4 v243, s[18:19]
	v_mfma_f32_32x32x16_bf16 v[98:113], v[216:219], v[228:231], v[98:113]
	s_add_u32 s66, s66, 64
	s_addc_u32 s67, s67, 0
	s_add_u32 s62, s62, 64
	s_addc_u32 s63, s63, 0
	v_mfma_f32_32x32x16_bf16 v[114:129], v[216:219], v[232:235], v[114:129]
	s_add_u32 s18, s18, 64
	s_addc_u32 s19, s19, 0
	s_waitcnt lgkmcnt(4)
	v_mfma_f32_32x32x16_bf16 v[2:17], v[130:133], v[138:141], v[2:17]
	ds_read_b128 v[212:215], v156 offset:16
	s_waitcnt lgkmcnt(2)
	v_mfma_f32_32x32x16_bf16 v[18:33], v[130:133], v[142:145], v[18:33]
	ds_read_b128 v[220:223], v236 offset:8208
	v_mfma_f32_32x32x16_bf16 v[34:49], v[134:137], v[138:141], v[34:49]
	ds_read_b128 v[228:231], v240 offset:16
	v_mfma_f32_32x32x16_bf16 v[50:65], v[134:137], v[142:145], v[50:65]
	ds_read_b128 v[216:219], v157 offset:49168
	v_mfma_f32_32x32x16_bf16 v[66:81], v[130:133], v[146:149], v[66:81]
	ds_read_b128 v[224:227], v237 offset:57360
	s_waitcnt lgkmcnt(5)
	v_mfma_f32_32x32x16_bf16 v[82:97], v[130:133], v[150:153], v[82:97]
	ds_read_b128 v[232:235], v241 offset:49168
	v_mfma_f32_32x32x16_bf16 v[98:113], v[134:137], v[146:149], v[98:113]
	v_mfma_f32_32x32x16_bf16 v[114:129], v[134:137], v[150:153], v[114:129]
	s_waitcnt vmcnt(0) lgkmcnt(0)
	s_barrier
	v_mfma_f32_32x32x16_bf16 v[2:17], v[212:215], v[220:223], v[2:17]
	s_add_u32 m0, s65, 0xc000
	ds_read_b128 v[130:133], v155 offset:16
	global_load_lds_dwordx4 v160, s[66:67]
	v_mfma_f32_32x32x16_bf16 v[18:33], v[212:215], v[224:227], v[18:33]
	s_add_u32 m0, s65, 0xd000
	ds_read_b128 v[138:141], v159 offset:8208
	global_load_lds_dwordx4 v161, s[66:67]
	v_mfma_f32_32x32x16_bf16 v[34:49], v[216:219], v[220:223], v[34:49]
	s_add_u32 m0, s65, 0xe000
	ds_read_b128 v[146:149], v239 offset:16
	global_load_lds_dwordx4 v160, s[62:63]
	v_mfma_f32_32x32x16_bf16 v[50:65], v[216:219], v[224:227], v[50:65]
	s_add_u32 m0, s65, 0xf000
	ds_read_b128 v[134:137], v154 offset:24592
	global_load_lds_dwordx4 v161, s[62:63]
	v_mfma_f32_32x32x16_bf16 v[66:81], v[212:215], v[228:231], v[66:81]
	s_add_u32 m0, s65, 0x10000
	ds_read_b128 v[142:145], v158 offset:32784
	global_load_lds_dwordx4 v160, s[18:19]
	v_mfma_f32_32x32x16_bf16 v[82:97], v[212:215], v[232:235], v[82:97]
	s_add_u32 m0, s65, 0x11000
	ds_read_b128 v[150:153], v238 offset:24592
	global_load_lds_dwordx4 v161, s[18:19]
	v_mfma_f32_32x32x16_bf16 v[98:113], v[216:219], v[228:231], v[98:113]
	s_add_u32 s66, s66, 64
	s_addc_u32 s67, s67, 0
	s_add_u32 s62, s62, 64
	s_addc_u32 s63, s63, 0
	v_mfma_f32_32x32x16_bf16 v[114:129], v[216:219], v[232:235], v[114:129]
	s_add_u32 s18, s18, 64
	s_addc_u32 s19, s19, 0
	s_waitcnt lgkmcnt(4)
	v_mfma_f32_32x32x16_bf16 v[2:17], v[130:133], v[138:141], v[2:17]
	ds_read_b128 v[212:215], v157 offset:16
	s_waitcnt lgkmcnt(2)
	v_mfma_f32_32x32x16_bf16 v[18:33], v[130:133], v[142:145], v[18:33]
	ds_read_b128 v[220:223], v237 offset:8208
	v_mfma_f32_32x32x16_bf16 v[34:49], v[134:137], v[138:141], v[34:49]
	ds_read_b128 v[228:231], v241 offset:16
	v_mfma_f32_32x32x16_bf16 v[50:65], v[134:137], v[142:145], v[50:65]
	ds_read_b128 v[216:219], v156 offset:24592
	v_mfma_f32_32x32x16_bf16 v[66:81], v[130:133], v[146:149], v[66:81]
	ds_read_b128 v[224:227], v236 offset:32784
	s_waitcnt lgkmcnt(5)
	v_mfma_f32_32x32x16_bf16 v[82:97], v[130:133], v[150:153], v[82:97]
	ds_read_b128 v[232:235], v240 offset:24592
	v_mfma_f32_32x32x16_bf16 v[98:113], v[134:137], v[146:149], v[98:113]
	v_mfma_f32_32x32x16_bf16 v[114:129], v[134:137], v[150:153], v[114:129]
	s_waitcnt vmcnt(0) lgkmcnt(0)
	s_barrier
	v_mfma_f32_32x32x16_bf16 v[2:17], v[212:215], v[220:223], v[2:17]
	s_add_u32 m0, s65, 0x0
	ds_read_b128 v[130:133], v154 offset:49168
	global_load_lds_dwordx4 v242, s[66:67]
	v_mfma_f32_32x32x16_bf16 v[18:33], v[212:215], v[224:227], v[18:33]
	s_add_u32 m0, s65, 0x1000
	ds_read_b128 v[138:141], v158 offset:57360
	global_load_lds_dwordx4 v243, s[66:67]
	v_mfma_f32_32x32x16_bf16 v[34:49], v[216:219], v[220:223], v[34:49]
	s_add_u32 m0, s65, 0x2000
	ds_read_b128 v[146:149], v238 offset:49168
	global_load_lds_dwordx4 v242, s[62:63]
	v_mfma_f32_32x32x16_bf16 v[50:65], v[216:219], v[224:227], v[50:65]
	s_add_u32 m0, s65, 0x3000
	ds_read_b128 v[134:137], v155 offset:24592
	global_load_lds_dwordx4 v243, s[62:63]
	v_mfma_f32_32x32x16_bf16 v[66:81], v[212:215], v[228:231], v[66:81]
	s_add_u32 m0, s65, 0x4000
	ds_read_b128 v[142:145], v159 offset:32784
	global_load_lds_dwordx4 v242, s[18:19]
	v_mfma_f32_32x32x16_bf16 v[82:97], v[212:215], v[232:235], v[82:97]
	s_add_u32 m0, s65, 0x5000
	ds_read_b128 v[150:153], v239 offset:24592
	global_load_lds_dwordx4 v243, s[18:19]
	v_mfma_f32_32x32x16_bf16 v[98:113], v[216:219], v[228:231], v[98:113]
	s_add_u32 s66, s66, 64
	s_addc_u32 s67, s67, 0
	s_add_u32 s62, s62, 64
	s_addc_u32 s63, s63, 0
	v_mfma_f32_32x32x16_bf16 v[114:129], v[216:219], v[232:235], v[114:129]
	s_add_u32 s18, s18, 64
	s_addc_u32 s19, s19, 0
	s_waitcnt lgkmcnt(4)
	v_mfma_f32_32x32x16_bf16 v[2:17], v[130:133], v[138:141], v[2:17]
	ds_read_b128 v[212:215], v156 offset:49168
	s_waitcnt lgkmcnt(2)
	v_mfma_f32_32x32x16_bf16 v[18:33], v[130:133], v[142:145], v[18:33]
	ds_read_b128 v[220:223], v236 offset:57360
	v_mfma_f32_32x32x16_bf16 v[34:49], v[134:137], v[138:141], v[34:49]
	ds_read_b128 v[228:231], v240 offset:49168
	v_mfma_f32_32x32x16_bf16 v[50:65], v[134:137], v[142:145], v[50:65]
	ds_read_b128 v[216:219], v157 offset:24592
	v_mfma_f32_32x32x16_bf16 v[66:81], v[130:133], v[146:149], v[66:81]
	ds_read_b128 v[224:227], v237 offset:32784
	s_waitcnt lgkmcnt(5)
	v_mfma_f32_32x32x16_bf16 v[82:97], v[130:133], v[150:153], v[82:97]
	ds_read_b128 v[232:235], v241 offset:24592
	v_mfma_f32_32x32x16_bf16 v[98:113], v[134:137], v[146:149], v[98:113]
	v_mfma_f32_32x32x16_bf16 v[114:129], v[134:137], v[150:153], v[114:129]
	s_waitcnt vmcnt(0) lgkmcnt(0)
	s_barrier
	v_mfma_f32_32x32x16_bf16 v[2:17], v[212:215], v[220:223], v[2:17]
	s_add_u32 m0, s65, 0x6000
	ds_read_b128 v[130:133], v155 offset:49168
	global_load_lds_dwordx4 v160, s[66:67]
	v_mfma_f32_32x32x16_bf16 v[18:33], v[212:215], v[224:227], v[18:33]
	s_add_u32 m0, s65, 0x7000
	ds_read_b128 v[138:141], v159 offset:57360
	global_load_lds_dwordx4 v161, s[66:67]
	v_mfma_f32_32x32x16_bf16 v[34:49], v[216:219], v[220:223], v[34:49]
	s_add_u32 m0, s65, 0x8000
	ds_read_b128 v[146:149], v239 offset:49168
	global_load_lds_dwordx4 v160, s[62:63]
	v_mfma_f32_32x32x16_bf16 v[50:65], v[216:219], v[224:227], v[50:65]
	s_add_u32 m0, s65, 0x9000
	ds_read_b128 v[134:137], v154 offset:16
	global_load_lds_dwordx4 v161, s[62:63]
	v_mfma_f32_32x32x16_bf16 v[66:81], v[212:215], v[228:231], v[66:81]
	s_add_u32 m0, s65, 0xa000
	ds_read_b128 v[142:145], v158 offset:8208
	global_load_lds_dwordx4 v160, s[18:19]
	v_mfma_f32_32x32x16_bf16 v[82:97], v[212:215], v[232:235], v[82:97]
	s_add_u32 m0, s65, 0xb000
	ds_read_b128 v[150:153], v238 offset:16
	global_load_lds_dwordx4 v161, s[18:19]
	v_mfma_f32_32x32x16_bf16 v[98:113], v[216:219], v[228:231], v[98:113]
	s_add_u32 s66, s66, 64
	s_addc_u32 s67, s67, 0
	s_add_u32 s62, s62, 64
	s_addc_u32 s63, s63, 0
	v_mfma_f32_32x32x16_bf16 v[114:129], v[216:219], v[232:235], v[114:129]
	s_add_u32 s18, s18, 64
	s_addc_u32 s19, s19, 0
	s_waitcnt lgkmcnt(4)
	v_mfma_f32_32x32x16_bf16 v[2:17], v[130:133], v[138:141], v[2:17]
	ds_read_b128 v[212:215], v157 offset:49168
	s_waitcnt lgkmcnt(2)
	v_mfma_f32_32x32x16_bf16 v[18:33], v[130:133], v[142:145], v[18:33]
	ds_read_b128 v[220:223], v237 offset:57360
	v_mfma_f32_32x32x16_bf16 v[34:49], v[134:137], v[138:141], v[34:49]
	ds_read_b128 v[228:231], v241 offset:49168
	v_mfma_f32_32x32x16_bf16 v[50:65], v[134:137], v[142:145], v[50:65]
	ds_read_b128 v[216:219], v156 offset:16
	v_mfma_f32_32x32x16_bf16 v[66:81], v[130:133], v[146:149], v[66:81]
	ds_read_b128 v[224:227], v236 offset:8208
	s_waitcnt lgkmcnt(5)
	v_mfma_f32_32x32x16_bf16 v[82:97], v[130:133], v[150:153], v[82:97]
	ds_read_b128 v[232:235], v240 offset:16
	v_mfma_f32_32x32x16_bf16 v[98:113], v[134:137], v[146:149], v[98:113]
	v_mfma_f32_32x32x16_bf16 v[114:129], v[134:137], v[150:153], v[114:129]
	s_waitcnt vmcnt(0) lgkmcnt(0)
	s_barrier
	v_mfma_f32_32x32x16_bf16 v[2:17], v[212:215], v[220:223], v[2:17]
	s_add_u32 m0, s65, 0xc000
	ds_read_b128 v[130:133], v154 offset:24592
	global_load_lds_dwordx4 v242, s[66:67]
	v_mfma_f32_32x32x16_bf16 v[18:33], v[212:215], v[224:227], v[18:33]
	s_add_u32 m0, s65, 0xd000
	ds_read_b128 v[138:141], v158 offset:32784
	global_load_lds_dwordx4 v243, s[66:67]
	v_mfma_f32_32x32x16_bf16 v[34:49], v[216:219], v[220:223], v[34:49]
	s_add_u32 m0, s65, 0xe000
	ds_read_b128 v[146:149], v238 offset:24592
	global_load_lds_dwordx4 v242, s[62:63]
	v_mfma_f32_32x32x16_bf16 v[50:65], v[216:219], v[224:227], v[50:65]
	s_add_u32 m0, s65, 0xf000
	ds_read_b128 v[134:137], v155 offset:16
	global_load_lds_dwordx4 v243, s[62:63]
	v_mfma_f32_32x32x16_bf16 v[66:81], v[212:215], v[228:231], v[66:81]
	s_add_u32 m0, s65, 0x10000
	ds_read_b128 v[142:145], v159 offset:8208
	global_load_lds_dwordx4 v242, s[18:19]
	v_mfma_f32_32x32x16_bf16 v[82:97], v[212:215], v[232:235], v[82:97]
	s_add_u32 m0, s65, 0x11000
	ds_read_b128 v[150:153], v239 offset:16
	global_load_lds_dwordx4 v243, s[18:19]
	v_mfma_f32_32x32x16_bf16 v[98:113], v[216:219], v[228:231], v[98:113]
	s_add_u32 s66, s66, 64
	s_addc_u32 s67, s67, 0
	s_add_u32 s62, s62, 64
	s_addc_u32 s63, s63, 0
	v_mfma_f32_32x32x16_bf16 v[114:129], v[216:219], v[232:235], v[114:129]
	s_add_u32 s18, s18, 64
	s_addc_u32 s19, s19, 0
	s_sub_u32 s59, s59, 1
	s_cmp_lg_u32 s59, 0
	s_cbranch_scc1 .Lhw_outproj_loop
	s_waitcnt lgkmcnt(4)
	v_mfma_f32_32x32x16_bf16 v[2:17], v[130:133], v[138:141], v[2:17]
	ds_read_b128 v[212:215], v156 offset:24592
	s_waitcnt lgkmcnt(2)
	v_mfma_f32_32x32x16_bf16 v[18:33], v[130:133], v[142:145], v[18:33]
	ds_read_b128 v[220:223], v236 offset:32784
	v_mfma_f32_32x32x16_bf16 v[34:49], v[134:137], v[138:141], v[34:49]
	ds_read_b128 v[228:231], v240 offset:24592
	v_mfma_f32_32x32x16_bf16 v[50:65], v[134:137], v[142:145], v[50:65]
	ds_read_b128 v[216:219], v157 offset:16
	v_mfma_f32_32x32x16_bf16 v[66:81], v[130:133], v[146:149], v[66:81]
	ds_read_b128 v[224:227], v237 offset:8208
	s_waitcnt lgkmcnt(5)
	v_mfma_f32_32x32x16_bf16 v[82:97], v[130:133], v[150:153], v[82:97]
	ds_read_b128 v[232:235], v241 offset:16
	v_mfma_f32_32x32x16_bf16 v[98:113], v[134:137], v[146:149], v[98:113]
	v_mfma_f32_32x32x16_bf16 v[114:129], v[134:137], v[150:153], v[114:129]
	s_waitcnt vmcnt(0) lgkmcnt(0)
	s_barrier
	v_mfma_f32_32x32x16_bf16 v[2:17], v[212:215], v[220:223], v[2:17]
	ds_read_b128 v[130:133], v155 offset:24592
	v_mfma_f32_32x32x16_bf16 v[18:33], v[212:215], v[224:227], v[18:33]
	ds_read_b128 v[138:141], v159 offset:32784
	v_mfma_f32_32x32x16_bf16 v[34:49], v[216:219], v[220:223], v[34:49]
	ds_read_b128 v[146:149], v239 offset:24592
	v_mfma_f32_32x32x16_bf16 v[50:65], v[216:219], v[224:227], v[50:65]
	ds_read_b128 v[134:137], v154 offset:49168
	v_mfma_f32_32x32x16_bf16 v[66:81], v[212:215], v[228:231], v[66:81]
	ds_read_b128 v[142:145], v158 offset:57360
	v_mfma_f32_32x32x16_bf16 v[82:97], v[212:215], v[232:235], v[82:97]
	ds_read_b128 v[150:153], v238 offset:49168
	v_mfma_f32_32x32x16_bf16 v[98:113], v[216:219], v[228:231], v[98:113]
	v_mfma_f32_32x32x16_bf16 v[114:129], v[216:219], v[232:235], v[114:129]
	s_waitcnt lgkmcnt(4)
	v_mfma_f32_32x32x16_bf16 v[2:17], v[130:133], v[138:141], v[2:17]
	ds_read_b128 v[212:215], v157 offset:24592
	s_waitcnt lgkmcnt(2)
	v_mfma_f32_32x32x16_bf16 v[18:33], v[130:133], v[142:145], v[18:33]
	ds_read_b128 v[220:223], v237 offset:32784
	v_mfma_f32_32x32x16_bf16 v[34:49], v[134:137], v[138:141], v[34:49]
	ds_read_b128 v[228:231], v241 offset:24592
	v_mfma_f32_32x32x16_bf16 v[50:65], v[134:137], v[142:145], v[50:65]
	ds_read_b128 v[216:219], v156 offset:49168
	v_mfma_f32_32x32x16_bf16 v[66:81], v[130:133], v[146:149], v[66:81]
	ds_read_b128 v[224:227], v236 offset:57360
	s_waitcnt lgkmcnt(5)
	v_mfma_f32_32x32x16_bf16 v[82:97], v[130:133], v[150:153], v[82:97]
	ds_read_b128 v[232:235], v240 offset:49168
	v_mfma_f32_32x32x16_bf16 v[98:113], v[134:137], v[146:149], v[98:113]
	v_mfma_f32_32x32x16_bf16 v[114:129], v[134:137], v[150:153], v[114:129]
	s_waitcnt lgkmcnt(0)
	v_mfma_f32_32x32x16_bf16 v[2:17], v[212:215], v[220:223], v[2:17]
	v_mfma_f32_32x32x16_bf16 v[18:33], v[212:215], v[224:227], v[18:33]
	v_mfma_f32_32x32x16_bf16 v[34:49], v[216:219], v[220:223], v[34:49]
	v_mfma_f32_32x32x16_bf16 v[50:65], v[216:219], v[224:227], v[50:65]
	v_mfma_f32_32x32x16_bf16 v[66:81], v[212:215], v[228:231], v[66:81]
	v_mfma_f32_32x32x16_bf16 v[82:97], v[212:215], v[232:235], v[82:97]
	v_mfma_f32_32x32x16_bf16 v[98:113], v[216:219], v[228:231], v[98:113]
	v_mfma_f32_32x32x16_bf16 v[114:129], v[216:219], v[232:235], v[114:129]
	s_nop 7
	s_nop 7
	s_sub_i32 s2, s6, 0x1000
	s_ashr_i32 s2, s2, 11
	s_add_i32 s2, s2, 1
	s_max_i32 s2, s2, 0
	v_readlane_b32 s17, v246, 28
	s_nop 0
	s_add_i32 s2, s2, s17
	s_mul_i32 s2, s2, 0x9000
	s_lshl_b32 s17, s15, 2
	s_add_u32 s2, s2, s17
	s_add_u32 s60, s8, s2
	s_addc_u32 s61, s9, 0
	s_lshr_b32 s2, s15, 7
	s_mul_i32 s2, s2, 0x18000
	s_lshl_b32 s20, s6, 2
	s_add_u32 s2, s2, s20
	s_add_u32 s10, s44, s2
	s_addc_u32 s11, s45, 0
	s_lshl_b32 s2, s6, 12
	s_add_u32 s2, s2, s17
	s_add_u32 s48, s40, s2
	s_addc_u32 s49, s41, 0
	global_load_dword v175, v166, s[60:61]
	global_load_dword v176, v166, s[60:61] offset:128
	global_load_dword v130, v162, s[48:49]
	global_load_dword v212, v162, s[48:49] offset:128
	global_load_dword v131, v163, s[48:49]
	global_load_dword v213, v163, s[48:49] offset:128
	global_load_dword v132, v164, s[48:49]
	global_load_dword v214, v164, s[48:49] offset:128
	global_load_dword v133, v165, s[48:49]
	global_load_dword v215, v165, s[48:49] offset:128
	s_add_u32 s48, s48, 0x8000
	s_addc_u32 s49, s49, 0
	global_load_dword v134, v162, s[48:49]
	global_load_dword v216, v162, s[48:49] offset:128
	global_load_dword v135, v163, s[48:49]
	global_load_dword v217, v163, s[48:49] offset:128
	global_load_dword v136, v164, s[48:49]
	global_load_dword v218, v164, s[48:49] offset:128
	global_load_dword v137, v165, s[48:49]
	global_load_dword v219, v165, s[48:49] offset:128
	s_add_u32 s48, s48, 0x8000
	s_addc_u32 s49, s49, 0
	global_load_dword v138, v162, s[48:49]
	global_load_dword v220, v162, s[48:49] offset:128
	global_load_dword v139, v163, s[48:49]
	global_load_dword v221, v163, s[48:49] offset:128
	global_load_dword v140, v164, s[48:49]
	global_load_dword v222, v164, s[48:49] offset:128
	global_load_dword v141, v165, s[48:49]
	global_load_dword v223, v165, s[48:49] offset:128
	s_add_u32 s48, s48, 0x8000
	s_addc_u32 s49, s49, 0
	global_load_dword v142, v162, s[48:49]
	global_load_dword v224, v162, s[48:49] offset:128
	global_load_dword v143, v163, s[48:49]
	global_load_dword v225, v163, s[48:49] offset:128
	global_load_dword v144, v164, s[48:49]
	global_load_dword v226, v164, s[48:49] offset:128
	global_load_dword v145, v165, s[48:49]
	global_load_dword v227, v165, s[48:49] offset:128
	s_sub_u32 s48, s48, 0x18000
	s_subb_u32 s49, s49, 0
	s_waitcnt vmcnt(32)
	s_waitcnt vmcnt(30)
	v_fmac_f32_e32 v130, v2, v175
	v_fmac_f32_e32 v212, v18, v176
	global_store_dword v162, v130, s[48:49]
	global_store_dword v162, v212, s[48:49] offset:128
	s_waitcnt vmcnt(30)
	v_fmac_f32_e32 v131, v3, v175
	v_fmac_f32_e32 v213, v19, v176
	global_store_dword v163, v131, s[48:49]
	global_store_dword v163, v213, s[48:49] offset:128
	s_waitcnt vmcnt(30)
	v_fmac_f32_e32 v132, v4, v175
	v_fmac_f32_e32 v214, v20, v176
	global_store_dword v164, v132, s[48:49]
	global_store_dword v164, v214, s[48:49] offset:128
	s_waitcnt vmcnt(30)
	v_fmac_f32_e32 v133, v5, v175
	v_fmac_f32_e32 v215, v21, v176
	global_store_dword v165, v133, s[48:49]
	global_store_dword v165, v215, s[48:49] offset:128
	s_add_u32 s48, s48, 0x8000
	s_addc_u32 s49, s49, 0
	s_waitcnt vmcnt(30)
	v_fmac_f32_e32 v134, v6, v175
	v_fmac_f32_e32 v216, v22, v176
	global_store_dword v162, v134, s[48:49]
	global_store_dword v162, v216, s[48:49] offset:128
	s_waitcnt vmcnt(30)
	v_fmac_f32_e32 v135, v7, v175
	v_fmac_f32_e32 v217, v23, v176
	global_store_dword v163, v135, s[48:49]
	global_store_dword v163, v217, s[48:49] offset:128
	s_waitcnt vmcnt(30)
	v_fmac_f32_e32 v136, v8, v175
	v_fmac_f32_e32 v218, v24, v176
	global_store_dword v164, v136, s[48:49]
	global_store_dword v164, v218, s[48:49] offset:128
	s_waitcnt vmcnt(30)
	v_fmac_f32_e32 v137, v9, v175
	v_fmac_f32_e32 v219, v25, v176
	global_store_dword v165, v137, s[48:49]
	global_store_dword v165, v219, s[48:49] offset:128
	s_add_u32 s48, s48, 0x8000
	s_addc_u32 s49, s49, 0
	s_waitcnt vmcnt(30)
	v_fmac_f32_e32 v138, v10, v175
	v_fmac_f32_e32 v220, v26, v176
	global_store_dword v162, v138, s[48:49]
	global_store_dword v162, v220, s[48:49] offset:128
	s_waitcnt vmcnt(30)
	v_fmac_f32_e32 v139, v11, v175
	v_fmac_f32_e32 v221, v27, v176
	global_store_dword v163, v139, s[48:49]
	global_store_dword v163, v221, s[48:49] offset:128
	s_waitcnt vmcnt(30)
	v_fmac_f32_e32 v140, v12, v175
	v_fmac_f32_e32 v222, v28, v176
	global_store_dword v164, v140, s[48:49]
	global_store_dword v164, v222, s[48:49] offset:128
	s_waitcnt vmcnt(30)
	v_fmac_f32_e32 v141, v13, v175
	v_fmac_f32_e32 v223, v29, v176
	global_store_dword v165, v141, s[48:49]
	global_store_dword v165, v223, s[48:49] offset:128
	s_add_u32 s48, s48, 0x8000
	s_addc_u32 s49, s49, 0
	s_waitcnt vmcnt(30)
	v_fmac_f32_e32 v142, v14, v175
	v_fmac_f32_e32 v224, v30, v176
	global_store_dword v162, v142, s[48:49]
	global_store_dword v162, v224, s[48:49] offset:128
	s_waitcnt vmcnt(30)
	v_fmac_f32_e32 v143, v15, v175
	v_fmac_f32_e32 v225, v31, v176
	global_store_dword v163, v143, s[48:49]
	global_store_dword v163, v225, s[48:49] offset:128
	s_waitcnt vmcnt(30)
	v_fmac_f32_e32 v144, v16, v175
	v_fmac_f32_e32 v226, v32, v176
	global_store_dword v164, v144, s[48:49]
	global_store_dword v164, v226, s[48:49] offset:128
	s_waitcnt vmcnt(30)
	v_fmac_f32_e32 v145, v17, v175
	v_fmac_f32_e32 v227, v33, v176
	global_store_dword v165, v145, s[48:49]
	global_store_dword v165, v227, s[48:49] offset:128
	s_sub_u32 s48, s48, 0x18000
	s_subb_u32 s49, s49, 0
	v_mul_f32_e32 v130, v130, v130
	v_fmac_f32_e32 v130, v212, v212
	v_mul_f32_e32 v131, v131, v131
	v_fmac_f32_e32 v131, v213, v213
	v_mul_f32_e32 v132, v132, v132
	v_fmac_f32_e32 v132, v214, v214
	v_mul_f32_e32 v133, v133, v133
	v_fmac_f32_e32 v133, v215, v215
	v_mul_f32_e32 v134, v134, v134
	v_fmac_f32_e32 v134, v216, v216
	v_mul_f32_e32 v135, v135, v135
	v_fmac_f32_e32 v135, v217, v217
	v_mul_f32_e32 v136, v136, v136
	v_fmac_f32_e32 v136, v218, v218
	v_mul_f32_e32 v137, v137, v137
	v_fmac_f32_e32 v137, v219, v219
	v_mul_f32_e32 v138, v138, v138
	v_fmac_f32_e32 v138, v220, v220
	v_mul_f32_e32 v139, v139, v139
	v_fmac_f32_e32 v139, v221, v221
	v_mul_f32_e32 v140, v140, v140
	v_fmac_f32_e32 v140, v222, v222
	v_mul_f32_e32 v141, v141, v141
	v_fmac_f32_e32 v141, v223, v223
	v_mul_f32_e32 v142, v142, v142
	v_fmac_f32_e32 v142, v224, v224
	v_mul_f32_e32 v143, v143, v143
	v_fmac_f32_e32 v143, v225, v225
	v_mul_f32_e32 v144, v144, v144
	v_fmac_f32_e32 v144, v226, v226
	v_mul_f32_e32 v145, v145, v145
	v_fmac_f32_e32 v145, v227, v227
	s_waitcnt lgkmcnt(0)
	ds_bpermute_b32 v212, v168, v130
	ds_bpermute_b32 v213, v168, v131
	ds_bpermute_b32 v214, v168, v132
	ds_bpermute_b32 v215, v168, v133
	ds_bpermute_b32 v216, v168, v134
	ds_bpermute_b32 v217, v168, v135
	ds_bpermute_b32 v218, v168, v136
	ds_bpermute_b32 v219, v168, v137
	s_waitcnt lgkmcnt(7)
	v_add_f32_e32 v130, v130, v212
	s_waitcnt lgkmcnt(6)
	v_add_f32_e32 v131, v131, v213
	s_waitcnt lgkmcnt(5)
	v_add_f32_e32 v132, v132, v214
	s_waitcnt lgkmcnt(4)
	v_add_f32_e32 v133, v133, v215
	s_waitcnt lgkmcnt(3)
	v_add_f32_e32 v134, v134, v216
	s_waitcnt lgkmcnt(2)
	v_add_f32_e32 v135, v135, v217
	s_waitcnt lgkmcnt(1)
	v_add_f32_e32 v136, v136, v218
	s_waitcnt lgkmcnt(0)
	v_add_f32_e32 v137, v137, v219
	ds_bpermute_b32 v212, v169, v130
	ds_bpermute_b32 v213, v169, v131
	ds_bpermute_b32 v214, v169, v132
	ds_bpermute_b32 v215, v169, v133
	ds_bpermute_b32 v216, v169, v134
	ds_bpermute_b32 v217, v169, v135
	ds_bpermute_b32 v218, v169, v136
	ds_bpermute_b32 v219, v169, v137
	s_waitcnt lgkmcnt(7)
	v_add_f32_e32 v130, v130, v212
	s_waitcnt lgkmcnt(6)
	v_add_f32_e32 v131, v131, v213
	s_waitcnt lgkmcnt(5)
	v_add_f32_e32 v132, v132, v214
	s_waitcnt lgkmcnt(4)
	v_add_f32_e32 v133, v133, v215
	s_waitcnt lgkmcnt(3)
	v_add_f32_e32 v134, v134, v216
	s_waitcnt lgkmcnt(2)
	v_add_f32_e32 v135, v135, v217
	s_waitcnt lgkmcnt(1)
	v_add_f32_e32 v136, v136, v218
	s_waitcnt lgkmcnt(0)
	v_add_f32_e32 v137, v137, v219
	ds_bpermute_b32 v212, v171, v130
	ds_bpermute_b32 v213, v171, v131
	ds_bpermute_b32 v214, v171, v132
	ds_bpermute_b32 v215, v171, v133
	ds_bpermute_b32 v216, v171, v134
	ds_bpermute_b32 v217, v171, v135
	ds_bpermute_b32 v218, v171, v136
	ds_bpermute_b32 v219, v171, v137
	s_waitcnt lgkmcnt(7)
	v_add_f32_e32 v130, v130, v212
	s_waitcnt lgkmcnt(6)
	v_add_f32_e32 v131, v131, v213
	s_waitcnt lgkmcnt(5)
	v_add_f32_e32 v132, v132, v214
	s_waitcnt lgkmcnt(4)
	v_add_f32_e32 v133, v133, v215
	s_waitcnt lgkmcnt(3)
	v_add_f32_e32 v134, v134, v216
	s_waitcnt lgkmcnt(2)
	v_add_f32_e32 v135, v135, v217
	s_waitcnt lgkmcnt(1)
	v_add_f32_e32 v136, v136, v218
	s_waitcnt lgkmcnt(0)
	v_add_f32_e32 v137, v137, v219
	ds_bpermute_b32 v212, v172, v130
	ds_bpermute_b32 v213, v172, v131
	ds_bpermute_b32 v214, v172, v132
	ds_bpermute_b32 v215, v172, v133
	ds_bpermute_b32 v216, v172, v134
	ds_bpermute_b32 v217, v172, v135
	ds_bpermute_b32 v218, v172, v136
	ds_bpermute_b32 v219, v172, v137
	s_waitcnt lgkmcnt(7)
	v_add_f32_e32 v130, v130, v212
	s_waitcnt lgkmcnt(6)
	v_add_f32_e32 v131, v131, v213
	s_waitcnt lgkmcnt(5)
	v_add_f32_e32 v132, v132, v214
	s_waitcnt lgkmcnt(4)
	v_add_f32_e32 v133, v133, v215
	s_waitcnt lgkmcnt(3)
	v_add_f32_e32 v134, v134, v216
	s_waitcnt lgkmcnt(2)
	v_add_f32_e32 v135, v135, v217
	s_waitcnt lgkmcnt(1)
	v_add_f32_e32 v136, v136, v218
	s_waitcnt lgkmcnt(0)
	v_add_f32_e32 v137, v137, v219
	ds_bpermute_b32 v212, v173, v130
	ds_bpermute_b32 v213, v173, v131
	ds_bpermute_b32 v214, v173, v132
	ds_bpermute_b32 v215, v173, v133
	ds_bpermute_b32 v216, v173, v134
	ds_bpermute_b32 v217, v173, v135
	ds_bpermute_b32 v218, v173, v136
	ds_bpermute_b32 v219, v173, v137
	s_waitcnt lgkmcnt(7)
	v_add_f32_e32 v130, v130, v212
	s_waitcnt lgkmcnt(6)
	v_add_f32_e32 v131, v131, v213
	s_waitcnt lgkmcnt(5)
	v_add_f32_e32 v132, v132, v214
	s_waitcnt lgkmcnt(4)
	v_add_f32_e32 v133, v133, v215
	s_waitcnt lgkmcnt(3)
	v_add_f32_e32 v134, v134, v216
	s_waitcnt lgkmcnt(2)
	v_add_f32_e32 v135, v135, v217
	s_waitcnt lgkmcnt(1)
	v_add_f32_e32 v136, v136, v218
	s_waitcnt lgkmcnt(0)
	v_add_f32_e32 v137, v137, v219
	ds_bpermute_b32 v220, v168, v138
	ds_bpermute_b32 v221, v168, v139
	ds_bpermute_b32 v222, v168, v140
	ds_bpermute_b32 v223, v168, v141
	ds_bpermute_b32 v224, v168, v142
	ds_bpermute_b32 v225, v168, v143
	ds_bpermute_b32 v226, v168, v144
	ds_bpermute_b32 v227, v168, v145
	s_waitcnt lgkmcnt(7)
	v_add_f32_e32 v138, v138, v220
	s_waitcnt lgkmcnt(6)
	v_add_f32_e32 v139, v139, v221
	s_waitcnt lgkmcnt(5)
	v_add_f32_e32 v140, v140, v222
	s_waitcnt lgkmcnt(4)
	v_add_f32_e32 v141, v141, v223
	s_waitcnt lgkmcnt(3)
	v_add_f32_e32 v142, v142, v224
	s_waitcnt lgkmcnt(2)
	v_add_f32_e32 v143, v143, v225
	s_waitcnt lgkmcnt(1)
	v_add_f32_e32 v144, v144, v226
	s_waitcnt lgkmcnt(0)
	v_add_f32_e32 v145, v145, v227
	ds_bpermute_b32 v220, v169, v138
	ds_bpermute_b32 v221, v169, v139
	ds_bpermute_b32 v222, v169, v140
	ds_bpermute_b32 v223, v169, v141
	ds_bpermute_b32 v224, v169, v142
	ds_bpermute_b32 v225, v169, v143
	ds_bpermute_b32 v226, v169, v144
	ds_bpermute_b32 v227, v169, v145
	s_waitcnt lgkmcnt(7)
	v_add_f32_e32 v138, v138, v220
	s_waitcnt lgkmcnt(6)
	v_add_f32_e32 v139, v139, v221
	s_waitcnt lgkmcnt(5)
	v_add_f32_e32 v140, v140, v222
	s_waitcnt lgkmcnt(4)
	v_add_f32_e32 v141, v141, v223
	s_waitcnt lgkmcnt(3)
	v_add_f32_e32 v142, v142, v224
	s_waitcnt lgkmcnt(2)
	v_add_f32_e32 v143, v143, v225
	s_waitcnt lgkmcnt(1)
	v_add_f32_e32 v144, v144, v226
	s_waitcnt lgkmcnt(0)
	v_add_f32_e32 v145, v145, v227
	ds_bpermute_b32 v220, v171, v138
	ds_bpermute_b32 v221, v171, v139
	ds_bpermute_b32 v222, v171, v140
	ds_bpermute_b32 v223, v171, v141
	ds_bpermute_b32 v224, v171, v142
	ds_bpermute_b32 v225, v171, v143
	ds_bpermute_b32 v226, v171, v144
	ds_bpermute_b32 v227, v171, v145
	s_waitcnt lgkmcnt(7)
	v_add_f32_e32 v138, v138, v220
	s_waitcnt lgkmcnt(6)
	v_add_f32_e32 v139, v139, v221
	s_waitcnt lgkmcnt(5)
	v_add_f32_e32 v140, v140, v222
	s_waitcnt lgkmcnt(4)
	v_add_f32_e32 v141, v141, v223
	s_waitcnt lgkmcnt(3)
	v_add_f32_e32 v142, v142, v224
	s_waitcnt lgkmcnt(2)
	v_add_f32_e32 v143, v143, v225
	s_waitcnt lgkmcnt(1)
	v_add_f32_e32 v144, v144, v226
	s_waitcnt lgkmcnt(0)
	v_add_f32_e32 v145, v145, v227
	ds_bpermute_b32 v220, v172, v138
	ds_bpermute_b32 v221, v172, v139
	ds_bpermute_b32 v222, v172, v140
	ds_bpermute_b32 v223, v172, v141
	ds_bpermute_b32 v224, v172, v142
	ds_bpermute_b32 v225, v172, v143
	ds_bpermute_b32 v226, v172, v144
	ds_bpermute_b32 v227, v172, v145
	s_waitcnt lgkmcnt(7)
	v_add_f32_e32 v138, v138, v220
	s_waitcnt lgkmcnt(6)
	v_add_f32_e32 v139, v139, v221
	s_waitcnt lgkmcnt(5)
	v_add_f32_e32 v140, v140, v222
	s_waitcnt lgkmcnt(4)
	v_add_f32_e32 v141, v141, v223
	s_waitcnt lgkmcnt(3)
	v_add_f32_e32 v142, v142, v224
	s_waitcnt lgkmcnt(2)
	v_add_f32_e32 v143, v143, v225
	s_waitcnt lgkmcnt(1)
	v_add_f32_e32 v144, v144, v226
	s_waitcnt lgkmcnt(0)
	v_add_f32_e32 v145, v145, v227
	ds_bpermute_b32 v220, v173, v138
	ds_bpermute_b32 v221, v173, v139
	ds_bpermute_b32 v222, v173, v140
	ds_bpermute_b32 v223, v173, v141
	ds_bpermute_b32 v224, v173, v142
	ds_bpermute_b32 v225, v173, v143
	ds_bpermute_b32 v226, v173, v144
	ds_bpermute_b32 v227, v173, v145
	s_waitcnt lgkmcnt(7)
	v_add_f32_e32 v138, v138, v220
	s_waitcnt lgkmcnt(6)
	v_add_f32_e32 v139, v139, v221
	s_waitcnt lgkmcnt(5)
	v_add_f32_e32 v140, v140, v222
	s_waitcnt lgkmcnt(4)
	v_add_f32_e32 v141, v141, v223
	s_waitcnt lgkmcnt(3)
	v_add_f32_e32 v142, v142, v224
	s_waitcnt lgkmcnt(2)
	v_add_f32_e32 v143, v143, v225
	s_waitcnt lgkmcnt(1)
	v_add_f32_e32 v144, v144, v226
	s_waitcnt lgkmcnt(0)
	v_add_f32_e32 v145, v145, v227
	v_cmp_eq_u32_e32 vcc, 0, v174
	s_and_saveexec_b64 s[58:59], vcc
	global_store_dword v167, v130, s[10:11]
	global_store_dword v167, v131, s[10:11] offset:4
	global_store_dword v167, v132, s[10:11] offset:8
	global_store_dword v167, v133, s[10:11] offset:12
	global_store_dword v167, v134, s[10:11] offset:32
	global_store_dword v167, v135, s[10:11] offset:36
	global_store_dword v167, v136, s[10:11] offset:40
	global_store_dword v167, v137, s[10:11] offset:44
	global_store_dword v167, v138, s[10:11] offset:64
	global_store_dword v167, v139, s[10:11] offset:68
	global_store_dword v167, v140, s[10:11] offset:72
	global_store_dword v167, v141, s[10:11] offset:76
	global_store_dword v167, v142, s[10:11] offset:96
	global_store_dword v167, v143, s[10:11] offset:100
	global_store_dword v167, v144, s[10:11] offset:104
	global_store_dword v167, v145, s[10:11] offset:108
	s_mov_b64 exec, -1
	s_add_u32 s48, s48, 0x20000
	s_addc_u32 s49, s49, 0
	global_load_dword v130, v162, s[48:49]
	global_load_dword v212, v162, s[48:49] offset:128
	global_load_dword v131, v163, s[48:49]
	global_load_dword v213, v163, s[48:49] offset:128
	global_load_dword v132, v164, s[48:49]
	global_load_dword v214, v164, s[48:49] offset:128
	global_load_dword v133, v165, s[48:49]
	global_load_dword v215, v165, s[48:49] offset:128
	s_add_u32 s48, s48, 0x8000
	s_addc_u32 s49, s49, 0
	global_load_dword v134, v162, s[48:49]
	global_load_dword v216, v162, s[48:49] offset:128
	global_load_dword v135, v163, s[48:49]
	global_load_dword v217, v163, s[48:49] offset:128
	global_load_dword v136, v164, s[48:49]
	global_load_dword v218, v164, s[48:49] offset:128
	global_load_dword v137, v165, s[48:49]
	global_load_dword v219, v165, s[48:49] offset:128
	s_add_u32 s48, s48, 0x8000
	s_addc_u32 s49, s49, 0
	global_load_dword v138, v162, s[48:49]
	global_load_dword v220, v162, s[48:49] offset:128
	global_load_dword v139, v163, s[48:49]
	global_load_dword v221, v163, s[48:49] offset:128
	global_load_dword v140, v164, s[48:49]
	global_load_dword v222, v164, s[48:49] offset:128
	global_load_dword v141, v165, s[48:49]
	global_load_dword v223, v165, s[48:49] offset:128
	s_add_u32 s48, s48, 0x8000
	s_addc_u32 s49, s49, 0
	global_load_dword v142, v162, s[48:49]
	global_load_dword v224, v162, s[48:49] offset:128
	global_load_dword v143, v163, s[48:49]
	global_load_dword v225, v163, s[48:49] offset:128
	global_load_dword v144, v164, s[48:49]
	global_load_dword v226, v164, s[48:49] offset:128
	global_load_dword v145, v165, s[48:49]
	global_load_dword v227, v165, s[48:49] offset:128
	s_sub_u32 s48, s48, 0x18000
	s_subb_u32 s49, s49, 0
	s_waitcnt vmcnt(30)
	v_fmac_f32_e32 v130, v34, v175
	v_fmac_f32_e32 v212, v50, v176
	global_store_dword v162, v130, s[48:49]
	global_store_dword v162, v212, s[48:49] offset:128
	s_waitcnt vmcnt(30)
	v_fmac_f32_e32 v131, v35, v175
	v_fmac_f32_e32 v213, v51, v176
	global_store_dword v163, v131, s[48:49]
	global_store_dword v163, v213, s[48:49] offset:128
	s_waitcnt vmcnt(30)
	v_fmac_f32_e32 v132, v36, v175
	v_fmac_f32_e32 v214, v52, v176
	global_store_dword v164, v132, s[48:49]
	global_store_dword v164, v214, s[48:49] offset:128
	s_waitcnt vmcnt(30)
	v_fmac_f32_e32 v133, v37, v175
	v_fmac_f32_e32 v215, v53, v176
	global_store_dword v165, v133, s[48:49]
	global_store_dword v165, v215, s[48:49] offset:128
	s_add_u32 s48, s48, 0x8000
	s_addc_u32 s49, s49, 0
	s_waitcnt vmcnt(30)
	v_fmac_f32_e32 v134, v38, v175
	v_fmac_f32_e32 v216, v54, v176
	global_store_dword v162, v134, s[48:49]
	global_store_dword v162, v216, s[48:49] offset:128
	s_waitcnt vmcnt(30)
	v_fmac_f32_e32 v135, v39, v175
	v_fmac_f32_e32 v217, v55, v176
	global_store_dword v163, v135, s[48:49]
	global_store_dword v163, v217, s[48:49] offset:128
	s_waitcnt vmcnt(30)
	v_fmac_f32_e32 v136, v40, v175
	v_fmac_f32_e32 v218, v56, v176
	global_store_dword v164, v136, s[48:49]
	global_store_dword v164, v218, s[48:49] offset:128
	s_waitcnt vmcnt(30)
	v_fmac_f32_e32 v137, v41, v175
	v_fmac_f32_e32 v219, v57, v176
	global_store_dword v165, v137, s[48:49]
	global_store_dword v165, v219, s[48:49] offset:128
	s_add_u32 s48, s48, 0x8000
	s_addc_u32 s49, s49, 0
	s_waitcnt vmcnt(30)
	v_fmac_f32_e32 v138, v42, v175
	v_fmac_f32_e32 v220, v58, v176
	global_store_dword v162, v138, s[48:49]
	global_store_dword v162, v220, s[48:49] offset:128
	s_waitcnt vmcnt(30)
	v_fmac_f32_e32 v139, v43, v175
	v_fmac_f32_e32 v221, v59, v176
	global_store_dword v163, v139, s[48:49]
	global_store_dword v163, v221, s[48:49] offset:128
	s_waitcnt vmcnt(30)
	v_fmac_f32_e32 v140, v44, v175
	v_fmac_f32_e32 v222, v60, v176
	global_store_dword v164, v140, s[48:49]
	global_store_dword v164, v222, s[48:49] offset:128
	s_waitcnt vmcnt(30)
	v_fmac_f32_e32 v141, v45, v175
	v_fmac_f32_e32 v223, v61, v176
	global_store_dword v165, v141, s[48:49]
	global_store_dword v165, v223, s[48:49] offset:128
	s_add_u32 s48, s48, 0x8000
	s_addc_u32 s49, s49, 0
	s_waitcnt vmcnt(30)
	v_fmac_f32_e32 v142, v46, v175
	v_fmac_f32_e32 v224, v62, v176
	global_store_dword v162, v142, s[48:49]
	global_store_dword v162, v224, s[48:49] offset:128
	s_waitcnt vmcnt(30)
	v_fmac_f32_e32 v143, v47, v175
	v_fmac_f32_e32 v225, v63, v176
	global_store_dword v163, v143, s[48:49]
	global_store_dword v163, v225, s[48:49] offset:128
	s_waitcnt vmcnt(30)
	v_fmac_f32_e32 v144, v48, v175
	v_fmac_f32_e32 v226, v64, v176
	global_store_dword v164, v144, s[48:49]
	global_store_dword v164, v226, s[48:49] offset:128
	s_waitcnt vmcnt(30)
	v_fmac_f32_e32 v145, v49, v175
	v_fmac_f32_e32 v227, v65, v176
	global_store_dword v165, v145, s[48:49]
	global_store_dword v165, v227, s[48:49] offset:128
	s_sub_u32 s48, s48, 0x18000
	s_subb_u32 s49, s49, 0
	v_mul_f32_e32 v130, v130, v130
	v_fmac_f32_e32 v130, v212, v212
	v_mul_f32_e32 v131, v131, v131
	v_fmac_f32_e32 v131, v213, v213
	v_mul_f32_e32 v132, v132, v132
	v_fmac_f32_e32 v132, v214, v214
	v_mul_f32_e32 v133, v133, v133
	v_fmac_f32_e32 v133, v215, v215
	v_mul_f32_e32 v134, v134, v134
	v_fmac_f32_e32 v134, v216, v216
	v_mul_f32_e32 v135, v135, v135
	v_fmac_f32_e32 v135, v217, v217
	v_mul_f32_e32 v136, v136, v136
	v_fmac_f32_e32 v136, v218, v218
	v_mul_f32_e32 v137, v137, v137
	v_fmac_f32_e32 v137, v219, v219
	v_mul_f32_e32 v138, v138, v138
	v_fmac_f32_e32 v138, v220, v220
	v_mul_f32_e32 v139, v139, v139
	v_fmac_f32_e32 v139, v221, v221
	v_mul_f32_e32 v140, v140, v140
	v_fmac_f32_e32 v140, v222, v222
	v_mul_f32_e32 v141, v141, v141
	v_fmac_f32_e32 v141, v223, v223
	v_mul_f32_e32 v142, v142, v142
	v_fmac_f32_e32 v142, v224, v224
	v_mul_f32_e32 v143, v143, v143
	v_fmac_f32_e32 v143, v225, v225
	v_mul_f32_e32 v144, v144, v144
	v_fmac_f32_e32 v144, v226, v226
	v_mul_f32_e32 v145, v145, v145
	v_fmac_f32_e32 v145, v227, v227
	s_waitcnt lgkmcnt(0)
	ds_bpermute_b32 v212, v168, v130
	ds_bpermute_b32 v213, v168, v131
	ds_bpermute_b32 v214, v168, v132
	ds_bpermute_b32 v215, v168, v133
	ds_bpermute_b32 v216, v168, v134
	ds_bpermute_b32 v217, v168, v135
	ds_bpermute_b32 v218, v168, v136
	ds_bpermute_b32 v219, v168, v137
	s_waitcnt lgkmcnt(7)
	v_add_f32_e32 v130, v130, v212
	s_waitcnt lgkmcnt(6)
	v_add_f32_e32 v131, v131, v213
	s_waitcnt lgkmcnt(5)
	v_add_f32_e32 v132, v132, v214
	s_waitcnt lgkmcnt(4)
	v_add_f32_e32 v133, v133, v215
	s_waitcnt lgkmcnt(3)
	v_add_f32_e32 v134, v134, v216
	s_waitcnt lgkmcnt(2)
	v_add_f32_e32 v135, v135, v217
	s_waitcnt lgkmcnt(1)
	v_add_f32_e32 v136, v136, v218
	s_waitcnt lgkmcnt(0)
	v_add_f32_e32 v137, v137, v219
	ds_bpermute_b32 v212, v169, v130
	ds_bpermute_b32 v213, v169, v131
	ds_bpermute_b32 v214, v169, v132
	ds_bpermute_b32 v215, v169, v133
	ds_bpermute_b32 v216, v169, v134
	ds_bpermute_b32 v217, v169, v135
	ds_bpermute_b32 v218, v169, v136
	ds_bpermute_b32 v219, v169, v137
	s_waitcnt lgkmcnt(7)
	v_add_f32_e32 v130, v130, v212
	s_waitcnt lgkmcnt(6)
	v_add_f32_e32 v131, v131, v213
	s_waitcnt lgkmcnt(5)
	v_add_f32_e32 v132, v132, v214
	s_waitcnt lgkmcnt(4)
	v_add_f32_e32 v133, v133, v215
	s_waitcnt lgkmcnt(3)
	v_add_f32_e32 v134, v134, v216
	s_waitcnt lgkmcnt(2)
	v_add_f32_e32 v135, v135, v217
	s_waitcnt lgkmcnt(1)
	v_add_f32_e32 v136, v136, v218
	s_waitcnt lgkmcnt(0)
	v_add_f32_e32 v137, v137, v219
	ds_bpermute_b32 v212, v171, v130
	ds_bpermute_b32 v213, v171, v131
	ds_bpermute_b32 v214, v171, v132
	ds_bpermute_b32 v215, v171, v133
	ds_bpermute_b32 v216, v171, v134
	ds_bpermute_b32 v217, v171, v135
	ds_bpermute_b32 v218, v171, v136
	ds_bpermute_b32 v219, v171, v137
	s_waitcnt lgkmcnt(7)
	v_add_f32_e32 v130, v130, v212
	s_waitcnt lgkmcnt(6)
	v_add_f32_e32 v131, v131, v213
	s_waitcnt lgkmcnt(5)
	v_add_f32_e32 v132, v132, v214
	s_waitcnt lgkmcnt(4)
	v_add_f32_e32 v133, v133, v215
	s_waitcnt lgkmcnt(3)
	v_add_f32_e32 v134, v134, v216
	s_waitcnt lgkmcnt(2)
	v_add_f32_e32 v135, v135, v217
	s_waitcnt lgkmcnt(1)
	v_add_f32_e32 v136, v136, v218
	s_waitcnt lgkmcnt(0)
	v_add_f32_e32 v137, v137, v219
	ds_bpermute_b32 v212, v172, v130
	ds_bpermute_b32 v213, v172, v131
	ds_bpermute_b32 v214, v172, v132
	ds_bpermute_b32 v215, v172, v133
	ds_bpermute_b32 v216, v172, v134
	ds_bpermute_b32 v217, v172, v135
	ds_bpermute_b32 v218, v172, v136
	ds_bpermute_b32 v219, v172, v137
	s_waitcnt lgkmcnt(7)
	v_add_f32_e32 v130, v130, v212
	s_waitcnt lgkmcnt(6)
	v_add_f32_e32 v131, v131, v213
	s_waitcnt lgkmcnt(5)
	v_add_f32_e32 v132, v132, v214
	s_waitcnt lgkmcnt(4)
	v_add_f32_e32 v133, v133, v215
	s_waitcnt lgkmcnt(3)
	v_add_f32_e32 v134, v134, v216
	s_waitcnt lgkmcnt(2)
	v_add_f32_e32 v135, v135, v217
	s_waitcnt lgkmcnt(1)
	v_add_f32_e32 v136, v136, v218
	s_waitcnt lgkmcnt(0)
	v_add_f32_e32 v137, v137, v219
	ds_bpermute_b32 v212, v173, v130
	ds_bpermute_b32 v213, v173, v131
	ds_bpermute_b32 v214, v173, v132
	ds_bpermute_b32 v215, v173, v133
	ds_bpermute_b32 v216, v173, v134
	ds_bpermute_b32 v217, v173, v135
	ds_bpermute_b32 v218, v173, v136
	ds_bpermute_b32 v219, v173, v137
	s_waitcnt lgkmcnt(7)
	v_add_f32_e32 v130, v130, v212
	s_waitcnt lgkmcnt(6)
	v_add_f32_e32 v131, v131, v213
	s_waitcnt lgkmcnt(5)
	v_add_f32_e32 v132, v132, v214
	s_waitcnt lgkmcnt(4)
	v_add_f32_e32 v133, v133, v215
	s_waitcnt lgkmcnt(3)
	v_add_f32_e32 v134, v134, v216
	s_waitcnt lgkmcnt(2)
	v_add_f32_e32 v135, v135, v217
	s_waitcnt lgkmcnt(1)
	v_add_f32_e32 v136, v136, v218
	s_waitcnt lgkmcnt(0)
	v_add_f32_e32 v137, v137, v219
	ds_bpermute_b32 v220, v168, v138
	ds_bpermute_b32 v221, v168, v139
	ds_bpermute_b32 v222, v168, v140
	ds_bpermute_b32 v223, v168, v141
	ds_bpermute_b32 v224, v168, v142
	ds_bpermute_b32 v225, v168, v143
	ds_bpermute_b32 v226, v168, v144
	ds_bpermute_b32 v227, v168, v145
	s_waitcnt lgkmcnt(7)
	v_add_f32_e32 v138, v138, v220
	s_waitcnt lgkmcnt(6)
	v_add_f32_e32 v139, v139, v221
	s_waitcnt lgkmcnt(5)
	v_add_f32_e32 v140, v140, v222
	s_waitcnt lgkmcnt(4)
	v_add_f32_e32 v141, v141, v223
	s_waitcnt lgkmcnt(3)
	v_add_f32_e32 v142, v142, v224
	s_waitcnt lgkmcnt(2)
	v_add_f32_e32 v143, v143, v225
	s_waitcnt lgkmcnt(1)
	v_add_f32_e32 v144, v144, v226
	s_waitcnt lgkmcnt(0)
	v_add_f32_e32 v145, v145, v227
	ds_bpermute_b32 v220, v169, v138
	ds_bpermute_b32 v221, v169, v139
	ds_bpermute_b32 v222, v169, v140
	ds_bpermute_b32 v223, v169, v141
	ds_bpermute_b32 v224, v169, v142
	ds_bpermute_b32 v225, v169, v143
	ds_bpermute_b32 v226, v169, v144
	ds_bpermute_b32 v227, v169, v145
	s_waitcnt lgkmcnt(7)
	v_add_f32_e32 v138, v138, v220
	s_waitcnt lgkmcnt(6)
	v_add_f32_e32 v139, v139, v221
	s_waitcnt lgkmcnt(5)
	v_add_f32_e32 v140, v140, v222
	s_waitcnt lgkmcnt(4)
	v_add_f32_e32 v141, v141, v223
	s_waitcnt lgkmcnt(3)
	v_add_f32_e32 v142, v142, v224
	s_waitcnt lgkmcnt(2)
	v_add_f32_e32 v143, v143, v225
	s_waitcnt lgkmcnt(1)
	v_add_f32_e32 v144, v144, v226
	s_waitcnt lgkmcnt(0)
	v_add_f32_e32 v145, v145, v227
	ds_bpermute_b32 v220, v171, v138
	ds_bpermute_b32 v221, v171, v139
	ds_bpermute_b32 v222, v171, v140
	ds_bpermute_b32 v223, v171, v141
	ds_bpermute_b32 v224, v171, v142
	ds_bpermute_b32 v225, v171, v143
	ds_bpermute_b32 v226, v171, v144
	ds_bpermute_b32 v227, v171, v145
	s_waitcnt lgkmcnt(7)
	v_add_f32_e32 v138, v138, v220
	s_waitcnt lgkmcnt(6)
	v_add_f32_e32 v139, v139, v221
	s_waitcnt lgkmcnt(5)
	v_add_f32_e32 v140, v140, v222
	s_waitcnt lgkmcnt(4)
	v_add_f32_e32 v141, v141, v223
	s_waitcnt lgkmcnt(3)
	v_add_f32_e32 v142, v142, v224
	s_waitcnt lgkmcnt(2)
	v_add_f32_e32 v143, v143, v225
	s_waitcnt lgkmcnt(1)
	v_add_f32_e32 v144, v144, v226
	s_waitcnt lgkmcnt(0)
	v_add_f32_e32 v145, v145, v227
	ds_bpermute_b32 v220, v172, v138
	ds_bpermute_b32 v221, v172, v139
	ds_bpermute_b32 v222, v172, v140
	ds_bpermute_b32 v223, v172, v141
	ds_bpermute_b32 v224, v172, v142
	ds_bpermute_b32 v225, v172, v143
	ds_bpermute_b32 v226, v172, v144
	ds_bpermute_b32 v227, v172, v145
	s_waitcnt lgkmcnt(7)
	v_add_f32_e32 v138, v138, v220
	s_waitcnt lgkmcnt(6)
	v_add_f32_e32 v139, v139, v221
	s_waitcnt lgkmcnt(5)
	v_add_f32_e32 v140, v140, v222
	s_waitcnt lgkmcnt(4)
	v_add_f32_e32 v141, v141, v223
	s_waitcnt lgkmcnt(3)
	v_add_f32_e32 v142, v142, v224
	s_waitcnt lgkmcnt(2)
	v_add_f32_e32 v143, v143, v225
	s_waitcnt lgkmcnt(1)
	v_add_f32_e32 v144, v144, v226
	s_waitcnt lgkmcnt(0)
	v_add_f32_e32 v145, v145, v227
	ds_bpermute_b32 v220, v173, v138
	ds_bpermute_b32 v221, v173, v139
	ds_bpermute_b32 v222, v173, v140
	ds_bpermute_b32 v223, v173, v141
	ds_bpermute_b32 v224, v173, v142
	ds_bpermute_b32 v225, v173, v143
	ds_bpermute_b32 v226, v173, v144
	ds_bpermute_b32 v227, v173, v145
	s_waitcnt lgkmcnt(7)
	v_add_f32_e32 v138, v138, v220
	s_waitcnt lgkmcnt(6)
	v_add_f32_e32 v139, v139, v221
	s_waitcnt lgkmcnt(5)
	v_add_f32_e32 v140, v140, v222
	s_waitcnt lgkmcnt(4)
	v_add_f32_e32 v141, v141, v223
	s_waitcnt lgkmcnt(3)
	v_add_f32_e32 v142, v142, v224
	s_waitcnt lgkmcnt(2)
	v_add_f32_e32 v143, v143, v225
	s_waitcnt lgkmcnt(1)
	v_add_f32_e32 v144, v144, v226
	s_waitcnt lgkmcnt(0)
	v_add_f32_e32 v145, v145, v227
	v_cmp_eq_u32_e32 vcc, 0, v174
	s_and_saveexec_b64 s[58:59], vcc
	global_store_dword v167, v130, s[10:11] offset:128
	global_store_dword v167, v131, s[10:11] offset:132
	global_store_dword v167, v132, s[10:11] offset:136
	global_store_dword v167, v133, s[10:11] offset:140
	global_store_dword v167, v134, s[10:11] offset:160
	global_store_dword v167, v135, s[10:11] offset:164
	global_store_dword v167, v136, s[10:11] offset:168
	global_store_dword v167, v137, s[10:11] offset:172
	global_store_dword v167, v138, s[10:11] offset:192
	global_store_dword v167, v139, s[10:11] offset:196
	global_store_dword v167, v140, s[10:11] offset:200
	global_store_dword v167, v141, s[10:11] offset:204
	global_store_dword v167, v142, s[10:11] offset:224
	global_store_dword v167, v143, s[10:11] offset:228
	global_store_dword v167, v144, s[10:11] offset:232
	global_store_dword v167, v145, s[10:11] offset:236
	s_mov_b64 exec, -1
	s_sub_u32 s48, s48, 0x20000
	s_subb_u32 s49, s49, 0
	s_add_u32 s60, s60, 0x200
	s_addc_u32 s61, s61, 0
	s_add_u32 s10, s10, 0x18000
	s_addc_u32 s11, s11, 0
	s_add_u32 s48, s48, 0x200
	s_addc_u32 s49, s49, 0
	global_load_dword v175, v166, s[60:61]
	global_load_dword v176, v166, s[60:61] offset:128
	global_load_dword v130, v162, s[48:49]
	global_load_dword v212, v162, s[48:49] offset:128
	global_load_dword v131, v163, s[48:49]
	global_load_dword v213, v163, s[48:49] offset:128
	global_load_dword v132, v164, s[48:49]
	global_load_dword v214, v164, s[48:49] offset:128
	global_load_dword v133, v165, s[48:49]
	global_load_dword v215, v165, s[48:49] offset:128
	s_add_u32 s48, s48, 0x8000
	s_addc_u32 s49, s49, 0
	global_load_dword v134, v162, s[48:49]
	global_load_dword v216, v162, s[48:49] offset:128
	global_load_dword v135, v163, s[48:49]
	global_load_dword v217, v163, s[48:49] offset:128
	global_load_dword v136, v164, s[48:49]
	global_load_dword v218, v164, s[48:49] offset:128
	global_load_dword v137, v165, s[48:49]
	global_load_dword v219, v165, s[48:49] offset:128
	s_add_u32 s48, s48, 0x8000
	s_addc_u32 s49, s49, 0
	global_load_dword v138, v162, s[48:49]
	global_load_dword v220, v162, s[48:49] offset:128
	global_load_dword v139, v163, s[48:49]
	global_load_dword v221, v163, s[48:49] offset:128
	global_load_dword v140, v164, s[48:49]
	global_load_dword v222, v164, s[48:49] offset:128
	global_load_dword v141, v165, s[48:49]
	global_load_dword v223, v165, s[48:49] offset:128
	s_add_u32 s48, s48, 0x8000
	s_addc_u32 s49, s49, 0
	global_load_dword v142, v162, s[48:49]
	global_load_dword v224, v162, s[48:49] offset:128
	global_load_dword v143, v163, s[48:49]
	global_load_dword v225, v163, s[48:49] offset:128
	global_load_dword v144, v164, s[48:49]
	global_load_dword v226, v164, s[48:49] offset:128
	global_load_dword v145, v165, s[48:49]
	global_load_dword v227, v165, s[48:49] offset:128
	s_sub_u32 s48, s48, 0x18000
	s_subb_u32 s49, s49, 0
	s_waitcnt vmcnt(32)
	s_waitcnt vmcnt(30)
	v_fmac_f32_e32 v130, v66, v175
	v_fmac_f32_e32 v212, v82, v176
	global_store_dword v162, v130, s[48:49]
	global_store_dword v162, v212, s[48:49] offset:128
	s_waitcnt vmcnt(30)
	v_fmac_f32_e32 v131, v67, v175
	v_fmac_f32_e32 v213, v83, v176
	global_store_dword v163, v131, s[48:49]
	global_store_dword v163, v213, s[48:49] offset:128
	s_waitcnt vmcnt(30)
	v_fmac_f32_e32 v132, v68, v175
	v_fmac_f32_e32 v214, v84, v176
	global_store_dword v164, v132, s[48:49]
	global_store_dword v164, v214, s[48:49] offset:128
	s_waitcnt vmcnt(30)
	v_fmac_f32_e32 v133, v69, v175
	v_fmac_f32_e32 v215, v85, v176
	global_store_dword v165, v133, s[48:49]
	global_store_dword v165, v215, s[48:49] offset:128
	s_add_u32 s48, s48, 0x8000
	s_addc_u32 s49, s49, 0
	s_waitcnt vmcnt(30)
	v_fmac_f32_e32 v134, v70, v175
	v_fmac_f32_e32 v216, v86, v176
	global_store_dword v162, v134, s[48:49]
	global_store_dword v162, v216, s[48:49] offset:128
	s_waitcnt vmcnt(30)
	v_fmac_f32_e32 v135, v71, v175
	v_fmac_f32_e32 v217, v87, v176
	global_store_dword v163, v135, s[48:49]
	global_store_dword v163, v217, s[48:49] offset:128
	s_waitcnt vmcnt(30)
	v_fmac_f32_e32 v136, v72, v175
	v_fmac_f32_e32 v218, v88, v176
	global_store_dword v164, v136, s[48:49]
	global_store_dword v164, v218, s[48:49] offset:128
	s_waitcnt vmcnt(30)
	v_fmac_f32_e32 v137, v73, v175
	v_fmac_f32_e32 v219, v89, v176
	global_store_dword v165, v137, s[48:49]
	global_store_dword v165, v219, s[48:49] offset:128
	s_add_u32 s48, s48, 0x8000
	s_addc_u32 s49, s49, 0
	s_waitcnt vmcnt(30)
	v_fmac_f32_e32 v138, v74, v175
	v_fmac_f32_e32 v220, v90, v176
	global_store_dword v162, v138, s[48:49]
	global_store_dword v162, v220, s[48:49] offset:128
	s_waitcnt vmcnt(30)
	v_fmac_f32_e32 v139, v75, v175
	v_fmac_f32_e32 v221, v91, v176
	global_store_dword v163, v139, s[48:49]
	global_store_dword v163, v221, s[48:49] offset:128
	s_waitcnt vmcnt(30)
	v_fmac_f32_e32 v140, v76, v175
	v_fmac_f32_e32 v222, v92, v176
	global_store_dword v164, v140, s[48:49]
	global_store_dword v164, v222, s[48:49] offset:128
	s_waitcnt vmcnt(30)
	v_fmac_f32_e32 v141, v77, v175
	v_fmac_f32_e32 v223, v93, v176
	global_store_dword v165, v141, s[48:49]
	global_store_dword v165, v223, s[48:49] offset:128
	s_add_u32 s48, s48, 0x8000
	s_addc_u32 s49, s49, 0
	s_waitcnt vmcnt(30)
	v_fmac_f32_e32 v142, v78, v175
	v_fmac_f32_e32 v224, v94, v176
	global_store_dword v162, v142, s[48:49]
	global_store_dword v162, v224, s[48:49] offset:128
	s_waitcnt vmcnt(30)
	v_fmac_f32_e32 v143, v79, v175
	v_fmac_f32_e32 v225, v95, v176
	global_store_dword v163, v143, s[48:49]
	global_store_dword v163, v225, s[48:49] offset:128
	s_waitcnt vmcnt(30)
	v_fmac_f32_e32 v144, v80, v175
	v_fmac_f32_e32 v226, v96, v176
	global_store_dword v164, v144, s[48:49]
	global_store_dword v164, v226, s[48:49] offset:128
	s_waitcnt vmcnt(30)
	v_fmac_f32_e32 v145, v81, v175
	v_fmac_f32_e32 v227, v97, v176
	global_store_dword v165, v145, s[48:49]
	global_store_dword v165, v227, s[48:49] offset:128
	s_sub_u32 s48, s48, 0x18000
	s_subb_u32 s49, s49, 0
	v_mul_f32_e32 v130, v130, v130
	v_fmac_f32_e32 v130, v212, v212
	v_mul_f32_e32 v131, v131, v131
	v_fmac_f32_e32 v131, v213, v213
	v_mul_f32_e32 v132, v132, v132
	v_fmac_f32_e32 v132, v214, v214
	v_mul_f32_e32 v133, v133, v133
	v_fmac_f32_e32 v133, v215, v215
	v_mul_f32_e32 v134, v134, v134
	v_fmac_f32_e32 v134, v216, v216
	v_mul_f32_e32 v135, v135, v135
	v_fmac_f32_e32 v135, v217, v217
	v_mul_f32_e32 v136, v136, v136
	v_fmac_f32_e32 v136, v218, v218
	v_mul_f32_e32 v137, v137, v137
	v_fmac_f32_e32 v137, v219, v219
	v_mul_f32_e32 v138, v138, v138
	v_fmac_f32_e32 v138, v220, v220
	v_mul_f32_e32 v139, v139, v139
	v_fmac_f32_e32 v139, v221, v221
	v_mul_f32_e32 v140, v140, v140
	v_fmac_f32_e32 v140, v222, v222
	v_mul_f32_e32 v141, v141, v141
	v_fmac_f32_e32 v141, v223, v223
	v_mul_f32_e32 v142, v142, v142
	v_fmac_f32_e32 v142, v224, v224
	v_mul_f32_e32 v143, v143, v143
	v_fmac_f32_e32 v143, v225, v225
	v_mul_f32_e32 v144, v144, v144
	v_fmac_f32_e32 v144, v226, v226
	v_mul_f32_e32 v145, v145, v145
	v_fmac_f32_e32 v145, v227, v227
	s_waitcnt lgkmcnt(0)
	ds_bpermute_b32 v212, v168, v130
	ds_bpermute_b32 v213, v168, v131
	ds_bpermute_b32 v214, v168, v132
	ds_bpermute_b32 v215, v168, v133
	ds_bpermute_b32 v216, v168, v134
	ds_bpermute_b32 v217, v168, v135
	ds_bpermute_b32 v218, v168, v136
	ds_bpermute_b32 v219, v168, v137
	s_waitcnt lgkmcnt(7)
	v_add_f32_e32 v130, v130, v212
	s_waitcnt lgkmcnt(6)
	v_add_f32_e32 v131, v131, v213
	s_waitcnt lgkmcnt(5)
	v_add_f32_e32 v132, v132, v214
	s_waitcnt lgkmcnt(4)
	v_add_f32_e32 v133, v133, v215
	s_waitcnt lgkmcnt(3)
	v_add_f32_e32 v134, v134, v216
	s_waitcnt lgkmcnt(2)
	v_add_f32_e32 v135, v135, v217
	s_waitcnt lgkmcnt(1)
	v_add_f32_e32 v136, v136, v218
	s_waitcnt lgkmcnt(0)
	v_add_f32_e32 v137, v137, v219
	ds_bpermute_b32 v212, v169, v130
	ds_bpermute_b32 v213, v169, v131
	ds_bpermute_b32 v214, v169, v132
	ds_bpermute_b32 v215, v169, v133
	ds_bpermute_b32 v216, v169, v134
	ds_bpermute_b32 v217, v169, v135
	ds_bpermute_b32 v218, v169, v136
	ds_bpermute_b32 v219, v169, v137
	s_waitcnt lgkmcnt(7)
	v_add_f32_e32 v130, v130, v212
	s_waitcnt lgkmcnt(6)
	v_add_f32_e32 v131, v131, v213
	s_waitcnt lgkmcnt(5)
	v_add_f32_e32 v132, v132, v214
	s_waitcnt lgkmcnt(4)
	v_add_f32_e32 v133, v133, v215
	s_waitcnt lgkmcnt(3)
	v_add_f32_e32 v134, v134, v216
	s_waitcnt lgkmcnt(2)
	v_add_f32_e32 v135, v135, v217
	s_waitcnt lgkmcnt(1)
	v_add_f32_e32 v136, v136, v218
	s_waitcnt lgkmcnt(0)
	v_add_f32_e32 v137, v137, v219
	ds_bpermute_b32 v212, v171, v130
	ds_bpermute_b32 v213, v171, v131
	ds_bpermute_b32 v214, v171, v132
	ds_bpermute_b32 v215, v171, v133
	ds_bpermute_b32 v216, v171, v134
	ds_bpermute_b32 v217, v171, v135
	ds_bpermute_b32 v218, v171, v136
	ds_bpermute_b32 v219, v171, v137
	s_waitcnt lgkmcnt(7)
	v_add_f32_e32 v130, v130, v212
	s_waitcnt lgkmcnt(6)
	v_add_f32_e32 v131, v131, v213
	s_waitcnt lgkmcnt(5)
	v_add_f32_e32 v132, v132, v214
	s_waitcnt lgkmcnt(4)
	v_add_f32_e32 v133, v133, v215
	s_waitcnt lgkmcnt(3)
	v_add_f32_e32 v134, v134, v216
	s_waitcnt lgkmcnt(2)
	v_add_f32_e32 v135, v135, v217
	s_waitcnt lgkmcnt(1)
	v_add_f32_e32 v136, v136, v218
	s_waitcnt lgkmcnt(0)
	v_add_f32_e32 v137, v137, v219
	ds_bpermute_b32 v212, v172, v130
	ds_bpermute_b32 v213, v172, v131
	ds_bpermute_b32 v214, v172, v132
	ds_bpermute_b32 v215, v172, v133
	ds_bpermute_b32 v216, v172, v134
	ds_bpermute_b32 v217, v172, v135
	ds_bpermute_b32 v218, v172, v136
	ds_bpermute_b32 v219, v172, v137
	s_waitcnt lgkmcnt(7)
	v_add_f32_e32 v130, v130, v212
	s_waitcnt lgkmcnt(6)
	v_add_f32_e32 v131, v131, v213
	s_waitcnt lgkmcnt(5)
	v_add_f32_e32 v132, v132, v214
	s_waitcnt lgkmcnt(4)
	v_add_f32_e32 v133, v133, v215
	s_waitcnt lgkmcnt(3)
	v_add_f32_e32 v134, v134, v216
	s_waitcnt lgkmcnt(2)
	v_add_f32_e32 v135, v135, v217
	s_waitcnt lgkmcnt(1)
	v_add_f32_e32 v136, v136, v218
	s_waitcnt lgkmcnt(0)
	v_add_f32_e32 v137, v137, v219
	ds_bpermute_b32 v212, v173, v130
	ds_bpermute_b32 v213, v173, v131
	ds_bpermute_b32 v214, v173, v132
	ds_bpermute_b32 v215, v173, v133
	ds_bpermute_b32 v216, v173, v134
	ds_bpermute_b32 v217, v173, v135
	ds_bpermute_b32 v218, v173, v136
	ds_bpermute_b32 v219, v173, v137
	s_waitcnt lgkmcnt(7)
	v_add_f32_e32 v130, v130, v212
	s_waitcnt lgkmcnt(6)
	v_add_f32_e32 v131, v131, v213
	s_waitcnt lgkmcnt(5)
	v_add_f32_e32 v132, v132, v214
	s_waitcnt lgkmcnt(4)
	v_add_f32_e32 v133, v133, v215
	s_waitcnt lgkmcnt(3)
	v_add_f32_e32 v134, v134, v216
	s_waitcnt lgkmcnt(2)
	v_add_f32_e32 v135, v135, v217
	s_waitcnt lgkmcnt(1)
	v_add_f32_e32 v136, v136, v218
	s_waitcnt lgkmcnt(0)
	v_add_f32_e32 v137, v137, v219
	ds_bpermute_b32 v220, v168, v138
	ds_bpermute_b32 v221, v168, v139
	ds_bpermute_b32 v222, v168, v140
	ds_bpermute_b32 v223, v168, v141
	ds_bpermute_b32 v224, v168, v142
	ds_bpermute_b32 v225, v168, v143
	ds_bpermute_b32 v226, v168, v144
	ds_bpermute_b32 v227, v168, v145
	s_waitcnt lgkmcnt(7)
	v_add_f32_e32 v138, v138, v220
	s_waitcnt lgkmcnt(6)
	v_add_f32_e32 v139, v139, v221
	s_waitcnt lgkmcnt(5)
	v_add_f32_e32 v140, v140, v222
	s_waitcnt lgkmcnt(4)
	v_add_f32_e32 v141, v141, v223
	s_waitcnt lgkmcnt(3)
	v_add_f32_e32 v142, v142, v224
	s_waitcnt lgkmcnt(2)
	v_add_f32_e32 v143, v143, v225
	s_waitcnt lgkmcnt(1)
	v_add_f32_e32 v144, v144, v226
	s_waitcnt lgkmcnt(0)
	v_add_f32_e32 v145, v145, v227
	ds_bpermute_b32 v220, v169, v138
	ds_bpermute_b32 v221, v169, v139
	ds_bpermute_b32 v222, v169, v140
	ds_bpermute_b32 v223, v169, v141
	ds_bpermute_b32 v224, v169, v142
	ds_bpermute_b32 v225, v169, v143
	ds_bpermute_b32 v226, v169, v144
	ds_bpermute_b32 v227, v169, v145
	s_waitcnt lgkmcnt(7)
	v_add_f32_e32 v138, v138, v220
	s_waitcnt lgkmcnt(6)
	v_add_f32_e32 v139, v139, v221
	s_waitcnt lgkmcnt(5)
	v_add_f32_e32 v140, v140, v222
	s_waitcnt lgkmcnt(4)
	v_add_f32_e32 v141, v141, v223
	s_waitcnt lgkmcnt(3)
	v_add_f32_e32 v142, v142, v224
	s_waitcnt lgkmcnt(2)
	v_add_f32_e32 v143, v143, v225
	s_waitcnt lgkmcnt(1)
	v_add_f32_e32 v144, v144, v226
	s_waitcnt lgkmcnt(0)
	v_add_f32_e32 v145, v145, v227
	ds_bpermute_b32 v220, v171, v138
	ds_bpermute_b32 v221, v171, v139
	ds_bpermute_b32 v222, v171, v140
	ds_bpermute_b32 v223, v171, v141
	ds_bpermute_b32 v224, v171, v142
	ds_bpermute_b32 v225, v171, v143
	ds_bpermute_b32 v226, v171, v144
	ds_bpermute_b32 v227, v171, v145
	s_waitcnt lgkmcnt(7)
	v_add_f32_e32 v138, v138, v220
	s_waitcnt lgkmcnt(6)
	v_add_f32_e32 v139, v139, v221
	s_waitcnt lgkmcnt(5)
	v_add_f32_e32 v140, v140, v222
	s_waitcnt lgkmcnt(4)
	v_add_f32_e32 v141, v141, v223
	s_waitcnt lgkmcnt(3)
	v_add_f32_e32 v142, v142, v224
	s_waitcnt lgkmcnt(2)
	v_add_f32_e32 v143, v143, v225
	s_waitcnt lgkmcnt(1)
	v_add_f32_e32 v144, v144, v226
	s_waitcnt lgkmcnt(0)
	v_add_f32_e32 v145, v145, v227
	ds_bpermute_b32 v220, v172, v138
	ds_bpermute_b32 v221, v172, v139
	ds_bpermute_b32 v222, v172, v140
	ds_bpermute_b32 v223, v172, v141
	ds_bpermute_b32 v224, v172, v142
	ds_bpermute_b32 v225, v172, v143
	ds_bpermute_b32 v226, v172, v144
	ds_bpermute_b32 v227, v172, v145
	s_waitcnt lgkmcnt(7)
	v_add_f32_e32 v138, v138, v220
	s_waitcnt lgkmcnt(6)
	v_add_f32_e32 v139, v139, v221
	s_waitcnt lgkmcnt(5)
	v_add_f32_e32 v140, v140, v222
	s_waitcnt lgkmcnt(4)
	v_add_f32_e32 v141, v141, v223
	s_waitcnt lgkmcnt(3)
	v_add_f32_e32 v142, v142, v224
	s_waitcnt lgkmcnt(2)
	v_add_f32_e32 v143, v143, v225
	s_waitcnt lgkmcnt(1)
	v_add_f32_e32 v144, v144, v226
	s_waitcnt lgkmcnt(0)
	v_add_f32_e32 v145, v145, v227
	ds_bpermute_b32 v220, v173, v138
	ds_bpermute_b32 v221, v173, v139
	ds_bpermute_b32 v222, v173, v140
	ds_bpermute_b32 v223, v173, v141
	ds_bpermute_b32 v224, v173, v142
	ds_bpermute_b32 v225, v173, v143
	ds_bpermute_b32 v226, v173, v144
	ds_bpermute_b32 v227, v173, v145
	s_waitcnt lgkmcnt(7)
	v_add_f32_e32 v138, v138, v220
	s_waitcnt lgkmcnt(6)
	v_add_f32_e32 v139, v139, v221
	s_waitcnt lgkmcnt(5)
	v_add_f32_e32 v140, v140, v222
	s_waitcnt lgkmcnt(4)
	v_add_f32_e32 v141, v141, v223
	s_waitcnt lgkmcnt(3)
	v_add_f32_e32 v142, v142, v224
	s_waitcnt lgkmcnt(2)
	v_add_f32_e32 v143, v143, v225
	s_waitcnt lgkmcnt(1)
	v_add_f32_e32 v144, v144, v226
	s_waitcnt lgkmcnt(0)
	v_add_f32_e32 v145, v145, v227
	v_cmp_eq_u32_e32 vcc, 0, v174
	s_and_saveexec_b64 s[58:59], vcc
	global_store_dword v167, v130, s[10:11]
	global_store_dword v167, v131, s[10:11] offset:4
	global_store_dword v167, v132, s[10:11] offset:8
	global_store_dword v167, v133, s[10:11] offset:12
	global_store_dword v167, v134, s[10:11] offset:32
	global_store_dword v167, v135, s[10:11] offset:36
	global_store_dword v167, v136, s[10:11] offset:40
	global_store_dword v167, v137, s[10:11] offset:44
	global_store_dword v167, v138, s[10:11] offset:64
	global_store_dword v167, v139, s[10:11] offset:68
	global_store_dword v167, v140, s[10:11] offset:72
	global_store_dword v167, v141, s[10:11] offset:76
	global_store_dword v167, v142, s[10:11] offset:96
	global_store_dword v167, v143, s[10:11] offset:100
	global_store_dword v167, v144, s[10:11] offset:104
	global_store_dword v167, v145, s[10:11] offset:108
	s_mov_b64 exec, -1
	s_add_u32 s48, s48, 0x20000
	s_addc_u32 s49, s49, 0
	global_load_dword v130, v162, s[48:49]
	global_load_dword v212, v162, s[48:49] offset:128
	global_load_dword v131, v163, s[48:49]
	global_load_dword v213, v163, s[48:49] offset:128
	global_load_dword v132, v164, s[48:49]
	global_load_dword v214, v164, s[48:49] offset:128
	global_load_dword v133, v165, s[48:49]
	global_load_dword v215, v165, s[48:49] offset:128
	s_add_u32 s48, s48, 0x8000
	s_addc_u32 s49, s49, 0
	global_load_dword v134, v162, s[48:49]
	global_load_dword v216, v162, s[48:49] offset:128
	global_load_dword v135, v163, s[48:49]
	global_load_dword v217, v163, s[48:49] offset:128
	global_load_dword v136, v164, s[48:49]
	global_load_dword v218, v164, s[48:49] offset:128
	global_load_dword v137, v165, s[48:49]
	global_load_dword v219, v165, s[48:49] offset:128
	s_add_u32 s48, s48, 0x8000
	s_addc_u32 s49, s49, 0
	global_load_dword v138, v162, s[48:49]
	global_load_dword v220, v162, s[48:49] offset:128
	global_load_dword v139, v163, s[48:49]
	global_load_dword v221, v163, s[48:49] offset:128
	global_load_dword v140, v164, s[48:49]
	global_load_dword v222, v164, s[48:49] offset:128
	global_load_dword v141, v165, s[48:49]
	global_load_dword v223, v165, s[48:49] offset:128
	s_add_u32 s48, s48, 0x8000
	s_addc_u32 s49, s49, 0
	global_load_dword v142, v162, s[48:49]
	global_load_dword v224, v162, s[48:49] offset:128
	global_load_dword v143, v163, s[48:49]
	global_load_dword v225, v163, s[48:49] offset:128
	global_load_dword v144, v164, s[48:49]
	global_load_dword v226, v164, s[48:49] offset:128
	global_load_dword v145, v165, s[48:49]
	global_load_dword v227, v165, s[48:49] offset:128
	s_sub_u32 s48, s48, 0x18000
	s_subb_u32 s49, s49, 0
	s_waitcnt vmcnt(30)
	v_fmac_f32_e32 v130, v98, v175
	v_fmac_f32_e32 v212, v114, v176
	global_store_dword v162, v130, s[48:49]
	global_store_dword v162, v212, s[48:49] offset:128
	s_waitcnt vmcnt(30)
	v_fmac_f32_e32 v131, v99, v175
	v_fmac_f32_e32 v213, v115, v176
	global_store_dword v163, v131, s[48:49]
	global_store_dword v163, v213, s[48:49] offset:128
	s_waitcnt vmcnt(30)
	v_fmac_f32_e32 v132, v100, v175
	v_fmac_f32_e32 v214, v116, v176
	global_store_dword v164, v132, s[48:49]
	global_store_dword v164, v214, s[48:49] offset:128
	s_waitcnt vmcnt(30)
	v_fmac_f32_e32 v133, v101, v175
	v_fmac_f32_e32 v215, v117, v176
	global_store_dword v165, v133, s[48:49]
	global_store_dword v165, v215, s[48:49] offset:128
	s_add_u32 s48, s48, 0x8000
	s_addc_u32 s49, s49, 0
	s_waitcnt vmcnt(30)
	v_fmac_f32_e32 v134, v102, v175
	v_fmac_f32_e32 v216, v118, v176
	global_store_dword v162, v134, s[48:49]
	global_store_dword v162, v216, s[48:49] offset:128
	s_waitcnt vmcnt(30)
	v_fmac_f32_e32 v135, v103, v175
	v_fmac_f32_e32 v217, v119, v176
	global_store_dword v163, v135, s[48:49]
	global_store_dword v163, v217, s[48:49] offset:128
	s_waitcnt vmcnt(30)
	v_fmac_f32_e32 v136, v104, v175
	v_fmac_f32_e32 v218, v120, v176
	global_store_dword v164, v136, s[48:49]
	global_store_dword v164, v218, s[48:49] offset:128
	s_waitcnt vmcnt(30)
	v_fmac_f32_e32 v137, v105, v175
	v_fmac_f32_e32 v219, v121, v176
	global_store_dword v165, v137, s[48:49]
	global_store_dword v165, v219, s[48:49] offset:128
	s_add_u32 s48, s48, 0x8000
	s_addc_u32 s49, s49, 0
	s_waitcnt vmcnt(30)
	v_fmac_f32_e32 v138, v106, v175
	v_fmac_f32_e32 v220, v122, v176
	global_store_dword v162, v138, s[48:49]
	global_store_dword v162, v220, s[48:49] offset:128
	s_waitcnt vmcnt(30)
	v_fmac_f32_e32 v139, v107, v175
	v_fmac_f32_e32 v221, v123, v176
	global_store_dword v163, v139, s[48:49]
	global_store_dword v163, v221, s[48:49] offset:128
	s_waitcnt vmcnt(30)
	v_fmac_f32_e32 v140, v108, v175
	v_fmac_f32_e32 v222, v124, v176
	global_store_dword v164, v140, s[48:49]
	global_store_dword v164, v222, s[48:49] offset:128
	s_waitcnt vmcnt(30)
	v_fmac_f32_e32 v141, v109, v175
	v_fmac_f32_e32 v223, v125, v176
	global_store_dword v165, v141, s[48:49]
	global_store_dword v165, v223, s[48:49] offset:128
	s_add_u32 s48, s48, 0x8000
	s_addc_u32 s49, s49, 0
	s_waitcnt vmcnt(30)
	v_fmac_f32_e32 v142, v110, v175
	v_fmac_f32_e32 v224, v126, v176
	global_store_dword v162, v142, s[48:49]
	global_store_dword v162, v224, s[48:49] offset:128
	s_waitcnt vmcnt(30)
	v_fmac_f32_e32 v143, v111, v175
	v_fmac_f32_e32 v225, v127, v176
	global_store_dword v163, v143, s[48:49]
	global_store_dword v163, v225, s[48:49] offset:128
	s_waitcnt vmcnt(30)
	v_fmac_f32_e32 v144, v112, v175
	v_fmac_f32_e32 v226, v128, v176
	global_store_dword v164, v144, s[48:49]
	global_store_dword v164, v226, s[48:49] offset:128
	s_waitcnt vmcnt(30)
	v_fmac_f32_e32 v145, v113, v175
	v_fmac_f32_e32 v227, v129, v176
	global_store_dword v165, v145, s[48:49]
	global_store_dword v165, v227, s[48:49] offset:128
	s_sub_u32 s48, s48, 0x18000
	s_subb_u32 s49, s49, 0
	v_mul_f32_e32 v130, v130, v130
	v_fmac_f32_e32 v130, v212, v212
	v_mul_f32_e32 v131, v131, v131
	v_fmac_f32_e32 v131, v213, v213
	v_mul_f32_e32 v132, v132, v132
	v_fmac_f32_e32 v132, v214, v214
	v_mul_f32_e32 v133, v133, v133
	v_fmac_f32_e32 v133, v215, v215
	v_mul_f32_e32 v134, v134, v134
	v_fmac_f32_e32 v134, v216, v216
	v_mul_f32_e32 v135, v135, v135
	v_fmac_f32_e32 v135, v217, v217
	v_mul_f32_e32 v136, v136, v136
	v_fmac_f32_e32 v136, v218, v218
	v_mul_f32_e32 v137, v137, v137
	v_fmac_f32_e32 v137, v219, v219
	v_mul_f32_e32 v138, v138, v138
	v_fmac_f32_e32 v138, v220, v220
	v_mul_f32_e32 v139, v139, v139
	v_fmac_f32_e32 v139, v221, v221
	v_mul_f32_e32 v140, v140, v140
	v_fmac_f32_e32 v140, v222, v222
	v_mul_f32_e32 v141, v141, v141
	v_fmac_f32_e32 v141, v223, v223
	v_mul_f32_e32 v142, v142, v142
	v_fmac_f32_e32 v142, v224, v224
	v_mul_f32_e32 v143, v143, v143
	v_fmac_f32_e32 v143, v225, v225
	v_mul_f32_e32 v144, v144, v144
	v_fmac_f32_e32 v144, v226, v226
	v_mul_f32_e32 v145, v145, v145
	v_fmac_f32_e32 v145, v227, v227
	s_waitcnt lgkmcnt(0)
	ds_bpermute_b32 v212, v168, v130
	ds_bpermute_b32 v213, v168, v131
	ds_bpermute_b32 v214, v168, v132
	ds_bpermute_b32 v215, v168, v133
	ds_bpermute_b32 v216, v168, v134
	ds_bpermute_b32 v217, v168, v135
	ds_bpermute_b32 v218, v168, v136
	ds_bpermute_b32 v219, v168, v137
	s_waitcnt lgkmcnt(7)
	v_add_f32_e32 v130, v130, v212
	s_waitcnt lgkmcnt(6)
	v_add_f32_e32 v131, v131, v213
	s_waitcnt lgkmcnt(5)
	v_add_f32_e32 v132, v132, v214
	s_waitcnt lgkmcnt(4)
	v_add_f32_e32 v133, v133, v215
	s_waitcnt lgkmcnt(3)
	v_add_f32_e32 v134, v134, v216
	s_waitcnt lgkmcnt(2)
	v_add_f32_e32 v135, v135, v217
	s_waitcnt lgkmcnt(1)
	v_add_f32_e32 v136, v136, v218
	s_waitcnt lgkmcnt(0)
	v_add_f32_e32 v137, v137, v219
	ds_bpermute_b32 v212, v169, v130
	ds_bpermute_b32 v213, v169, v131
	ds_bpermute_b32 v214, v169, v132
	ds_bpermute_b32 v215, v169, v133
	ds_bpermute_b32 v216, v169, v134
	ds_bpermute_b32 v217, v169, v135
	ds_bpermute_b32 v218, v169, v136
	ds_bpermute_b32 v219, v169, v137
	s_waitcnt lgkmcnt(7)
	v_add_f32_e32 v130, v130, v212
	s_waitcnt lgkmcnt(6)
	v_add_f32_e32 v131, v131, v213
	s_waitcnt lgkmcnt(5)
	v_add_f32_e32 v132, v132, v214
	s_waitcnt lgkmcnt(4)
	v_add_f32_e32 v133, v133, v215
	s_waitcnt lgkmcnt(3)
	v_add_f32_e32 v134, v134, v216
	s_waitcnt lgkmcnt(2)
	v_add_f32_e32 v135, v135, v217
	s_waitcnt lgkmcnt(1)
	v_add_f32_e32 v136, v136, v218
	s_waitcnt lgkmcnt(0)
	v_add_f32_e32 v137, v137, v219
	ds_bpermute_b32 v212, v171, v130
	ds_bpermute_b32 v213, v171, v131
	ds_bpermute_b32 v214, v171, v132
	ds_bpermute_b32 v215, v171, v133
	ds_bpermute_b32 v216, v171, v134
	ds_bpermute_b32 v217, v171, v135
	ds_bpermute_b32 v218, v171, v136
	ds_bpermute_b32 v219, v171, v137
	s_waitcnt lgkmcnt(7)
	v_add_f32_e32 v130, v130, v212
	s_waitcnt lgkmcnt(6)
	v_add_f32_e32 v131, v131, v213
	s_waitcnt lgkmcnt(5)
	v_add_f32_e32 v132, v132, v214
	s_waitcnt lgkmcnt(4)
	v_add_f32_e32 v133, v133, v215
	s_waitcnt lgkmcnt(3)
	v_add_f32_e32 v134, v134, v216
	s_waitcnt lgkmcnt(2)
	v_add_f32_e32 v135, v135, v217
	s_waitcnt lgkmcnt(1)
	v_add_f32_e32 v136, v136, v218
	s_waitcnt lgkmcnt(0)
	v_add_f32_e32 v137, v137, v219
	ds_bpermute_b32 v212, v172, v130
	ds_bpermute_b32 v213, v172, v131
	ds_bpermute_b32 v214, v172, v132
	ds_bpermute_b32 v215, v172, v133
	ds_bpermute_b32 v216, v172, v134
	ds_bpermute_b32 v217, v172, v135
	ds_bpermute_b32 v218, v172, v136
	ds_bpermute_b32 v219, v172, v137
	s_waitcnt lgkmcnt(7)
	v_add_f32_e32 v130, v130, v212
	s_waitcnt lgkmcnt(6)
	v_add_f32_e32 v131, v131, v213
	s_waitcnt lgkmcnt(5)
	v_add_f32_e32 v132, v132, v214
	s_waitcnt lgkmcnt(4)
	v_add_f32_e32 v133, v133, v215
	s_waitcnt lgkmcnt(3)
	v_add_f32_e32 v134, v134, v216
	s_waitcnt lgkmcnt(2)
	v_add_f32_e32 v135, v135, v217
	s_waitcnt lgkmcnt(1)
	v_add_f32_e32 v136, v136, v218
	s_waitcnt lgkmcnt(0)
	v_add_f32_e32 v137, v137, v219
	ds_bpermute_b32 v212, v173, v130
	ds_bpermute_b32 v213, v173, v131
	ds_bpermute_b32 v214, v173, v132
	ds_bpermute_b32 v215, v173, v133
	ds_bpermute_b32 v216, v173, v134
	ds_bpermute_b32 v217, v173, v135
	ds_bpermute_b32 v218, v173, v136
	ds_bpermute_b32 v219, v173, v137
	s_waitcnt lgkmcnt(7)
	v_add_f32_e32 v130, v130, v212
	s_waitcnt lgkmcnt(6)
	v_add_f32_e32 v131, v131, v213
	s_waitcnt lgkmcnt(5)
	v_add_f32_e32 v132, v132, v214
	s_waitcnt lgkmcnt(4)
	v_add_f32_e32 v133, v133, v215
	s_waitcnt lgkmcnt(3)
	v_add_f32_e32 v134, v134, v216
	s_waitcnt lgkmcnt(2)
	v_add_f32_e32 v135, v135, v217
	s_waitcnt lgkmcnt(1)
	v_add_f32_e32 v136, v136, v218
	s_waitcnt lgkmcnt(0)
	v_add_f32_e32 v137, v137, v219
	ds_bpermute_b32 v220, v168, v138
	ds_bpermute_b32 v221, v168, v139
	ds_bpermute_b32 v222, v168, v140
	ds_bpermute_b32 v223, v168, v141
	ds_bpermute_b32 v224, v168, v142
	ds_bpermute_b32 v225, v168, v143
	ds_bpermute_b32 v226, v168, v144
	ds_bpermute_b32 v227, v168, v145
	s_waitcnt lgkmcnt(7)
	v_add_f32_e32 v138, v138, v220
	s_waitcnt lgkmcnt(6)
	v_add_f32_e32 v139, v139, v221
	s_waitcnt lgkmcnt(5)
	v_add_f32_e32 v140, v140, v222
	s_waitcnt lgkmcnt(4)
	v_add_f32_e32 v141, v141, v223
	s_waitcnt lgkmcnt(3)
	v_add_f32_e32 v142, v142, v224
	s_waitcnt lgkmcnt(2)
	v_add_f32_e32 v143, v143, v225
	s_waitcnt lgkmcnt(1)
	v_add_f32_e32 v144, v144, v226
	s_waitcnt lgkmcnt(0)
	v_add_f32_e32 v145, v145, v227
	ds_bpermute_b32 v220, v169, v138
	ds_bpermute_b32 v221, v169, v139
	ds_bpermute_b32 v222, v169, v140
	ds_bpermute_b32 v223, v169, v141
	ds_bpermute_b32 v224, v169, v142
	ds_bpermute_b32 v225, v169, v143
	ds_bpermute_b32 v226, v169, v144
	ds_bpermute_b32 v227, v169, v145
	s_waitcnt lgkmcnt(7)
	v_add_f32_e32 v138, v138, v220
	s_waitcnt lgkmcnt(6)
	v_add_f32_e32 v139, v139, v221
	s_waitcnt lgkmcnt(5)
	v_add_f32_e32 v140, v140, v222
	s_waitcnt lgkmcnt(4)
	v_add_f32_e32 v141, v141, v223
	s_waitcnt lgkmcnt(3)
	v_add_f32_e32 v142, v142, v224
	s_waitcnt lgkmcnt(2)
	v_add_f32_e32 v143, v143, v225
	s_waitcnt lgkmcnt(1)
	v_add_f32_e32 v144, v144, v226
	s_waitcnt lgkmcnt(0)
	v_add_f32_e32 v145, v145, v227
	ds_bpermute_b32 v220, v171, v138
	ds_bpermute_b32 v221, v171, v139
	ds_bpermute_b32 v222, v171, v140
	ds_bpermute_b32 v223, v171, v141
	ds_bpermute_b32 v224, v171, v142
	ds_bpermute_b32 v225, v171, v143
	ds_bpermute_b32 v226, v171, v144
	ds_bpermute_b32 v227, v171, v145
	s_waitcnt lgkmcnt(7)
	v_add_f32_e32 v138, v138, v220
	s_waitcnt lgkmcnt(6)
	v_add_f32_e32 v139, v139, v221
	s_waitcnt lgkmcnt(5)
	v_add_f32_e32 v140, v140, v222
	s_waitcnt lgkmcnt(4)
	v_add_f32_e32 v141, v141, v223
	s_waitcnt lgkmcnt(3)
	v_add_f32_e32 v142, v142, v224
	s_waitcnt lgkmcnt(2)
	v_add_f32_e32 v143, v143, v225
	s_waitcnt lgkmcnt(1)
	v_add_f32_e32 v144, v144, v226
	s_waitcnt lgkmcnt(0)
	v_add_f32_e32 v145, v145, v227
	ds_bpermute_b32 v220, v172, v138
	ds_bpermute_b32 v221, v172, v139
	ds_bpermute_b32 v222, v172, v140
	ds_bpermute_b32 v223, v172, v141
	ds_bpermute_b32 v224, v172, v142
	ds_bpermute_b32 v225, v172, v143
	ds_bpermute_b32 v226, v172, v144
	ds_bpermute_b32 v227, v172, v145
	s_waitcnt lgkmcnt(7)
	v_add_f32_e32 v138, v138, v220
	s_waitcnt lgkmcnt(6)
	v_add_f32_e32 v139, v139, v221
	s_waitcnt lgkmcnt(5)
	v_add_f32_e32 v140, v140, v222
	s_waitcnt lgkmcnt(4)
	v_add_f32_e32 v141, v141, v223
	s_waitcnt lgkmcnt(3)
	v_add_f32_e32 v142, v142, v224
	s_waitcnt lgkmcnt(2)
	v_add_f32_e32 v143, v143, v225
	s_waitcnt lgkmcnt(1)
	v_add_f32_e32 v144, v144, v226
	s_waitcnt lgkmcnt(0)
	v_add_f32_e32 v145, v145, v227
	ds_bpermute_b32 v220, v173, v138
	ds_bpermute_b32 v221, v173, v139
	ds_bpermute_b32 v222, v173, v140
	ds_bpermute_b32 v223, v173, v141
	ds_bpermute_b32 v224, v173, v142
	ds_bpermute_b32 v225, v173, v143
	ds_bpermute_b32 v226, v173, v144
	ds_bpermute_b32 v227, v173, v145
	s_waitcnt lgkmcnt(7)
	v_add_f32_e32 v138, v138, v220
	s_waitcnt lgkmcnt(6)
	v_add_f32_e32 v139, v139, v221
	s_waitcnt lgkmcnt(5)
	v_add_f32_e32 v140, v140, v222
	s_waitcnt lgkmcnt(4)
	v_add_f32_e32 v141, v141, v223
	s_waitcnt lgkmcnt(3)
	v_add_f32_e32 v142, v142, v224
	s_waitcnt lgkmcnt(2)
	v_add_f32_e32 v143, v143, v225
	s_waitcnt lgkmcnt(1)
	v_add_f32_e32 v144, v144, v226
	s_waitcnt lgkmcnt(0)
	v_add_f32_e32 v145, v145, v227
	v_cmp_eq_u32_e32 vcc, 0, v174
	s_and_saveexec_b64 s[58:59], vcc
	global_store_dword v167, v130, s[10:11] offset:128
	global_store_dword v167, v131, s[10:11] offset:132
	global_store_dword v167, v132, s[10:11] offset:136
	global_store_dword v167, v133, s[10:11] offset:140
	global_store_dword v167, v134, s[10:11] offset:160
	global_store_dword v167, v135, s[10:11] offset:164
	global_store_dword v167, v136, s[10:11] offset:168
	global_store_dword v167, v137, s[10:11] offset:172
	global_store_dword v167, v138, s[10:11] offset:192
	global_store_dword v167, v139, s[10:11] offset:196
	global_store_dword v167, v140, s[10:11] offset:200
	global_store_dword v167, v141, s[10:11] offset:204
	global_store_dword v167, v142, s[10:11] offset:224
	global_store_dword v167, v143, s[10:11] offset:228
	global_store_dword v167, v144, s[10:11] offset:232
	global_store_dword v167, v145, s[10:11] offset:236
	s_mov_b64 exec, -1
	s_sub_u32 s48, s48, 0x20000
	s_subb_u32 s49, s49, 0
	v_readlane_b32 s2, v246, 14
	s_nop 0
	s_add_i32 s16, s16, s2
	s_branch .Lhw_outproj_tloop

.Lhw_ffndown_tloop:
	s_cmpk_gt_u32 s16, 47
	s_cbranch_scc1 .Lhw_ffndown_exit
	v_readlane_b32 s6, v246, 16
	s_lshr_b32 s2, s16, 2
	s_and_b32 s15, s16, 3
	s_add_i32 s6, s6, s2
	s_lshl_b32 s6, s6, 7
	s_lshl_b32 s15, s15, 8
	s_mul_i32 vcc_lo, s6, 0x1600
	s_add_u32 s66, s42, vcc_lo
	s_addc_u32 s67, s43, 0
	s_mul_i32 vcc_lo, s15, 0x1600
	s_add_u32 s62, s46, vcc_lo
	s_addc_u32 s63, s47, 0
	s_add_u32 s18, s62, 0xb0000
	s_addc_u32 s19, s63, 0
	s_barrier
	s_sub_u32 s66, s66, 64
	s_subb_u32 s67, s67, 0
	s_sub_u32 s62, s62, 64
	s_subb_u32 s63, s63, 0
	s_sub_u32 s18, s18, 64
	s_subb_u32 s19, s19, 0
	s_add_u32 m0, s65, 0x0
	s_nop 0
	global_load_lds_dwordx4 v242, s[66:67]
	s_add_u32 m0, s65, 0x1000
	s_nop 0
	global_load_lds_dwordx4 v243, s[66:67]
	s_add_u32 m0, s65, 0x2000
	s_nop 0
	global_load_lds_dwordx4 v242, s[62:63]
	s_add_u32 m0, s65, 0x3000
	s_nop 0
	global_load_lds_dwordx4 v243, s[62:63]
	s_add_u32 m0, s65, 0x4000
	s_nop 0
	global_load_lds_dwordx4 v242, s[18:19]
	s_add_u32 m0, s65, 0x5000
	s_nop 0
	global_load_lds_dwordx4 v243, s[18:19]
	s_add_u32 s66, s66, 64
	s_addc_u32 s67, s67, 0
	s_add_u32 s62, s62, 64
	s_addc_u32 s63, s63, 0
	s_add_u32 s18, s18, 64
	s_addc_u32 s19, s19, 0
	s_add_u32 m0, s65, 0x6000
	s_nop 0
	global_load_lds_dwordx4 v160, s[66:67]
	s_add_u32 m0, s65, 0x7000
	s_nop 0
	global_load_lds_dwordx4 v161, s[66:67]
	s_add_u32 m0, s65, 0x8000
	s_nop 0
	global_load_lds_dwordx4 v160, s[62:63]
	s_add_u32 m0, s65, 0x9000
	s_nop 0
	global_load_lds_dwordx4 v161, s[62:63]
	s_add_u32 m0, s65, 0xa000
	s_nop 0
	global_load_lds_dwordx4 v160, s[18:19]
	s_add_u32 m0, s65, 0xb000
	s_nop 0
	global_load_lds_dwordx4 v161, s[18:19]
	s_add_u32 s66, s66, 64
	s_addc_u32 s67, s67, 0
	s_add_u32 s62, s62, 64
	s_addc_u32 s63, s63, 0
	s_add_u32 s18, s18, 64
	s_addc_u32 s19, s19, 0
	s_add_u32 m0, s65, 0xc000
	s_nop 0
	global_load_lds_dwordx4 v242, s[66:67]
	s_add_u32 m0, s65, 0xd000
	s_nop 0
	global_load_lds_dwordx4 v243, s[66:67]
	s_add_u32 m0, s65, 0xe000
	s_nop 0
	global_load_lds_dwordx4 v242, s[62:63]
	s_add_u32 m0, s65, 0xf000
	s_nop 0
	global_load_lds_dwordx4 v243, s[62:63]
	s_add_u32 m0, s65, 0x10000
	s_nop 0
	global_load_lds_dwordx4 v242, s[18:19]
	s_add_u32 m0, s65, 0x11000
	s_nop 0
	global_load_lds_dwordx4 v243, s[18:19]
	s_add_u32 s66, s66, 64
	s_addc_u32 s67, s67, 0
	s_add_u32 s62, s62, 64
	s_addc_u32 s63, s63, 0
	s_add_u32 s18, s18, 64
	s_addc_u32 s19, s19, 0
	v_mov_b32_e32 v2, 0
	v_mov_b32_e32 v3, 0
	v_mov_b32_e32 v4, 0
	v_mov_b32_e32 v5, 0
	v_mov_b32_e32 v6, 0
	v_mov_b32_e32 v7, 0
	v_mov_b32_e32 v8, 0
	v_mov_b32_e32 v9, 0
	v_mov_b32_e32 v10, 0
	v_mov_b32_e32 v11, 0
	v_mov_b32_e32 v12, 0
	v_mov_b32_e32 v13, 0
	v_mov_b32_e32 v14, 0
	v_mov_b32_e32 v15, 0
	v_mov_b32_e32 v16, 0
	v_mov_b32_e32 v17, 0
	v_mov_b32_e32 v18, 0
	v_mov_b32_e32 v19, 0
	v_mov_b32_e32 v20, 0
	v_mov_b32_e32 v21, 0
	v_mov_b32_e32 v22, 0
	v_mov_b32_e32 v23, 0
	v_mov_b32_e32 v24, 0
	v_mov_b32_e32 v25, 0
	v_mov_b32_e32 v26, 0
	v_mov_b32_e32 v27, 0
	v_mov_b32_e32 v28, 0
	v_mov_b32_e32 v29, 0
	v_mov_b32_e32 v30, 0
	v_mov_b32_e32 v31, 0
	v_mov_b32_e32 v32, 0
	v_mov_b32_e32 v33, 0
	v_mov_b32_e32 v34, 0
	v_mov_b32_e32 v35, 0
	v_mov_b32_e32 v36, 0
	v_mov_b32_e32 v37, 0
	v_mov_b32_e32 v38, 0
	v_mov_b32_e32 v39, 0
	v_mov_b32_e32 v40, 0
	v_mov_b32_e32 v41, 0
	v_mov_b32_e32 v42, 0
	v_mov_b32_e32 v43, 0
	v_mov_b32_e32 v44, 0
	v_mov_b32_e32 v45, 0
	v_mov_b32_e32 v46, 0
	v_mov_b32_e32 v47, 0
	v_mov_b32_e32 v48, 0
	v_mov_b32_e32 v49, 0
	v_mov_b32_e32 v50, 0
	v_mov_b32_e32 v51, 0
	v_mov_b32_e32 v52, 0
	v_mov_b32_e32 v53, 0
	v_mov_b32_e32 v54, 0
	v_mov_b32_e32 v55, 0
	v_mov_b32_e32 v56, 0
	v_mov_b32_e32 v57, 0
	v_mov_b32_e32 v58, 0
	v_mov_b32_e32 v59, 0
	v_mov_b32_e32 v60, 0
	v_mov_b32_e32 v61, 0
	v_mov_b32_e32 v62, 0
	v_mov_b32_e32 v63, 0
	v_mov_b32_e32 v64, 0
	v_mov_b32_e32 v65, 0
	v_mov_b32_e32 v66, 0
	v_mov_b32_e32 v67, 0
	v_mov_b32_e32 v68, 0
	v_mov_b32_e32 v69, 0
	v_mov_b32_e32 v70, 0
	v_mov_b32_e32 v71, 0
	v_mov_b32_e32 v72, 0
	v_mov_b32_e32 v73, 0
	v_mov_b32_e32 v74, 0
	v_mov_b32_e32 v75, 0
	v_mov_b32_e32 v76, 0
	v_mov_b32_e32 v77, 0
	v_mov_b32_e32 v78, 0
	v_mov_b32_e32 v79, 0
	v_mov_b32_e32 v80, 0
	v_mov_b32_e32 v81, 0
	v_mov_b32_e32 v82, 0
	v_mov_b32_e32 v83, 0
	v_mov_b32_e32 v84, 0
	v_mov_b32_e32 v85, 0
	v_mov_b32_e32 v86, 0
	v_mov_b32_e32 v87, 0
	v_mov_b32_e32 v88, 0
	v_mov_b32_e32 v89, 0
	v_mov_b32_e32 v90, 0
	v_mov_b32_e32 v91, 0
	v_mov_b32_e32 v92, 0
	v_mov_b32_e32 v93, 0
	v_mov_b32_e32 v94, 0
	v_mov_b32_e32 v95, 0
	v_mov_b32_e32 v96, 0
	v_mov_b32_e32 v97, 0
	v_mov_b32_e32 v98, 0
	v_mov_b32_e32 v99, 0
	v_mov_b32_e32 v100, 0
	v_mov_b32_e32 v101, 0
	v_mov_b32_e32 v102, 0
	v_mov_b32_e32 v103, 0
	v_mov_b32_e32 v104, 0
	v_mov_b32_e32 v105, 0
	v_mov_b32_e32 v106, 0
	v_mov_b32_e32 v107, 0
	v_mov_b32_e32 v108, 0
	v_mov_b32_e32 v109, 0
	v_mov_b32_e32 v110, 0
	v_mov_b32_e32 v111, 0
	v_mov_b32_e32 v112, 0
	v_mov_b32_e32 v113, 0
	v_mov_b32_e32 v114, 0
	v_mov_b32_e32 v115, 0
	v_mov_b32_e32 v116, 0
	v_mov_b32_e32 v117, 0
	v_mov_b32_e32 v118, 0
	v_mov_b32_e32 v119, 0
	v_mov_b32_e32 v120, 0
	v_mov_b32_e32 v121, 0
	v_mov_b32_e32 v122, 0
	v_mov_b32_e32 v123, 0
	v_mov_b32_e32 v124, 0
	v_mov_b32_e32 v125, 0
	v_mov_b32_e32 v126, 0
	v_mov_b32_e32 v127, 0
	v_mov_b32_e32 v128, 0
	v_mov_b32_e32 v129, 0
	s_waitcnt vmcnt(6)
	s_barrier
	ds_read_b128 v[130:133], v154 offset:24592
	ds_read_b128 v[138:141], v158 offset:32784
	ds_read_b128 v[146:149], v238 offset:24592
	ds_read_b128 v[134:137], v155 offset:16
	ds_read_b128 v[142:145], v159 offset:8208
	ds_read_b128 v[150:153], v239 offset:16
	s_mov_b32 s59, 14
.Lhw_ffndown_loop:
	s_waitcnt lgkmcnt(4)
	v_mfma_f32_32x32x16_bf16 v[2:17], v[130:133], v[138:141], v[2:17]
	ds_read_b128 v[212:215], v156 offset:24592
	s_waitcnt lgkmcnt(2)
	v_mfma_f32_32x32x16_bf16 v[18:33], v[130:133], v[142:145], v[18:33]
	ds_read_b128 v[220:223], v236 offset:32784
	v_mfma_f32_32x32x16_bf16 v[34:49], v[134:137], v[138:141], v[34:49]
	ds_read_b128 v[228:231], v240 offset:24592
	v_mfma_f32_32x32x16_bf16 v[50:65], v[134:137], v[142:145], v[50:65]
	ds_read_b128 v[216:219], v157 offset:16
	v_mfma_f32_32x32x16_bf16 v[66:81], v[130:133], v[146:149], v[66:81]
	ds_read_b128 v[224:227], v237 offset:8208
	s_waitcnt lgkmcnt(5)
	v_mfma_f32_32x32x16_bf16 v[82:97], v[130:133], v[150:153], v[82:97]
	ds_read_b128 v[232:235], v241 offset:16
	v_mfma_f32_32x32x16_bf16 v[98:113], v[134:137], v[146:149], v[98:113]
	v_mfma_f32_32x32x16_bf16 v[114:129], v[134:137], v[150:153], v[114:129]
	s_waitcnt vmcnt(0) lgkmcnt(0)
	s_barrier
	v_mfma_f32_32x32x16_bf16 v[2:17], v[212:215], v[220:223], v[2:17]
	s_add_u32 m0, s65, 0x0
	ds_read_b128 v[130:133], v155 offset:24592
	global_load_lds_dwordx4 v160, s[66:67]
	v_mfma_f32_32x32x16_bf16 v[18:33], v[212:215], v[224:227], v[18:33]
	s_add_u32 m0, s65, 0x1000
	ds_read_b128 v[138:141], v159 offset:32784
	global_load_lds_dwordx4 v161, s[66:67]
	v_mfma_f32_32x32x16_bf16 v[34:49], v[216:219], v[220:223], v[34:49]
	s_add_u32 m0, s65, 0x2000
	ds_read_b128 v[146:149], v239 offset:24592
	global_load_lds_dwordx4 v160, s[62:63]
	v_mfma_f32_32x32x16_bf16 v[50:65], v[216:219], v[224:227], v[50:65]
	s_add_u32 m0, s65, 0x3000
	ds_read_b128 v[134:137], v154 offset:49168
	global_load_lds_dwordx4 v161, s[62:63]
	v_mfma_f32_32x32x16_bf16 v[66:81], v[212:215], v[228:231], v[66:81]
	s_add_u32 m0, s65, 0x4000
	ds_read_b128 v[142:145], v158 offset:57360
	global_load_lds_dwordx4 v160, s[18:19]
	v_mfma_f32_32x32x16_bf16 v[82:97], v[212:215], v[232:235], v[82:97]
	s_add_u32 m0, s65, 0x5000
	ds_read_b128 v[150:153], v238 offset:49168
	global_load_lds_dwordx4 v161, s[18:19]
	v_mfma_f32_32x32x16_bf16 v[98:113], v[216:219], v[228:231], v[98:113]
	s_add_u32 s66, s66, 64
	s_addc_u32 s67, s67, 0
	s_add_u32 s62, s62, 64
	s_addc_u32 s63, s63, 0
	v_mfma_f32_32x32x16_bf16 v[114:129], v[216:219], v[232:235], v[114:129]
	s_add_u32 s18, s18, 64
	s_addc_u32 s19, s19, 0
	s_waitcnt lgkmcnt(4)
	v_mfma_f32_32x32x16_bf16 v[2:17], v[130:133], v[138:141], v[2:17]
	ds_read_b128 v[212:215], v157 offset:24592
	s_waitcnt lgkmcnt(2)
	v_mfma_f32_32x32x16_bf16 v[18:33], v[130:133], v[142:145], v[18:33]
	ds_read_b128 v[220:223], v237 offset:32784
	v_mfma_f32_32x32x16_bf16 v[34:49], v[134:137], v[138:141], v[34:49]
	ds_read_b128 v[228:231], v241 offset:24592
	v_mfma_f32_32x32x16_bf16 v[50:65], v[134:137], v[142:145], v[50:65]
	ds_read_b128 v[216:219], v156 offset:49168
	v_mfma_f32_32x32x16_bf16 v[66:81], v[130:133], v[146:149], v[66:81]
	ds_read_b128 v[224:227], v236 offset:57360
	s_waitcnt lgkmcnt(5)
	v_mfma_f32_32x32x16_bf16 v[82:97], v[130:133], v[150:153], v[82:97]
	ds_read_b128 v[232:235], v240 offset:49168
	v_mfma_f32_32x32x16_bf16 v[98:113], v[134:137], v[146:149], v[98:113]
	v_mfma_f32_32x32x16_bf16 v[114:129], v[134:137], v[150:153], v[114:129]
	s_waitcnt vmcnt(0) lgkmcnt(0)
	s_barrier
	v_mfma_f32_32x32x16_bf16 v[2:17], v[212:215], v[220:223], v[2:17]
	s_add_u32 m0, s65, 0x6000
	ds_read_b128 v[130:133], v154 offset:16
	global_load_lds_dwordx4 v242, s[66:67]
	v_mfma_f32_32x32x16_bf16 v[18:33], v[212:215], v[224:227], v[18:33]
	s_add_u32 m0, s65, 0x7000
	ds_read_b128 v[138:141], v158 offset:8208
	global_load_lds_dwordx4 v243, s[66:67]
	v_mfma_f32_32x32x16_bf16 v[34:49], v[216:219], v[220:223], v[34:49]
	s_add_u32 m0, s65, 0x8000
	ds_read_b128 v[146:149], v238 offset:16
	global_load_lds_dwordx4 v242, s[62:63]
	v_mfma_f32_32x32x16_bf16 v[50:65], v[216:219], v[224:227], v[50:65]
	s_add_u32 m0, s65, 0x9000
	ds_read_b128 v[134:137], v155 offset:49168
	global_load_lds_dwordx4 v243, s[62:63]
	v_mfma_f32_32x32x16_bf16 v[66:81], v[212:215], v[228:231], v[66:81]
	s_add_u32 m0, s65, 0xa000
	ds_read_b128 v[142:145], v159 offset:57360
	global_load_lds_dwordx4 v242, s[18:19]
	v_mfma_f32_32x32x16_bf16 v[82:97], v[212:215], v[232:235], v[82:97]
	s_add_u32 m0, s65, 0xb000
	ds_read_b128 v[150:153], v239 offset:49168
	global_load_lds_dwordx4 v243, s[18:19]
	v_mfma_f32_32x32x16_bf16 v[98:113], v[216:219], v[228:231], v[98:113]
	s_add_u32 s66, s66, 64
	s_addc_u32 s67, s67, 0
	s_add_u32 s62, s62, 64
	s_addc_u32 s63, s63, 0
	v_mfma_f32_32x32x16_bf16 v[114:129], v[216:219], v[232:235], v[114:129]
	s_add_u32 s18, s18, 64
	s_addc_u32 s19, s19, 0
	s_waitcnt lgkmcnt(4)
	v_mfma_f32_32x32x16_bf16 v[2:17], v[130:133], v[138:141], v[2:17]
	ds_read_b128 v[212:215], v156 offset:16
	s_waitcnt lgkmcnt(2)
	v_mfma_f32_32x32x16_bf16 v[18:33], v[130:133], v[142:145], v[18:33]
	ds_read_b128 v[220:223], v236 offset:8208
	v_mfma_f32_32x32x16_bf16 v[34:49], v[134:137], v[138:141], v[34:49]
	ds_read_b128 v[228:231], v240 offset:16
	v_mfma_f32_32x32x16_bf16 v[50:65], v[134:137], v[142:145], v[50:65]
	ds_read_b128 v[216:219], v157 offset:49168
	v_mfma_f32_32x32x16_bf16 v[66:81], v[130:133], v[146:149], v[66:81]
	ds_read_b128 v[224:227], v237 offset:57360
	s_waitcnt lgkmcnt(5)
	v_mfma_f32_32x32x16_bf16 v[82:97], v[130:133], v[150:153], v[82:97]
	ds_read_b128 v[232:235], v241 offset:49168
	v_mfma_f32_32x32x16_bf16 v[98:113], v[134:137], v[146:149], v[98:113]
	v_mfma_f32_32x32x16_bf16 v[114:129], v[134:137], v[150:153], v[114:129]
	s_waitcnt vmcnt(0) lgkmcnt(0)
	s_barrier
	v_mfma_f32_32x32x16_bf16 v[2:17], v[212:215], v[220:223], v[2:17]
	s_add_u32 m0, s65, 0xc000
	ds_read_b128 v[130:133], v155 offset:16
	global_load_lds_dwordx4 v160, s[66:67]
	v_mfma_f32_32x32x16_bf16 v[18:33], v[212:215], v[224:227], v[18:33]
	s_add_u32 m0, s65, 0xd000
	ds_read_b128 v[138:141], v159 offset:8208
	global_load_lds_dwordx4 v161, s[66:67]
	v_mfma_f32_32x32x16_bf16 v[34:49], v[216:219], v[220:223], v[34:49]
	s_add_u32 m0, s65, 0xe000
	ds_read_b128 v[146:149], v239 offset:16
	global_load_lds_dwordx4 v160, s[62:63]
	v_mfma_f32_32x32x16_bf16 v[50:65], v[216:219], v[224:227], v[50:65]
	s_add_u32 m0, s65, 0xf000
	ds_read_b128 v[134:137], v154 offset:24592
	global_load_lds_dwordx4 v161, s[62:63]
	v_mfma_f32_32x32x16_bf16 v[66:81], v[212:215], v[228:231], v[66:81]
	s_add_u32 m0, s65, 0x10000
	ds_read_b128 v[142:145], v158 offset:32784
	global_load_lds_dwordx4 v160, s[18:19]
	v_mfma_f32_32x32x16_bf16 v[82:97], v[212:215], v[232:235], v[82:97]
	s_add_u32 m0, s65, 0x11000
	ds_read_b128 v[150:153], v238 offset:24592
	global_load_lds_dwordx4 v161, s[18:19]
	v_mfma_f32_32x32x16_bf16 v[98:113], v[216:219], v[228:231], v[98:113]
	s_add_u32 s66, s66, 64
	s_addc_u32 s67, s67, 0
	s_add_u32 s62, s62, 64
	s_addc_u32 s63, s63, 0
	v_mfma_f32_32x32x16_bf16 v[114:129], v[216:219], v[232:235], v[114:129]
	s_add_u32 s18, s18, 64
	s_addc_u32 s19, s19, 0
	s_waitcnt lgkmcnt(4)
	v_mfma_f32_32x32x16_bf16 v[2:17], v[130:133], v[138:141], v[2:17]
	ds_read_b128 v[212:215], v157 offset:16
	s_waitcnt lgkmcnt(2)
	v_mfma_f32_32x32x16_bf16 v[18:33], v[130:133], v[142:145], v[18:33]
	ds_read_b128 v[220:223], v237 offset:8208
	v_mfma_f32_32x32x16_bf16 v[34:49], v[134:137], v[138:141], v[34:49]
	ds_read_b128 v[228:231], v241 offset:16
	v_mfma_f32_32x32x16_bf16 v[50:65], v[134:137], v[142:145], v[50:65]
	ds_read_b128 v[216:219], v156 offset:24592
	v_mfma_f32_32x32x16_bf16 v[66:81], v[130:133], v[146:149], v[66:81]
	ds_read_b128 v[224:227], v236 offset:32784
	s_waitcnt lgkmcnt(5)
	v_mfma_f32_32x32x16_bf16 v[82:97], v[130:133], v[150:153], v[82:97]
	ds_read_b128 v[232:235], v240 offset:24592
	v_mfma_f32_32x32x16_bf16 v[98:113], v[134:137], v[146:149], v[98:113]
	v_mfma_f32_32x32x16_bf16 v[114:129], v[134:137], v[150:153], v[114:129]
	s_waitcnt vmcnt(0) lgkmcnt(0)
	s_barrier
	v_mfma_f32_32x32x16_bf16 v[2:17], v[212:215], v[220:223], v[2:17]
	s_add_u32 m0, s65, 0x0
	ds_read_b128 v[130:133], v154 offset:49168
	global_load_lds_dwordx4 v242, s[66:67]
	v_mfma_f32_32x32x16_bf16 v[18:33], v[212:215], v[224:227], v[18:33]
	s_add_u32 m0, s65, 0x1000
	ds_read_b128 v[138:141], v158 offset:57360
	global_load_lds_dwordx4 v243, s[66:67]
	v_mfma_f32_32x32x16_bf16 v[34:49], v[216:219], v[220:223], v[34:49]
	s_add_u32 m0, s65, 0x2000
	ds_read_b128 v[146:149], v238 offset:49168
	global_load_lds_dwordx4 v242, s[62:63]
	v_mfma_f32_32x32x16_bf16 v[50:65], v[216:219], v[224:227], v[50:65]
	s_add_u32 m0, s65, 0x3000
	ds_read_b128 v[134:137], v155 offset:24592
	global_load_lds_dwordx4 v243, s[62:63]
	v_mfma_f32_32x32x16_bf16 v[66:81], v[212:215], v[228:231], v[66:81]
	s_add_u32 m0, s65, 0x4000
	ds_read_b128 v[142:145], v159 offset:32784
	global_load_lds_dwordx4 v242, s[18:19]
	v_mfma_f32_32x32x16_bf16 v[82:97], v[212:215], v[232:235], v[82:97]
	s_add_u32 m0, s65, 0x5000
	ds_read_b128 v[150:153], v239 offset:24592
	global_load_lds_dwordx4 v243, s[18:19]
	v_mfma_f32_32x32x16_bf16 v[98:113], v[216:219], v[228:231], v[98:113]
	s_add_u32 s66, s66, 64
	s_addc_u32 s67, s67, 0
	s_add_u32 s62, s62, 64
	s_addc_u32 s63, s63, 0
	v_mfma_f32_32x32x16_bf16 v[114:129], v[216:219], v[232:235], v[114:129]
	s_add_u32 s18, s18, 64
	s_addc_u32 s19, s19, 0
	s_waitcnt lgkmcnt(4)
	v_mfma_f32_32x32x16_bf16 v[2:17], v[130:133], v[138:141], v[2:17]
	ds_read_b128 v[212:215], v156 offset:49168
	s_waitcnt lgkmcnt(2)
	v_mfma_f32_32x32x16_bf16 v[18:33], v[130:133], v[142:145], v[18:33]
	ds_read_b128 v[220:223], v236 offset:57360
	v_mfma_f32_32x32x16_bf16 v[34:49], v[134:137], v[138:141], v[34:49]
	ds_read_b128 v[228:231], v240 offset:49168
	v_mfma_f32_32x32x16_bf16 v[50:65], v[134:137], v[142:145], v[50:65]
	ds_read_b128 v[216:219], v157 offset:24592
	v_mfma_f32_32x32x16_bf16 v[66:81], v[130:133], v[146:149], v[66:81]
	ds_read_b128 v[224:227], v237 offset:32784
	s_waitcnt lgkmcnt(5)
	v_mfma_f32_32x32x16_bf16 v[82:97], v[130:133], v[150:153], v[82:97]
	ds_read_b128 v[232:235], v241 offset:24592
	v_mfma_f32_32x32x16_bf16 v[98:113], v[134:137], v[146:149], v[98:113]
	v_mfma_f32_32x32x16_bf16 v[114:129], v[134:137], v[150:153], v[114:129]
	s_waitcnt vmcnt(0) lgkmcnt(0)
	s_barrier
	v_mfma_f32_32x32x16_bf16 v[2:17], v[212:215], v[220:223], v[2:17]
	s_add_u32 m0, s65, 0x6000
	ds_read_b128 v[130:133], v155 offset:49168
	global_load_lds_dwordx4 v160, s[66:67]
	v_mfma_f32_32x32x16_bf16 v[18:33], v[212:215], v[224:227], v[18:33]
	s_add_u32 m0, s65, 0x7000
	ds_read_b128 v[138:141], v159 offset:57360
	global_load_lds_dwordx4 v161, s[66:67]
	v_mfma_f32_32x32x16_bf16 v[34:49], v[216:219], v[220:223], v[34:49]
	s_add_u32 m0, s65, 0x8000
	ds_read_b128 v[146:149], v239 offset:49168
	global_load_lds_dwordx4 v160, s[62:63]
	v_mfma_f32_32x32x16_bf16 v[50:65], v[216:219], v[224:227], v[50:65]
	s_add_u32 m0, s65, 0x9000
	ds_read_b128 v[134:137], v154 offset:16
	global_load_lds_dwordx4 v161, s[62:63]
	v_mfma_f32_32x32x16_bf16 v[66:81], v[212:215], v[228:231], v[66:81]
	s_add_u32 m0, s65, 0xa000
	ds_read_b128 v[142:145], v158 offset:8208
	global_load_lds_dwordx4 v160, s[18:19]
	v_mfma_f32_32x32x16_bf16 v[82:97], v[212:215], v[232:235], v[82:97]
	s_add_u32 m0, s65, 0xb000
	ds_read_b128 v[150:153], v238 offset:16
	global_load_lds_dwordx4 v161, s[18:19]
	v_mfma_f32_32x32x16_bf16 v[98:113], v[216:219], v[228:231], v[98:113]
	s_add_u32 s66, s66, 64
	s_addc_u32 s67, s67, 0
	s_add_u32 s62, s62, 64
	s_addc_u32 s63, s63, 0
	v_mfma_f32_32x32x16_bf16 v[114:129], v[216:219], v[232:235], v[114:129]
	s_add_u32 s18, s18, 64
	s_addc_u32 s19, s19, 0
	s_waitcnt lgkmcnt(4)
	v_mfma_f32_32x32x16_bf16 v[2:17], v[130:133], v[138:141], v[2:17]
	ds_read_b128 v[212:215], v157 offset:49168
	s_waitcnt lgkmcnt(2)
	v_mfma_f32_32x32x16_bf16 v[18:33], v[130:133], v[142:145], v[18:33]
	ds_read_b128 v[220:223], v237 offset:57360
	v_mfma_f32_32x32x16_bf16 v[34:49], v[134:137], v[138:141], v[34:49]
	ds_read_b128 v[228:231], v241 offset:49168
	v_mfma_f32_32x32x16_bf16 v[50:65], v[134:137], v[142:145], v[50:65]
	ds_read_b128 v[216:219], v156 offset:16
	v_mfma_f32_32x32x16_bf16 v[66:81], v[130:133], v[146:149], v[66:81]
	ds_read_b128 v[224:227], v236 offset:8208
	s_waitcnt lgkmcnt(5)
	v_mfma_f32_32x32x16_bf16 v[82:97], v[130:133], v[150:153], v[82:97]
	ds_read_b128 v[232:235], v240 offset:16
	v_mfma_f32_32x32x16_bf16 v[98:113], v[134:137], v[146:149], v[98:113]
	v_mfma_f32_32x32x16_bf16 v[114:129], v[134:137], v[150:153], v[114:129]
	s_waitcnt vmcnt(0) lgkmcnt(0)
	s_barrier
	v_mfma_f32_32x32x16_bf16 v[2:17], v[212:215], v[220:223], v[2:17]
	s_add_u32 m0, s65, 0xc000
	ds_read_b128 v[130:133], v154 offset:24592
	global_load_lds_dwordx4 v242, s[66:67]
	v_mfma_f32_32x32x16_bf16 v[18:33], v[212:215], v[224:227], v[18:33]
	s_add_u32 m0, s65, 0xd000
	ds_read_b128 v[138:141], v158 offset:32784
	global_load_lds_dwordx4 v243, s[66:67]
	v_mfma_f32_32x32x16_bf16 v[34:49], v[216:219], v[220:223], v[34:49]
	s_add_u32 m0, s65, 0xe000
	ds_read_b128 v[146:149], v238 offset:24592
	global_load_lds_dwordx4 v242, s[62:63]
	v_mfma_f32_32x32x16_bf16 v[50:65], v[216:219], v[224:227], v[50:65]
	s_add_u32 m0, s65, 0xf000
	ds_read_b128 v[134:137], v155 offset:16
	global_load_lds_dwordx4 v243, s[62:63]
	v_mfma_f32_32x32x16_bf16 v[66:81], v[212:215], v[228:231], v[66:81]
	s_add_u32 m0, s65, 0x10000
	ds_read_b128 v[142:145], v159 offset:8208
	global_load_lds_dwordx4 v242, s[18:19]
	v_mfma_f32_32x32x16_bf16 v[82:97], v[212:215], v[232:235], v[82:97]
	s_add_u32 m0, s65, 0x11000
	ds_read_b128 v[150:153], v239 offset:16
	global_load_lds_dwordx4 v243, s[18:19]
	v_mfma_f32_32x32x16_bf16 v[98:113], v[216:219], v[228:231], v[98:113]
	s_add_u32 s66, s66, 64
	s_addc_u32 s67, s67, 0
	s_add_u32 s62, s62, 64
	s_addc_u32 s63, s63, 0
	v_mfma_f32_32x32x16_bf16 v[114:129], v[216:219], v[232:235], v[114:129]
	s_add_u32 s18, s18, 64
	s_addc_u32 s19, s19, 0
	s_sub_u32 s59, s59, 1
	s_cmp_lg_u32 s59, 0
	s_cbranch_scc1 .Lhw_ffndown_loop
	s_waitcnt lgkmcnt(4)
	v_mfma_f32_32x32x16_bf16 v[2:17], v[130:133], v[138:141], v[2:17]
	ds_read_b128 v[212:215], v156 offset:24592
	s_waitcnt lgkmcnt(2)
	v_mfma_f32_32x32x16_bf16 v[18:33], v[130:133], v[142:145], v[18:33]
	ds_read_b128 v[220:223], v236 offset:32784
	v_mfma_f32_32x32x16_bf16 v[34:49], v[134:137], v[138:141], v[34:49]
	ds_read_b128 v[228:231], v240 offset:24592
	v_mfma_f32_32x32x16_bf16 v[50:65], v[134:137], v[142:145], v[50:65]
	ds_read_b128 v[216:219], v157 offset:16
	v_mfma_f32_32x32x16_bf16 v[66:81], v[130:133], v[146:149], v[66:81]
	ds_read_b128 v[224:227], v237 offset:8208
	s_waitcnt lgkmcnt(5)
	v_mfma_f32_32x32x16_bf16 v[82:97], v[130:133], v[150:153], v[82:97]
	ds_read_b128 v[232:235], v241 offset:16
	v_mfma_f32_32x32x16_bf16 v[98:113], v[134:137], v[146:149], v[98:113]
	v_mfma_f32_32x32x16_bf16 v[114:129], v[134:137], v[150:153], v[114:129]
	s_waitcnt vmcnt(0) lgkmcnt(0)
	s_barrier
	v_mfma_f32_32x32x16_bf16 v[2:17], v[212:215], v[220:223], v[2:17]
	s_add_u32 m0, s65, 0x0
	ds_read_b128 v[130:133], v155 offset:24592
	global_load_lds_dwordx4 v160, s[66:67]
	v_mfma_f32_32x32x16_bf16 v[18:33], v[212:215], v[224:227], v[18:33]
	s_add_u32 m0, s65, 0x1000
	ds_read_b128 v[138:141], v159 offset:32784
	global_load_lds_dwordx4 v161, s[66:67]
	v_mfma_f32_32x32x16_bf16 v[34:49], v[216:219], v[220:223], v[34:49]
	s_add_u32 m0, s65, 0x2000
	ds_read_b128 v[146:149], v239 offset:24592
	global_load_lds_dwordx4 v160, s[62:63]
	v_mfma_f32_32x32x16_bf16 v[50:65], v[216:219], v[224:227], v[50:65]
	s_add_u32 m0, s65, 0x3000
	ds_read_b128 v[134:137], v154 offset:49168
	global_load_lds_dwordx4 v161, s[62:63]
	v_mfma_f32_32x32x16_bf16 v[66:81], v[212:215], v[228:231], v[66:81]
	s_add_u32 m0, s65, 0x4000
	ds_read_b128 v[142:145], v158 offset:57360
	global_load_lds_dwordx4 v160, s[18:19]
	v_mfma_f32_32x32x16_bf16 v[82:97], v[212:215], v[232:235], v[82:97]
	s_add_u32 m0, s65, 0x5000
	ds_read_b128 v[150:153], v238 offset:49168
	global_load_lds_dwordx4 v161, s[18:19]
	v_mfma_f32_32x32x16_bf16 v[98:113], v[216:219], v[228:231], v[98:113]
	s_add_u32 s66, s66, 64
	s_addc_u32 s67, s67, 0
	s_add_u32 s62, s62, 64
	s_addc_u32 s63, s63, 0
	v_mfma_f32_32x32x16_bf16 v[114:129], v[216:219], v[232:235], v[114:129]
	s_add_u32 s18, s18, 64
	s_addc_u32 s19, s19, 0
	s_waitcnt lgkmcnt(4)
	v_mfma_f32_32x32x16_bf16 v[2:17], v[130:133], v[138:141], v[2:17]
	ds_read_b128 v[212:215], v157 offset:24592
	s_waitcnt lgkmcnt(2)
	v_mfma_f32_32x32x16_bf16 v[18:33], v[130:133], v[142:145], v[18:33]
	ds_read_b128 v[220:223], v237 offset:32784
	v_mfma_f32_32x32x16_bf16 v[34:49], v[134:137], v[138:141], v[34:49]
	ds_read_b128 v[228:231], v241 offset:24592
	v_mfma_f32_32x32x16_bf16 v[50:65], v[134:137], v[142:145], v[50:65]
	ds_read_b128 v[216:219], v156 offset:49168
	v_mfma_f32_32x32x16_bf16 v[66:81], v[130:133], v[146:149], v[66:81]
	ds_read_b128 v[224:227], v236 offset:57360
	s_waitcnt lgkmcnt(5)
	v_mfma_f32_32x32x16_bf16 v[82:97], v[130:133], v[150:153], v[82:97]
	ds_read_b128 v[232:235], v240 offset:49168
	v_mfma_f32_32x32x16_bf16 v[98:113], v[134:137], v[146:149], v[98:113]
	v_mfma_f32_32x32x16_bf16 v[114:129], v[134:137], v[150:153], v[114:129]
	s_waitcnt vmcnt(0) lgkmcnt(0)
	s_barrier
	v_mfma_f32_32x32x16_bf16 v[2:17], v[212:215], v[220:223], v[2:17]
	s_add_u32 m0, s65, 0x6000
	ds_read_b128 v[130:133], v154 offset:16
	global_load_lds_dwordx4 v242, s[66:67]
	v_mfma_f32_32x32x16_bf16 v[18:33], v[212:215], v[224:227], v[18:33]
	s_add_u32 m0, s65, 0x7000
	ds_read_b128 v[138:141], v158 offset:8208
	global_load_lds_dwordx4 v243, s[66:67]
	v_mfma_f32_32x32x16_bf16 v[34:49], v[216:219], v[220:223], v[34:49]
	s_add_u32 m0, s65, 0x8000
	ds_read_b128 v[146:149], v238 offset:16
	global_load_lds_dwordx4 v242, s[62:63]
	v_mfma_f32_32x32x16_bf16 v[50:65], v[216:219], v[224:227], v[50:65]
	s_add_u32 m0, s65, 0x9000
	ds_read_b128 v[134:137], v155 offset:49168
	global_load_lds_dwordx4 v243, s[62:63]
	v_mfma_f32_32x32x16_bf16 v[66:81], v[212:215], v[228:231], v[66:81]
	s_add_u32 m0, s65, 0xa000
	ds_read_b128 v[142:145], v159 offset:57360
	global_load_lds_dwordx4 v242, s[18:19]
	v_mfma_f32_32x32x16_bf16 v[82:97], v[212:215], v[232:235], v[82:97]
	s_add_u32 m0, s65, 0xb000
	ds_read_b128 v[150:153], v239 offset:49168
	global_load_lds_dwordx4 v243, s[18:19]
	v_mfma_f32_32x32x16_bf16 v[98:113], v[216:219], v[228:231], v[98:113]
	s_add_u32 s66, s66, 64
	s_addc_u32 s67, s67, 0
	s_add_u32 s62, s62, 64
	s_addc_u32 s63, s63, 0
	v_mfma_f32_32x32x16_bf16 v[114:129], v[216:219], v[232:235], v[114:129]
	s_add_u32 s18, s18, 64
	s_addc_u32 s19, s19, 0
	s_waitcnt lgkmcnt(4)
	v_mfma_f32_32x32x16_bf16 v[2:17], v[130:133], v[138:141], v[2:17]
	ds_read_b128 v[212:215], v156 offset:16
	s_waitcnt lgkmcnt(2)
	v_mfma_f32_32x32x16_bf16 v[18:33], v[130:133], v[142:145], v[18:33]
	ds_read_b128 v[220:223], v236 offset:8208
	v_mfma_f32_32x32x16_bf16 v[34:49], v[134:137], v[138:141], v[34:49]
	ds_read_b128 v[228:231], v240 offset:16
	v_mfma_f32_32x32x16_bf16 v[50:65], v[134:137], v[142:145], v[50:65]
	ds_read_b128 v[216:219], v157 offset:49168
	v_mfma_f32_32x32x16_bf16 v[66:81], v[130:133], v[146:149], v[66:81]
	ds_read_b128 v[224:227], v237 offset:57360
	s_waitcnt lgkmcnt(5)
	v_mfma_f32_32x32x16_bf16 v[82:97], v[130:133], v[150:153], v[82:97]
	ds_read_b128 v[232:235], v241 offset:49168
	v_mfma_f32_32x32x16_bf16 v[98:113], v[134:137], v[146:149], v[98:113]
	v_mfma_f32_32x32x16_bf16 v[114:129], v[134:137], v[150:153], v[114:129]
	s_waitcnt vmcnt(0) lgkmcnt(0)
	s_barrier
	v_mfma_f32_32x32x16_bf16 v[2:17], v[212:215], v[220:223], v[2:17]
	ds_read_b128 v[130:133], v155 offset:16
	v_mfma_f32_32x32x16_bf16 v[18:33], v[212:215], v[224:227], v[18:33]
	ds_read_b128 v[138:141], v159 offset:8208
	v_mfma_f32_32x32x16_bf16 v[34:49], v[216:219], v[220:223], v[34:49]
	ds_read_b128 v[146:149], v239 offset:16
	v_mfma_f32_32x32x16_bf16 v[50:65], v[216:219], v[224:227], v[50:65]
	ds_read_b128 v[134:137], v154 offset:24592
	v_mfma_f32_32x32x16_bf16 v[66:81], v[212:215], v[228:231], v[66:81]
	ds_read_b128 v[142:145], v158 offset:32784
	v_mfma_f32_32x32x16_bf16 v[82:97], v[212:215], v[232:235], v[82:97]
	ds_read_b128 v[150:153], v238 offset:24592
	v_mfma_f32_32x32x16_bf16 v[98:113], v[216:219], v[228:231], v[98:113]
	v_mfma_f32_32x32x16_bf16 v[114:129], v[216:219], v[232:235], v[114:129]
	s_waitcnt lgkmcnt(4)
	v_mfma_f32_32x32x16_bf16 v[2:17], v[130:133], v[138:141], v[2:17]
	ds_read_b128 v[212:215], v157 offset:16
	s_waitcnt lgkmcnt(2)
	v_mfma_f32_32x32x16_bf16 v[18:33], v[130:133], v[142:145], v[18:33]
	ds_read_b128 v[220:223], v237 offset:8208
	v_mfma_f32_32x32x16_bf16 v[34:49], v[134:137], v[138:141], v[34:49]
	ds_read_b128 v[228:231], v241 offset:16
	v_mfma_f32_32x32x16_bf16 v[50:65], v[134:137], v[142:145], v[50:65]
	ds_read_b128 v[216:219], v156 offset:24592
	v_mfma_f32_32x32x16_bf16 v[66:81], v[130:133], v[146:149], v[66:81]
	ds_read_b128 v[224:227], v236 offset:32784
	s_waitcnt lgkmcnt(5)
	v_mfma_f32_32x32x16_bf16 v[82:97], v[130:133], v[150:153], v[82:97]
	ds_read_b128 v[232:235], v240 offset:24592
	v_mfma_f32_32x32x16_bf16 v[98:113], v[134:137], v[146:149], v[98:113]
	v_mfma_f32_32x32x16_bf16 v[114:129], v[134:137], v[150:153], v[114:129]
	s_waitcnt lgkmcnt(0)
	v_mfma_f32_32x32x16_bf16 v[2:17], v[212:215], v[220:223], v[2:17]
	v_mfma_f32_32x32x16_bf16 v[18:33], v[212:215], v[224:227], v[18:33]
	v_mfma_f32_32x32x16_bf16 v[34:49], v[216:219], v[220:223], v[34:49]
	v_mfma_f32_32x32x16_bf16 v[50:65], v[216:219], v[224:227], v[50:65]
	v_mfma_f32_32x32x16_bf16 v[66:81], v[212:215], v[228:231], v[66:81]
	v_mfma_f32_32x32x16_bf16 v[82:97], v[212:215], v[232:235], v[82:97]
	v_mfma_f32_32x32x16_bf16 v[98:113], v[216:219], v[228:231], v[98:113]
	v_mfma_f32_32x32x16_bf16 v[114:129], v[216:219], v[232:235], v[114:129]
	s_nop 7
	s_nop 7
	s_sub_i32 s2, s6, 0x1000
	s_ashr_i32 s2, s2, 11
	s_add_i32 s2, s2, 1
	s_max_i32 s2, s2, 0
	v_readlane_b32 s17, v246, 28
	s_nop 0
	s_add_i32 s2, s2, s17
	s_mul_i32 s2, s2, 0x9000
	s_lshl_b32 s17, s15, 2
	s_add_u32 s2, s2, s17
	s_add_u32 s60, s12, s2
	s_addc_u32 s61, s13, 0
	s_lshr_b32 s2, s15, 7
	s_mul_i32 s2, s2, 0x18000
	s_lshl_b32 s20, s6, 2
	s_add_u32 s2, s2, s20
	s_add_u32 s10, s44, s2
	s_addc_u32 s11, s45, 0
	s_lshl_b32 s2, s6, 12
	s_add_u32 s2, s2, s17
	s_add_u32 s48, s40, s2
	s_addc_u32 s49, s41, 0
	global_load_dword v175, v166, s[60:61]
	global_load_dword v176, v166, s[60:61] offset:128
	global_load_dword v130, v162, s[48:49]
	global_load_dword v212, v162, s[48:49] offset:128
	global_load_dword v131, v163, s[48:49]
	global_load_dword v213, v163, s[48:49] offset:128
	global_load_dword v132, v164, s[48:49]
	global_load_dword v214, v164, s[48:49] offset:128
	global_load_dword v133, v165, s[48:49]
	global_load_dword v215, v165, s[48:49] offset:128
	s_add_u32 s48, s48, 0x8000
	s_addc_u32 s49, s49, 0
	global_load_dword v134, v162, s[48:49]
	global_load_dword v216, v162, s[48:49] offset:128
	global_load_dword v135, v163, s[48:49]
	global_load_dword v217, v163, s[48:49] offset:128
	global_load_dword v136, v164, s[48:49]
	global_load_dword v218, v164, s[48:49] offset:128
	global_load_dword v137, v165, s[48:49]
	global_load_dword v219, v165, s[48:49] offset:128
	s_add_u32 s48, s48, 0x8000
	s_addc_u32 s49, s49, 0
	global_load_dword v138, v162, s[48:49]
	global_load_dword v220, v162, s[48:49] offset:128
	global_load_dword v139, v163, s[48:49]
	global_load_dword v221, v163, s[48:49] offset:128
	global_load_dword v140, v164, s[48:49]
	global_load_dword v222, v164, s[48:49] offset:128
	global_load_dword v141, v165, s[48:49]
	global_load_dword v223, v165, s[48:49] offset:128
	s_add_u32 s48, s48, 0x8000
	s_addc_u32 s49, s49, 0
	global_load_dword v142, v162, s[48:49]
	global_load_dword v224, v162, s[48:49] offset:128
	global_load_dword v143, v163, s[48:49]
	global_load_dword v225, v163, s[48:49] offset:128
	global_load_dword v144, v164, s[48:49]
	global_load_dword v226, v164, s[48:49] offset:128
	global_load_dword v145, v165, s[48:49]
	global_load_dword v227, v165, s[48:49] offset:128
	s_sub_u32 s48, s48, 0x18000
	s_subb_u32 s49, s49, 0
	s_waitcnt vmcnt(32)
	v_mul_f32_e32 v175, 0.5, v175
	v_mul_f32_e32 v176, 0.5, v176
	s_waitcnt vmcnt(30)
	v_fmac_f32_e32 v130, v2, v175
	v_fmac_f32_e32 v212, v18, v176
	global_store_dword v162, v130, s[48:49]
	global_store_dword v162, v212, s[48:49] offset:128
	s_waitcnt vmcnt(30)
	v_fmac_f32_e32 v131, v3, v175
	v_fmac_f32_e32 v213, v19, v176
	global_store_dword v163, v131, s[48:49]
	global_store_dword v163, v213, s[48:49] offset:128
	s_waitcnt vmcnt(30)
	v_fmac_f32_e32 v132, v4, v175
	v_fmac_f32_e32 v214, v20, v176
	global_store_dword v164, v132, s[48:49]
	global_store_dword v164, v214, s[48:49] offset:128
	s_waitcnt vmcnt(30)
	v_fmac_f32_e32 v133, v5, v175
	v_fmac_f32_e32 v215, v21, v176
	global_store_dword v165, v133, s[48:49]
	global_store_dword v165, v215, s[48:49] offset:128
	s_add_u32 s48, s48, 0x8000
	s_addc_u32 s49, s49, 0
	s_waitcnt vmcnt(30)
	v_fmac_f32_e32 v134, v6, v175
	v_fmac_f32_e32 v216, v22, v176
	global_store_dword v162, v134, s[48:49]
	global_store_dword v162, v216, s[48:49] offset:128
	s_waitcnt vmcnt(30)
	v_fmac_f32_e32 v135, v7, v175
	v_fmac_f32_e32 v217, v23, v176
	global_store_dword v163, v135, s[48:49]
	global_store_dword v163, v217, s[48:49] offset:128
	s_waitcnt vmcnt(30)
	v_fmac_f32_e32 v136, v8, v175
	v_fmac_f32_e32 v218, v24, v176
	global_store_dword v164, v136, s[48:49]
	global_store_dword v164, v218, s[48:49] offset:128
	s_waitcnt vmcnt(30)
	v_fmac_f32_e32 v137, v9, v175
	v_fmac_f32_e32 v219, v25, v176
	global_store_dword v165, v137, s[48:49]
	global_store_dword v165, v219, s[48:49] offset:128
	s_add_u32 s48, s48, 0x8000
	s_addc_u32 s49, s49, 0
	s_waitcnt vmcnt(30)
	v_fmac_f32_e32 v138, v10, v175
	v_fmac_f32_e32 v220, v26, v176
	global_store_dword v162, v138, s[48:49]
	global_store_dword v162, v220, s[48:49] offset:128
	s_waitcnt vmcnt(30)
	v_fmac_f32_e32 v139, v11, v175
	v_fmac_f32_e32 v221, v27, v176
	global_store_dword v163, v139, s[48:49]
	global_store_dword v163, v221, s[48:49] offset:128
	s_waitcnt vmcnt(30)
	v_fmac_f32_e32 v140, v12, v175
	v_fmac_f32_e32 v222, v28, v176
	global_store_dword v164, v140, s[48:49]
	global_store_dword v164, v222, s[48:49] offset:128
	s_waitcnt vmcnt(30)
	v_fmac_f32_e32 v141, v13, v175
	v_fmac_f32_e32 v223, v29, v176
	global_store_dword v165, v141, s[48:49]
	global_store_dword v165, v223, s[48:49] offset:128
	s_add_u32 s48, s48, 0x8000
	s_addc_u32 s49, s49, 0
	s_waitcnt vmcnt(30)
	v_fmac_f32_e32 v142, v14, v175
	v_fmac_f32_e32 v224, v30, v176
	global_store_dword v162, v142, s[48:49]
	global_store_dword v162, v224, s[48:49] offset:128
	s_waitcnt vmcnt(30)
	v_fmac_f32_e32 v143, v15, v175
	v_fmac_f32_e32 v225, v31, v176
	global_store_dword v163, v143, s[48:49]
	global_store_dword v163, v225, s[48:49] offset:128
	s_waitcnt vmcnt(30)
	v_fmac_f32_e32 v144, v16, v175
	v_fmac_f32_e32 v226, v32, v176
	global_store_dword v164, v144, s[48:49]
	global_store_dword v164, v226, s[48:49] offset:128
	s_waitcnt vmcnt(30)
	v_fmac_f32_e32 v145, v17, v175
	v_fmac_f32_e32 v227, v33, v176
	global_store_dword v165, v145, s[48:49]
	global_store_dword v165, v227, s[48:49] offset:128
	s_sub_u32 s48, s48, 0x18000
	s_subb_u32 s49, s49, 0
	v_mul_f32_e32 v130, v130, v130
	v_fmac_f32_e32 v130, v212, v212
	v_mul_f32_e32 v131, v131, v131
	v_fmac_f32_e32 v131, v213, v213
	v_mul_f32_e32 v132, v132, v132
	v_fmac_f32_e32 v132, v214, v214
	v_mul_f32_e32 v133, v133, v133
	v_fmac_f32_e32 v133, v215, v215
	v_mul_f32_e32 v134, v134, v134
	v_fmac_f32_e32 v134, v216, v216
	v_mul_f32_e32 v135, v135, v135
	v_fmac_f32_e32 v135, v217, v217
	v_mul_f32_e32 v136, v136, v136
	v_fmac_f32_e32 v136, v218, v218
	v_mul_f32_e32 v137, v137, v137
	v_fmac_f32_e32 v137, v219, v219
	v_mul_f32_e32 v138, v138, v138
	v_fmac_f32_e32 v138, v220, v220
	v_mul_f32_e32 v139, v139, v139
	v_fmac_f32_e32 v139, v221, v221
	v_mul_f32_e32 v140, v140, v140
	v_fmac_f32_e32 v140, v222, v222
	v_mul_f32_e32 v141, v141, v141
	v_fmac_f32_e32 v141, v223, v223
	v_mul_f32_e32 v142, v142, v142
	v_fmac_f32_e32 v142, v224, v224
	v_mul_f32_e32 v143, v143, v143
	v_fmac_f32_e32 v143, v225, v225
	v_mul_f32_e32 v144, v144, v144
	v_fmac_f32_e32 v144, v226, v226
	v_mul_f32_e32 v145, v145, v145
	v_fmac_f32_e32 v145, v227, v227
	s_waitcnt lgkmcnt(0)
	ds_bpermute_b32 v212, v168, v130
	ds_bpermute_b32 v213, v168, v131
	ds_bpermute_b32 v214, v168, v132
	ds_bpermute_b32 v215, v168, v133
	ds_bpermute_b32 v216, v168, v134
	ds_bpermute_b32 v217, v168, v135
	ds_bpermute_b32 v218, v168, v136
	ds_bpermute_b32 v219, v168, v137
	s_waitcnt lgkmcnt(7)
	v_add_f32_e32 v130, v130, v212
	s_waitcnt lgkmcnt(6)
	v_add_f32_e32 v131, v131, v213
	s_waitcnt lgkmcnt(5)
	v_add_f32_e32 v132, v132, v214
	s_waitcnt lgkmcnt(4)
	v_add_f32_e32 v133, v133, v215
	s_waitcnt lgkmcnt(3)
	v_add_f32_e32 v134, v134, v216
	s_waitcnt lgkmcnt(2)
	v_add_f32_e32 v135, v135, v217
	s_waitcnt lgkmcnt(1)
	v_add_f32_e32 v136, v136, v218
	s_waitcnt lgkmcnt(0)
	v_add_f32_e32 v137, v137, v219
	ds_bpermute_b32 v212, v169, v130
	ds_bpermute_b32 v213, v169, v131
	ds_bpermute_b32 v214, v169, v132
	ds_bpermute_b32 v215, v169, v133
	ds_bpermute_b32 v216, v169, v134
	ds_bpermute_b32 v217, v169, v135
	ds_bpermute_b32 v218, v169, v136
	ds_bpermute_b32 v219, v169, v137
	s_waitcnt lgkmcnt(7)
	v_add_f32_e32 v130, v130, v212
	s_waitcnt lgkmcnt(6)
	v_add_f32_e32 v131, v131, v213
	s_waitcnt lgkmcnt(5)
	v_add_f32_e32 v132, v132, v214
	s_waitcnt lgkmcnt(4)
	v_add_f32_e32 v133, v133, v215
	s_waitcnt lgkmcnt(3)
	v_add_f32_e32 v134, v134, v216
	s_waitcnt lgkmcnt(2)
	v_add_f32_e32 v135, v135, v217
	s_waitcnt lgkmcnt(1)
	v_add_f32_e32 v136, v136, v218
	s_waitcnt lgkmcnt(0)
	v_add_f32_e32 v137, v137, v219
	ds_bpermute_b32 v212, v171, v130
	ds_bpermute_b32 v213, v171, v131
	ds_bpermute_b32 v214, v171, v132
	ds_bpermute_b32 v215, v171, v133
	ds_bpermute_b32 v216, v171, v134
	ds_bpermute_b32 v217, v171, v135
	ds_bpermute_b32 v218, v171, v136
	ds_bpermute_b32 v219, v171, v137
	s_waitcnt lgkmcnt(7)
	v_add_f32_e32 v130, v130, v212
	s_waitcnt lgkmcnt(6)
	v_add_f32_e32 v131, v131, v213
	s_waitcnt lgkmcnt(5)
	v_add_f32_e32 v132, v132, v214
	s_waitcnt lgkmcnt(4)
	v_add_f32_e32 v133, v133, v215
	s_waitcnt lgkmcnt(3)
	v_add_f32_e32 v134, v134, v216
	s_waitcnt lgkmcnt(2)
	v_add_f32_e32 v135, v135, v217
	s_waitcnt lgkmcnt(1)
	v_add_f32_e32 v136, v136, v218
	s_waitcnt lgkmcnt(0)
	v_add_f32_e32 v137, v137, v219
	ds_bpermute_b32 v212, v172, v130
	ds_bpermute_b32 v213, v172, v131
	ds_bpermute_b32 v214, v172, v132
	ds_bpermute_b32 v215, v172, v133
	ds_bpermute_b32 v216, v172, v134
	ds_bpermute_b32 v217, v172, v135
	ds_bpermute_b32 v218, v172, v136
	ds_bpermute_b32 v219, v172, v137
	s_waitcnt lgkmcnt(7)
	v_add_f32_e32 v130, v130, v212
	s_waitcnt lgkmcnt(6)
	v_add_f32_e32 v131, v131, v213
	s_waitcnt lgkmcnt(5)
	v_add_f32_e32 v132, v132, v214
	s_waitcnt lgkmcnt(4)
	v_add_f32_e32 v133, v133, v215
	s_waitcnt lgkmcnt(3)
	v_add_f32_e32 v134, v134, v216
	s_waitcnt lgkmcnt(2)
	v_add_f32_e32 v135, v135, v217
	s_waitcnt lgkmcnt(1)
	v_add_f32_e32 v136, v136, v218
	s_waitcnt lgkmcnt(0)
	v_add_f32_e32 v137, v137, v219
	ds_bpermute_b32 v212, v173, v130
	ds_bpermute_b32 v213, v173, v131
	ds_bpermute_b32 v214, v173, v132
	ds_bpermute_b32 v215, v173, v133
	ds_bpermute_b32 v216, v173, v134
	ds_bpermute_b32 v217, v173, v135
	ds_bpermute_b32 v218, v173, v136
	ds_bpermute_b32 v219, v173, v137
	s_waitcnt lgkmcnt(7)
	v_add_f32_e32 v130, v130, v212
	s_waitcnt lgkmcnt(6)
	v_add_f32_e32 v131, v131, v213
	s_waitcnt lgkmcnt(5)
	v_add_f32_e32 v132, v132, v214
	s_waitcnt lgkmcnt(4)
	v_add_f32_e32 v133, v133, v215
	s_waitcnt lgkmcnt(3)
	v_add_f32_e32 v134, v134, v216
	s_waitcnt lgkmcnt(2)
	v_add_f32_e32 v135, v135, v217
	s_waitcnt lgkmcnt(1)
	v_add_f32_e32 v136, v136, v218
	s_waitcnt lgkmcnt(0)
	v_add_f32_e32 v137, v137, v219
	ds_bpermute_b32 v220, v168, v138
	ds_bpermute_b32 v221, v168, v139
	ds_bpermute_b32 v222, v168, v140
	ds_bpermute_b32 v223, v168, v141
	ds_bpermute_b32 v224, v168, v142
	ds_bpermute_b32 v225, v168, v143
	ds_bpermute_b32 v226, v168, v144
	ds_bpermute_b32 v227, v168, v145
	s_waitcnt lgkmcnt(7)
	v_add_f32_e32 v138, v138, v220
	s_waitcnt lgkmcnt(6)
	v_add_f32_e32 v139, v139, v221
	s_waitcnt lgkmcnt(5)
	v_add_f32_e32 v140, v140, v222
	s_waitcnt lgkmcnt(4)
	v_add_f32_e32 v141, v141, v223
	s_waitcnt lgkmcnt(3)
	v_add_f32_e32 v142, v142, v224
	s_waitcnt lgkmcnt(2)
	v_add_f32_e32 v143, v143, v225
	s_waitcnt lgkmcnt(1)
	v_add_f32_e32 v144, v144, v226
	s_waitcnt lgkmcnt(0)
	v_add_f32_e32 v145, v145, v227
	ds_bpermute_b32 v220, v169, v138
	ds_bpermute_b32 v221, v169, v139
	ds_bpermute_b32 v222, v169, v140
	ds_bpermute_b32 v223, v169, v141
	ds_bpermute_b32 v224, v169, v142
	ds_bpermute_b32 v225, v169, v143
	ds_bpermute_b32 v226, v169, v144
	ds_bpermute_b32 v227, v169, v145
	s_waitcnt lgkmcnt(7)
	v_add_f32_e32 v138, v138, v220
	s_waitcnt lgkmcnt(6)
	v_add_f32_e32 v139, v139, v221
	s_waitcnt lgkmcnt(5)
	v_add_f32_e32 v140, v140, v222
	s_waitcnt lgkmcnt(4)
	v_add_f32_e32 v141, v141, v223
	s_waitcnt lgkmcnt(3)
	v_add_f32_e32 v142, v142, v224
	s_waitcnt lgkmcnt(2)
	v_add_f32_e32 v143, v143, v225
	s_waitcnt lgkmcnt(1)
	v_add_f32_e32 v144, v144, v226
	s_waitcnt lgkmcnt(0)
	v_add_f32_e32 v145, v145, v227
	ds_bpermute_b32 v220, v171, v138
	ds_bpermute_b32 v221, v171, v139
	ds_bpermute_b32 v222, v171, v140
	ds_bpermute_b32 v223, v171, v141
	ds_bpermute_b32 v224, v171, v142
	ds_bpermute_b32 v225, v171, v143
	ds_bpermute_b32 v226, v171, v144
	ds_bpermute_b32 v227, v171, v145
	s_waitcnt lgkmcnt(7)
	v_add_f32_e32 v138, v138, v220
	s_waitcnt lgkmcnt(6)
	v_add_f32_e32 v139, v139, v221
	s_waitcnt lgkmcnt(5)
	v_add_f32_e32 v140, v140, v222
	s_waitcnt lgkmcnt(4)
	v_add_f32_e32 v141, v141, v223
	s_waitcnt lgkmcnt(3)
	v_add_f32_e32 v142, v142, v224
	s_waitcnt lgkmcnt(2)
	v_add_f32_e32 v143, v143, v225
	s_waitcnt lgkmcnt(1)
	v_add_f32_e32 v144, v144, v226
	s_waitcnt lgkmcnt(0)
	v_add_f32_e32 v145, v145, v227
	ds_bpermute_b32 v220, v172, v138
	ds_bpermute_b32 v221, v172, v139
	ds_bpermute_b32 v222, v172, v140
	ds_bpermute_b32 v223, v172, v141
	ds_bpermute_b32 v224, v172, v142
	ds_bpermute_b32 v225, v172, v143
	ds_bpermute_b32 v226, v172, v144
	ds_bpermute_b32 v227, v172, v145
	s_waitcnt lgkmcnt(7)
	v_add_f32_e32 v138, v138, v220
	s_waitcnt lgkmcnt(6)
	v_add_f32_e32 v139, v139, v221
	s_waitcnt lgkmcnt(5)
	v_add_f32_e32 v140, v140, v222
	s_waitcnt lgkmcnt(4)
	v_add_f32_e32 v141, v141, v223
	s_waitcnt lgkmcnt(3)
	v_add_f32_e32 v142, v142, v224
	s_waitcnt lgkmcnt(2)
	v_add_f32_e32 v143, v143, v225
	s_waitcnt lgkmcnt(1)
	v_add_f32_e32 v144, v144, v226
	s_waitcnt lgkmcnt(0)
	v_add_f32_e32 v145, v145, v227
	ds_bpermute_b32 v220, v173, v138
	ds_bpermute_b32 v221, v173, v139
	ds_bpermute_b32 v222, v173, v140
	ds_bpermute_b32 v223, v173, v141
	ds_bpermute_b32 v224, v173, v142
	ds_bpermute_b32 v225, v173, v143
	ds_bpermute_b32 v226, v173, v144
	ds_bpermute_b32 v227, v173, v145
	s_waitcnt lgkmcnt(7)
	v_add_f32_e32 v138, v138, v220
	s_waitcnt lgkmcnt(6)
	v_add_f32_e32 v139, v139, v221
	s_waitcnt lgkmcnt(5)
	v_add_f32_e32 v140, v140, v222
	s_waitcnt lgkmcnt(4)
	v_add_f32_e32 v141, v141, v223
	s_waitcnt lgkmcnt(3)
	v_add_f32_e32 v142, v142, v224
	s_waitcnt lgkmcnt(2)
	v_add_f32_e32 v143, v143, v225
	s_waitcnt lgkmcnt(1)
	v_add_f32_e32 v144, v144, v226
	s_waitcnt lgkmcnt(0)
	v_add_f32_e32 v145, v145, v227
	v_cmp_eq_u32_e32 vcc, 0, v174
	s_and_saveexec_b64 s[58:59], vcc
	global_store_dword v167, v130, s[10:11]
	global_store_dword v167, v131, s[10:11] offset:4
	global_store_dword v167, v132, s[10:11] offset:8
	global_store_dword v167, v133, s[10:11] offset:12
	global_store_dword v167, v134, s[10:11] offset:32
	global_store_dword v167, v135, s[10:11] offset:36
	global_store_dword v167, v136, s[10:11] offset:40
	global_store_dword v167, v137, s[10:11] offset:44
	global_store_dword v167, v138, s[10:11] offset:64
	global_store_dword v167, v139, s[10:11] offset:68
	global_store_dword v167, v140, s[10:11] offset:72
	global_store_dword v167, v141, s[10:11] offset:76
	global_store_dword v167, v142, s[10:11] offset:96
	global_store_dword v167, v143, s[10:11] offset:100
	global_store_dword v167, v144, s[10:11] offset:104
	global_store_dword v167, v145, s[10:11] offset:108
	s_mov_b64 exec, -1
	s_add_u32 s48, s48, 0x20000
	s_addc_u32 s49, s49, 0
	global_load_dword v130, v162, s[48:49]
	global_load_dword v212, v162, s[48:49] offset:128
	global_load_dword v131, v163, s[48:49]
	global_load_dword v213, v163, s[48:49] offset:128
	global_load_dword v132, v164, s[48:49]
	global_load_dword v214, v164, s[48:49] offset:128
	global_load_dword v133, v165, s[48:49]
	global_load_dword v215, v165, s[48:49] offset:128
	s_add_u32 s48, s48, 0x8000
	s_addc_u32 s49, s49, 0
	global_load_dword v134, v162, s[48:49]
	global_load_dword v216, v162, s[48:49] offset:128
	global_load_dword v135, v163, s[48:49]
	global_load_dword v217, v163, s[48:49] offset:128
	global_load_dword v136, v164, s[48:49]
	global_load_dword v218, v164, s[48:49] offset:128
	global_load_dword v137, v165, s[48:49]
	global_load_dword v219, v165, s[48:49] offset:128
	s_add_u32 s48, s48, 0x8000
	s_addc_u32 s49, s49, 0
	global_load_dword v138, v162, s[48:49]
	global_load_dword v220, v162, s[48:49] offset:128
	global_load_dword v139, v163, s[48:49]
	global_load_dword v221, v163, s[48:49] offset:128
	global_load_dword v140, v164, s[48:49]
	global_load_dword v222, v164, s[48:49] offset:128
	global_load_dword v141, v165, s[48:49]
	global_load_dword v223, v165, s[48:49] offset:128
	s_add_u32 s48, s48, 0x8000
	s_addc_u32 s49, s49, 0
	global_load_dword v142, v162, s[48:49]
	global_load_dword v224, v162, s[48:49] offset:128
	global_load_dword v143, v163, s[48:49]
	global_load_dword v225, v163, s[48:49] offset:128
	global_load_dword v144, v164, s[48:49]
	global_load_dword v226, v164, s[48:49] offset:128
	global_load_dword v145, v165, s[48:49]
	global_load_dword v227, v165, s[48:49] offset:128
	s_sub_u32 s48, s48, 0x18000
	s_subb_u32 s49, s49, 0
	s_waitcnt vmcnt(30)
	v_fmac_f32_e32 v130, v34, v175
	v_fmac_f32_e32 v212, v50, v176
	global_store_dword v162, v130, s[48:49]
	global_store_dword v162, v212, s[48:49] offset:128
	s_waitcnt vmcnt(30)
	v_fmac_f32_e32 v131, v35, v175
	v_fmac_f32_e32 v213, v51, v176
	global_store_dword v163, v131, s[48:49]
	global_store_dword v163, v213, s[48:49] offset:128
	s_waitcnt vmcnt(30)
	v_fmac_f32_e32 v132, v36, v175
	v_fmac_f32_e32 v214, v52, v176
	global_store_dword v164, v132, s[48:49]
	global_store_dword v164, v214, s[48:49] offset:128
	s_waitcnt vmcnt(30)
	v_fmac_f32_e32 v133, v37, v175
	v_fmac_f32_e32 v215, v53, v176
	global_store_dword v165, v133, s[48:49]
	global_store_dword v165, v215, s[48:49] offset:128
	s_add_u32 s48, s48, 0x8000
	s_addc_u32 s49, s49, 0
	s_waitcnt vmcnt(30)
	v_fmac_f32_e32 v134, v38, v175
	v_fmac_f32_e32 v216, v54, v176
	global_store_dword v162, v134, s[48:49]
	global_store_dword v162, v216, s[48:49] offset:128
	s_waitcnt vmcnt(30)
	v_fmac_f32_e32 v135, v39, v175
	v_fmac_f32_e32 v217, v55, v176
	global_store_dword v163, v135, s[48:49]
	global_store_dword v163, v217, s[48:49] offset:128
	s_waitcnt vmcnt(30)
	v_fmac_f32_e32 v136, v40, v175
	v_fmac_f32_e32 v218, v56, v176
	global_store_dword v164, v136, s[48:49]
	global_store_dword v164, v218, s[48:49] offset:128
	s_waitcnt vmcnt(30)
	v_fmac_f32_e32 v137, v41, v175
	v_fmac_f32_e32 v219, v57, v176
	global_store_dword v165, v137, s[48:49]
	global_store_dword v165, v219, s[48:49] offset:128
	s_add_u32 s48, s48, 0x8000
	s_addc_u32 s49, s49, 0
	s_waitcnt vmcnt(30)
	v_fmac_f32_e32 v138, v42, v175
	v_fmac_f32_e32 v220, v58, v176
	global_store_dword v162, v138, s[48:49]
	global_store_dword v162, v220, s[48:49] offset:128
	s_waitcnt vmcnt(30)
	v_fmac_f32_e32 v139, v43, v175
	v_fmac_f32_e32 v221, v59, v176
	global_store_dword v163, v139, s[48:49]
	global_store_dword v163, v221, s[48:49] offset:128
	s_waitcnt vmcnt(30)
	v_fmac_f32_e32 v140, v44, v175
	v_fmac_f32_e32 v222, v60, v176
	global_store_dword v164, v140, s[48:49]
	global_store_dword v164, v222, s[48:49] offset:128
	s_waitcnt vmcnt(30)
	v_fmac_f32_e32 v141, v45, v175
	v_fmac_f32_e32 v223, v61, v176
	global_store_dword v165, v141, s[48:49]
	global_store_dword v165, v223, s[48:49] offset:128
	s_add_u32 s48, s48, 0x8000
	s_addc_u32 s49, s49, 0
	s_waitcnt vmcnt(30)
	v_fmac_f32_e32 v142, v46, v175
	v_fmac_f32_e32 v224, v62, v176
	global_store_dword v162, v142, s[48:49]
	global_store_dword v162, v224, s[48:49] offset:128
	s_waitcnt vmcnt(30)
	v_fmac_f32_e32 v143, v47, v175
	v_fmac_f32_e32 v225, v63, v176
	global_store_dword v163, v143, s[48:49]
	global_store_dword v163, v225, s[48:49] offset:128
	s_waitcnt vmcnt(30)
	v_fmac_f32_e32 v144, v48, v175
	v_fmac_f32_e32 v226, v64, v176
	global_store_dword v164, v144, s[48:49]
	global_store_dword v164, v226, s[48:49] offset:128
	s_waitcnt vmcnt(30)
	v_fmac_f32_e32 v145, v49, v175
	v_fmac_f32_e32 v227, v65, v176
	global_store_dword v165, v145, s[48:49]
	global_store_dword v165, v227, s[48:49] offset:128
	s_sub_u32 s48, s48, 0x18000
	s_subb_u32 s49, s49, 0
	v_mul_f32_e32 v130, v130, v130
	v_fmac_f32_e32 v130, v212, v212
	v_mul_f32_e32 v131, v131, v131
	v_fmac_f32_e32 v131, v213, v213
	v_mul_f32_e32 v132, v132, v132
	v_fmac_f32_e32 v132, v214, v214
	v_mul_f32_e32 v133, v133, v133
	v_fmac_f32_e32 v133, v215, v215
	v_mul_f32_e32 v134, v134, v134
	v_fmac_f32_e32 v134, v216, v216
	v_mul_f32_e32 v135, v135, v135
	v_fmac_f32_e32 v135, v217, v217
	v_mul_f32_e32 v136, v136, v136
	v_fmac_f32_e32 v136, v218, v218
	v_mul_f32_e32 v137, v137, v137
	v_fmac_f32_e32 v137, v219, v219
	v_mul_f32_e32 v138, v138, v138
	v_fmac_f32_e32 v138, v220, v220
	v_mul_f32_e32 v139, v139, v139
	v_fmac_f32_e32 v139, v221, v221
	v_mul_f32_e32 v140, v140, v140
	v_fmac_f32_e32 v140, v222, v222
	v_mul_f32_e32 v141, v141, v141
	v_fmac_f32_e32 v141, v223, v223
	v_mul_f32_e32 v142, v142, v142
	v_fmac_f32_e32 v142, v224, v224
	v_mul_f32_e32 v143, v143, v143
	v_fmac_f32_e32 v143, v225, v225
	v_mul_f32_e32 v144, v144, v144
	v_fmac_f32_e32 v144, v226, v226
	v_mul_f32_e32 v145, v145, v145
	v_fmac_f32_e32 v145, v227, v227
	s_waitcnt lgkmcnt(0)
	ds_bpermute_b32 v212, v168, v130
	ds_bpermute_b32 v213, v168, v131
	ds_bpermute_b32 v214, v168, v132
	ds_bpermute_b32 v215, v168, v133
	ds_bpermute_b32 v216, v168, v134
	ds_bpermute_b32 v217, v168, v135
	ds_bpermute_b32 v218, v168, v136
	ds_bpermute_b32 v219, v168, v137
	s_waitcnt lgkmcnt(7)
	v_add_f32_e32 v130, v130, v212
	s_waitcnt lgkmcnt(6)
	v_add_f32_e32 v131, v131, v213
	s_waitcnt lgkmcnt(5)
	v_add_f32_e32 v132, v132, v214
	s_waitcnt lgkmcnt(4)
	v_add_f32_e32 v133, v133, v215
	s_waitcnt lgkmcnt(3)
	v_add_f32_e32 v134, v134, v216
	s_waitcnt lgkmcnt(2)
	v_add_f32_e32 v135, v135, v217
	s_waitcnt lgkmcnt(1)
	v_add_f32_e32 v136, v136, v218
	s_waitcnt lgkmcnt(0)
	v_add_f32_e32 v137, v137, v219
	ds_bpermute_b32 v212, v169, v130
	ds_bpermute_b32 v213, v169, v131
	ds_bpermute_b32 v214, v169, v132
	ds_bpermute_b32 v215, v169, v133
	ds_bpermute_b32 v216, v169, v134
	ds_bpermute_b32 v217, v169, v135
	ds_bpermute_b32 v218, v169, v136
	ds_bpermute_b32 v219, v169, v137
	s_waitcnt lgkmcnt(7)
	v_add_f32_e32 v130, v130, v212
	s_waitcnt lgkmcnt(6)
	v_add_f32_e32 v131, v131, v213
	s_waitcnt lgkmcnt(5)
	v_add_f32_e32 v132, v132, v214
	s_waitcnt lgkmcnt(4)
	v_add_f32_e32 v133, v133, v215
	s_waitcnt lgkmcnt(3)
	v_add_f32_e32 v134, v134, v216
	s_waitcnt lgkmcnt(2)
	v_add_f32_e32 v135, v135, v217
	s_waitcnt lgkmcnt(1)
	v_add_f32_e32 v136, v136, v218
	s_waitcnt lgkmcnt(0)
	v_add_f32_e32 v137, v137, v219
	ds_bpermute_b32 v212, v171, v130
	ds_bpermute_b32 v213, v171, v131
	ds_bpermute_b32 v214, v171, v132
	ds_bpermute_b32 v215, v171, v133
	ds_bpermute_b32 v216, v171, v134
	ds_bpermute_b32 v217, v171, v135
	ds_bpermute_b32 v218, v171, v136
	ds_bpermute_b32 v219, v171, v137
	s_waitcnt lgkmcnt(7)
	v_add_f32_e32 v130, v130, v212
	s_waitcnt lgkmcnt(6)
	v_add_f32_e32 v131, v131, v213
	s_waitcnt lgkmcnt(5)
	v_add_f32_e32 v132, v132, v214
	s_waitcnt lgkmcnt(4)
	v_add_f32_e32 v133, v133, v215
	s_waitcnt lgkmcnt(3)
	v_add_f32_e32 v134, v134, v216
	s_waitcnt lgkmcnt(2)
	v_add_f32_e32 v135, v135, v217
	s_waitcnt lgkmcnt(1)
	v_add_f32_e32 v136, v136, v218
	s_waitcnt lgkmcnt(0)
	v_add_f32_e32 v137, v137, v219
	ds_bpermute_b32 v212, v172, v130
	ds_bpermute_b32 v213, v172, v131
	ds_bpermute_b32 v214, v172, v132
	ds_bpermute_b32 v215, v172, v133
	ds_bpermute_b32 v216, v172, v134
	ds_bpermute_b32 v217, v172, v135
	ds_bpermute_b32 v218, v172, v136
	ds_bpermute_b32 v219, v172, v137
	s_waitcnt lgkmcnt(7)
	v_add_f32_e32 v130, v130, v212
	s_waitcnt lgkmcnt(6)
	v_add_f32_e32 v131, v131, v213
	s_waitcnt lgkmcnt(5)
	v_add_f32_e32 v132, v132, v214
	s_waitcnt lgkmcnt(4)
	v_add_f32_e32 v133, v133, v215
	s_waitcnt lgkmcnt(3)
	v_add_f32_e32 v134, v134, v216
	s_waitcnt lgkmcnt(2)
	v_add_f32_e32 v135, v135, v217
	s_waitcnt lgkmcnt(1)
	v_add_f32_e32 v136, v136, v218
	s_waitcnt lgkmcnt(0)
	v_add_f32_e32 v137, v137, v219
	ds_bpermute_b32 v212, v173, v130
	ds_bpermute_b32 v213, v173, v131
	ds_bpermute_b32 v214, v173, v132
	ds_bpermute_b32 v215, v173, v133
	ds_bpermute_b32 v216, v173, v134
	ds_bpermute_b32 v217, v173, v135
	ds_bpermute_b32 v218, v173, v136
	ds_bpermute_b32 v219, v173, v137
	s_waitcnt lgkmcnt(7)
	v_add_f32_e32 v130, v130, v212
	s_waitcnt lgkmcnt(6)
	v_add_f32_e32 v131, v131, v213
	s_waitcnt lgkmcnt(5)
	v_add_f32_e32 v132, v132, v214
	s_waitcnt lgkmcnt(4)
	v_add_f32_e32 v133, v133, v215
	s_waitcnt lgkmcnt(3)
	v_add_f32_e32 v134, v134, v216
	s_waitcnt lgkmcnt(2)
	v_add_f32_e32 v135, v135, v217
	s_waitcnt lgkmcnt(1)
	v_add_f32_e32 v136, v136, v218
	s_waitcnt lgkmcnt(0)
	v_add_f32_e32 v137, v137, v219
	ds_bpermute_b32 v220, v168, v138
	ds_bpermute_b32 v221, v168, v139
	ds_bpermute_b32 v222, v168, v140
	ds_bpermute_b32 v223, v168, v141
	ds_bpermute_b32 v224, v168, v142
	ds_bpermute_b32 v225, v168, v143
	ds_bpermute_b32 v226, v168, v144
	ds_bpermute_b32 v227, v168, v145
	s_waitcnt lgkmcnt(7)
	v_add_f32_e32 v138, v138, v220
	s_waitcnt lgkmcnt(6)
	v_add_f32_e32 v139, v139, v221
	s_waitcnt lgkmcnt(5)
	v_add_f32_e32 v140, v140, v222
	s_waitcnt lgkmcnt(4)
	v_add_f32_e32 v141, v141, v223
	s_waitcnt lgkmcnt(3)
	v_add_f32_e32 v142, v142, v224
	s_waitcnt lgkmcnt(2)
	v_add_f32_e32 v143, v143, v225
	s_waitcnt lgkmcnt(1)
	v_add_f32_e32 v144, v144, v226
	s_waitcnt lgkmcnt(0)
	v_add_f32_e32 v145, v145, v227
	ds_bpermute_b32 v220, v169, v138
	ds_bpermute_b32 v221, v169, v139
	ds_bpermute_b32 v222, v169, v140
	ds_bpermute_b32 v223, v169, v141
	ds_bpermute_b32 v224, v169, v142
	ds_bpermute_b32 v225, v169, v143
	ds_bpermute_b32 v226, v169, v144
	ds_bpermute_b32 v227, v169, v145
	s_waitcnt lgkmcnt(7)
	v_add_f32_e32 v138, v138, v220
	s_waitcnt lgkmcnt(6)
	v_add_f32_e32 v139, v139, v221
	s_waitcnt lgkmcnt(5)
	v_add_f32_e32 v140, v140, v222
	s_waitcnt lgkmcnt(4)
	v_add_f32_e32 v141, v141, v223
	s_waitcnt lgkmcnt(3)
	v_add_f32_e32 v142, v142, v224
	s_waitcnt lgkmcnt(2)
	v_add_f32_e32 v143, v143, v225
	s_waitcnt lgkmcnt(1)
	v_add_f32_e32 v144, v144, v226
	s_waitcnt lgkmcnt(0)
	v_add_f32_e32 v145, v145, v227
	ds_bpermute_b32 v220, v171, v138
	ds_bpermute_b32 v221, v171, v139
	ds_bpermute_b32 v222, v171, v140
	ds_bpermute_b32 v223, v171, v141
	ds_bpermute_b32 v224, v171, v142
	ds_bpermute_b32 v225, v171, v143
	ds_bpermute_b32 v226, v171, v144
	ds_bpermute_b32 v227, v171, v145
	s_waitcnt lgkmcnt(7)
	v_add_f32_e32 v138, v138, v220
	s_waitcnt lgkmcnt(6)
	v_add_f32_e32 v139, v139, v221
	s_waitcnt lgkmcnt(5)
	v_add_f32_e32 v140, v140, v222
	s_waitcnt lgkmcnt(4)
	v_add_f32_e32 v141, v141, v223
	s_waitcnt lgkmcnt(3)
	v_add_f32_e32 v142, v142, v224
	s_waitcnt lgkmcnt(2)
	v_add_f32_e32 v143, v143, v225
	s_waitcnt lgkmcnt(1)
	v_add_f32_e32 v144, v144, v226
	s_waitcnt lgkmcnt(0)
	v_add_f32_e32 v145, v145, v227
	ds_bpermute_b32 v220, v172, v138
	ds_bpermute_b32 v221, v172, v139
	ds_bpermute_b32 v222, v172, v140
	ds_bpermute_b32 v223, v172, v141
	ds_bpermute_b32 v224, v172, v142
	ds_bpermute_b32 v225, v172, v143
	ds_bpermute_b32 v226, v172, v144
	ds_bpermute_b32 v227, v172, v145
	s_waitcnt lgkmcnt(7)
	v_add_f32_e32 v138, v138, v220
	s_waitcnt lgkmcnt(6)
	v_add_f32_e32 v139, v139, v221
	s_waitcnt lgkmcnt(5)
	v_add_f32_e32 v140, v140, v222
	s_waitcnt lgkmcnt(4)
	v_add_f32_e32 v141, v141, v223
	s_waitcnt lgkmcnt(3)
	v_add_f32_e32 v142, v142, v224
	s_waitcnt lgkmcnt(2)
	v_add_f32_e32 v143, v143, v225
	s_waitcnt lgkmcnt(1)
	v_add_f32_e32 v144, v144, v226
	s_waitcnt lgkmcnt(0)
	v_add_f32_e32 v145, v145, v227
	ds_bpermute_b32 v220, v173, v138
	ds_bpermute_b32 v221, v173, v139
	ds_bpermute_b32 v222, v173, v140
	ds_bpermute_b32 v223, v173, v141
	ds_bpermute_b32 v224, v173, v142
	ds_bpermute_b32 v225, v173, v143
	ds_bpermute_b32 v226, v173, v144
	ds_bpermute_b32 v227, v173, v145
	s_waitcnt lgkmcnt(7)
	v_add_f32_e32 v138, v138, v220
	s_waitcnt lgkmcnt(6)
	v_add_f32_e32 v139, v139, v221
	s_waitcnt lgkmcnt(5)
	v_add_f32_e32 v140, v140, v222
	s_waitcnt lgkmcnt(4)
	v_add_f32_e32 v141, v141, v223
	s_waitcnt lgkmcnt(3)
	v_add_f32_e32 v142, v142, v224
	s_waitcnt lgkmcnt(2)
	v_add_f32_e32 v143, v143, v225
	s_waitcnt lgkmcnt(1)
	v_add_f32_e32 v144, v144, v226
	s_waitcnt lgkmcnt(0)
	v_add_f32_e32 v145, v145, v227
	v_cmp_eq_u32_e32 vcc, 0, v174
	s_and_saveexec_b64 s[58:59], vcc
	global_store_dword v167, v130, s[10:11] offset:128
	global_store_dword v167, v131, s[10:11] offset:132
	global_store_dword v167, v132, s[10:11] offset:136
	global_store_dword v167, v133, s[10:11] offset:140
	global_store_dword v167, v134, s[10:11] offset:160
	global_store_dword v167, v135, s[10:11] offset:164
	global_store_dword v167, v136, s[10:11] offset:168
	global_store_dword v167, v137, s[10:11] offset:172
	global_store_dword v167, v138, s[10:11] offset:192
	global_store_dword v167, v139, s[10:11] offset:196
	global_store_dword v167, v140, s[10:11] offset:200
	global_store_dword v167, v141, s[10:11] offset:204
	global_store_dword v167, v142, s[10:11] offset:224
	global_store_dword v167, v143, s[10:11] offset:228
	global_store_dword v167, v144, s[10:11] offset:232
	global_store_dword v167, v145, s[10:11] offset:236
	s_mov_b64 exec, -1
	s_sub_u32 s48, s48, 0x20000
	s_subb_u32 s49, s49, 0
	s_add_u32 s60, s60, 0x200
	s_addc_u32 s61, s61, 0
	s_add_u32 s10, s10, 0x18000
	s_addc_u32 s11, s11, 0
	s_add_u32 s48, s48, 0x200
	s_addc_u32 s49, s49, 0
	global_load_dword v175, v166, s[60:61]
	global_load_dword v176, v166, s[60:61] offset:128
	global_load_dword v130, v162, s[48:49]
	global_load_dword v212, v162, s[48:49] offset:128
	global_load_dword v131, v163, s[48:49]
	global_load_dword v213, v163, s[48:49] offset:128
	global_load_dword v132, v164, s[48:49]
	global_load_dword v214, v164, s[48:49] offset:128
	global_load_dword v133, v165, s[48:49]
	global_load_dword v215, v165, s[48:49] offset:128
	s_add_u32 s48, s48, 0x8000
	s_addc_u32 s49, s49, 0
	global_load_dword v134, v162, s[48:49]
	global_load_dword v216, v162, s[48:49] offset:128
	global_load_dword v135, v163, s[48:49]
	global_load_dword v217, v163, s[48:49] offset:128
	global_load_dword v136, v164, s[48:49]
	global_load_dword v218, v164, s[48:49] offset:128
	global_load_dword v137, v165, s[48:49]
	global_load_dword v219, v165, s[48:49] offset:128
	s_add_u32 s48, s48, 0x8000
	s_addc_u32 s49, s49, 0
	global_load_dword v138, v162, s[48:49]
	global_load_dword v220, v162, s[48:49] offset:128
	global_load_dword v139, v163, s[48:49]
	global_load_dword v221, v163, s[48:49] offset:128
	global_load_dword v140, v164, s[48:49]
	global_load_dword v222, v164, s[48:49] offset:128
	global_load_dword v141, v165, s[48:49]
	global_load_dword v223, v165, s[48:49] offset:128
	s_add_u32 s48, s48, 0x8000
	s_addc_u32 s49, s49, 0
	global_load_dword v142, v162, s[48:49]
	global_load_dword v224, v162, s[48:49] offset:128
	global_load_dword v143, v163, s[48:49]
	global_load_dword v225, v163, s[48:49] offset:128
	global_load_dword v144, v164, s[48:49]
	global_load_dword v226, v164, s[48:49] offset:128
	global_load_dword v145, v165, s[48:49]
	global_load_dword v227, v165, s[48:49] offset:128
	s_sub_u32 s48, s48, 0x18000
	s_subb_u32 s49, s49, 0
	s_waitcnt vmcnt(32)
	v_mul_f32_e32 v175, 0.5, v175
	v_mul_f32_e32 v176, 0.5, v176
	s_waitcnt vmcnt(30)
	v_fmac_f32_e32 v130, v66, v175
	v_fmac_f32_e32 v212, v82, v176
	global_store_dword v162, v130, s[48:49]
	global_store_dword v162, v212, s[48:49] offset:128
	s_waitcnt vmcnt(30)
	v_fmac_f32_e32 v131, v67, v175
	v_fmac_f32_e32 v213, v83, v176
	global_store_dword v163, v131, s[48:49]
	global_store_dword v163, v213, s[48:49] offset:128
	s_waitcnt vmcnt(30)
	v_fmac_f32_e32 v132, v68, v175
	v_fmac_f32_e32 v214, v84, v176
	global_store_dword v164, v132, s[48:49]
	global_store_dword v164, v214, s[48:49] offset:128
	s_waitcnt vmcnt(30)
	v_fmac_f32_e32 v133, v69, v175
	v_fmac_f32_e32 v215, v85, v176
	global_store_dword v165, v133, s[48:49]
	global_store_dword v165, v215, s[48:49] offset:128
	s_add_u32 s48, s48, 0x8000
	s_addc_u32 s49, s49, 0
	s_waitcnt vmcnt(30)
	v_fmac_f32_e32 v134, v70, v175
	v_fmac_f32_e32 v216, v86, v176
	global_store_dword v162, v134, s[48:49]
	global_store_dword v162, v216, s[48:49] offset:128
	s_waitcnt vmcnt(30)
	v_fmac_f32_e32 v135, v71, v175
	v_fmac_f32_e32 v217, v87, v176
	global_store_dword v163, v135, s[48:49]
	global_store_dword v163, v217, s[48:49] offset:128
	s_waitcnt vmcnt(30)
	v_fmac_f32_e32 v136, v72, v175
	v_fmac_f32_e32 v218, v88, v176
	global_store_dword v164, v136, s[48:49]
	global_store_dword v164, v218, s[48:49] offset:128
	s_waitcnt vmcnt(30)
	v_fmac_f32_e32 v137, v73, v175
	v_fmac_f32_e32 v219, v89, v176
	global_store_dword v165, v137, s[48:49]
	global_store_dword v165, v219, s[48:49] offset:128
	s_add_u32 s48, s48, 0x8000
	s_addc_u32 s49, s49, 0
	s_waitcnt vmcnt(30)
	v_fmac_f32_e32 v138, v74, v175
	v_fmac_f32_e32 v220, v90, v176
	global_store_dword v162, v138, s[48:49]
	global_store_dword v162, v220, s[48:49] offset:128
	s_waitcnt vmcnt(30)
	v_fmac_f32_e32 v139, v75, v175
	v_fmac_f32_e32 v221, v91, v176
	global_store_dword v163, v139, s[48:49]
	global_store_dword v163, v221, s[48:49] offset:128
	s_waitcnt vmcnt(30)
	v_fmac_f32_e32 v140, v76, v175
	v_fmac_f32_e32 v222, v92, v176
	global_store_dword v164, v140, s[48:49]
	global_store_dword v164, v222, s[48:49] offset:128
	s_waitcnt vmcnt(30)
	v_fmac_f32_e32 v141, v77, v175
	v_fmac_f32_e32 v223, v93, v176
	global_store_dword v165, v141, s[48:49]
	global_store_dword v165, v223, s[48:49] offset:128
	s_add_u32 s48, s48, 0x8000
	s_addc_u32 s49, s49, 0
	s_waitcnt vmcnt(30)
	v_fmac_f32_e32 v142, v78, v175
	v_fmac_f32_e32 v224, v94, v176
	global_store_dword v162, v142, s[48:49]
	global_store_dword v162, v224, s[48:49] offset:128
	s_waitcnt vmcnt(30)
	v_fmac_f32_e32 v143, v79, v175
	v_fmac_f32_e32 v225, v95, v176
	global_store_dword v163, v143, s[48:49]
	global_store_dword v163, v225, s[48:49] offset:128
	s_waitcnt vmcnt(30)
	v_fmac_f32_e32 v144, v80, v175
	v_fmac_f32_e32 v226, v96, v176
	global_store_dword v164, v144, s[48:49]
	global_store_dword v164, v226, s[48:49] offset:128
	s_waitcnt vmcnt(30)
	v_fmac_f32_e32 v145, v81, v175
	v_fmac_f32_e32 v227, v97, v176
	global_store_dword v165, v145, s[48:49]
	global_store_dword v165, v227, s[48:49] offset:128
	s_sub_u32 s48, s48, 0x18000
	s_subb_u32 s49, s49, 0
	v_mul_f32_e32 v130, v130, v130
	v_fmac_f32_e32 v130, v212, v212
	v_mul_f32_e32 v131, v131, v131
	v_fmac_f32_e32 v131, v213, v213
	v_mul_f32_e32 v132, v132, v132
	v_fmac_f32_e32 v132, v214, v214
	v_mul_f32_e32 v133, v133, v133
	v_fmac_f32_e32 v133, v215, v215
	v_mul_f32_e32 v134, v134, v134
	v_fmac_f32_e32 v134, v216, v216
	v_mul_f32_e32 v135, v135, v135
	v_fmac_f32_e32 v135, v217, v217
	v_mul_f32_e32 v136, v136, v136
	v_fmac_f32_e32 v136, v218, v218
	v_mul_f32_e32 v137, v137, v137
	v_fmac_f32_e32 v137, v219, v219
	v_mul_f32_e32 v138, v138, v138
	v_fmac_f32_e32 v138, v220, v220
	v_mul_f32_e32 v139, v139, v139
	v_fmac_f32_e32 v139, v221, v221
	v_mul_f32_e32 v140, v140, v140
	v_fmac_f32_e32 v140, v222, v222
	v_mul_f32_e32 v141, v141, v141
	v_fmac_f32_e32 v141, v223, v223
	v_mul_f32_e32 v142, v142, v142
	v_fmac_f32_e32 v142, v224, v224
	v_mul_f32_e32 v143, v143, v143
	v_fmac_f32_e32 v143, v225, v225
	v_mul_f32_e32 v144, v144, v144
	v_fmac_f32_e32 v144, v226, v226
	v_mul_f32_e32 v145, v145, v145
	v_fmac_f32_e32 v145, v227, v227
	s_waitcnt lgkmcnt(0)
	ds_bpermute_b32 v212, v168, v130
	ds_bpermute_b32 v213, v168, v131
	ds_bpermute_b32 v214, v168, v132
	ds_bpermute_b32 v215, v168, v133
	ds_bpermute_b32 v216, v168, v134
	ds_bpermute_b32 v217, v168, v135
	ds_bpermute_b32 v218, v168, v136
	ds_bpermute_b32 v219, v168, v137
	s_waitcnt lgkmcnt(7)
	v_add_f32_e32 v130, v130, v212
	s_waitcnt lgkmcnt(6)
	v_add_f32_e32 v131, v131, v213
	s_waitcnt lgkmcnt(5)
	v_add_f32_e32 v132, v132, v214
	s_waitcnt lgkmcnt(4)
	v_add_f32_e32 v133, v133, v215
	s_waitcnt lgkmcnt(3)
	v_add_f32_e32 v134, v134, v216
	s_waitcnt lgkmcnt(2)
	v_add_f32_e32 v135, v135, v217
	s_waitcnt lgkmcnt(1)
	v_add_f32_e32 v136, v136, v218
	s_waitcnt lgkmcnt(0)
	v_add_f32_e32 v137, v137, v219
	ds_bpermute_b32 v212, v169, v130
	ds_bpermute_b32 v213, v169, v131
	ds_bpermute_b32 v214, v169, v132
	ds_bpermute_b32 v215, v169, v133
	ds_bpermute_b32 v216, v169, v134
	ds_bpermute_b32 v217, v169, v135
	ds_bpermute_b32 v218, v169, v136
	ds_bpermute_b32 v219, v169, v137
	s_waitcnt lgkmcnt(7)
	v_add_f32_e32 v130, v130, v212
	s_waitcnt lgkmcnt(6)
	v_add_f32_e32 v131, v131, v213
	s_waitcnt lgkmcnt(5)
	v_add_f32_e32 v132, v132, v214
	s_waitcnt lgkmcnt(4)
	v_add_f32_e32 v133, v133, v215
	s_waitcnt lgkmcnt(3)
	v_add_f32_e32 v134, v134, v216
	s_waitcnt lgkmcnt(2)
	v_add_f32_e32 v135, v135, v217
	s_waitcnt lgkmcnt(1)
	v_add_f32_e32 v136, v136, v218
	s_waitcnt lgkmcnt(0)
	v_add_f32_e32 v137, v137, v219
	ds_bpermute_b32 v212, v171, v130
	ds_bpermute_b32 v213, v171, v131
	ds_bpermute_b32 v214, v171, v132
	ds_bpermute_b32 v215, v171, v133
	ds_bpermute_b32 v216, v171, v134
	ds_bpermute_b32 v217, v171, v135
	ds_bpermute_b32 v218, v171, v136
	ds_bpermute_b32 v219, v171, v137
	s_waitcnt lgkmcnt(7)
	v_add_f32_e32 v130, v130, v212
	s_waitcnt lgkmcnt(6)
	v_add_f32_e32 v131, v131, v213
	s_waitcnt lgkmcnt(5)
	v_add_f32_e32 v132, v132, v214
	s_waitcnt lgkmcnt(4)
	v_add_f32_e32 v133, v133, v215
	s_waitcnt lgkmcnt(3)
	v_add_f32_e32 v134, v134, v216
	s_waitcnt lgkmcnt(2)
	v_add_f32_e32 v135, v135, v217
	s_waitcnt lgkmcnt(1)
	v_add_f32_e32 v136, v136, v218
	s_waitcnt lgkmcnt(0)
	v_add_f32_e32 v137, v137, v219
	ds_bpermute_b32 v212, v172, v130
	ds_bpermute_b32 v213, v172, v131
	ds_bpermute_b32 v214, v172, v132
	ds_bpermute_b32 v215, v172, v133
	ds_bpermute_b32 v216, v172, v134
	ds_bpermute_b32 v217, v172, v135
	ds_bpermute_b32 v218, v172, v136
	ds_bpermute_b32 v219, v172, v137
	s_waitcnt lgkmcnt(7)
	v_add_f32_e32 v130, v130, v212
	s_waitcnt lgkmcnt(6)
	v_add_f32_e32 v131, v131, v213
	s_waitcnt lgkmcnt(5)
	v_add_f32_e32 v132, v132, v214
	s_waitcnt lgkmcnt(4)
	v_add_f32_e32 v133, v133, v215
	s_waitcnt lgkmcnt(3)
	v_add_f32_e32 v134, v134, v216
	s_waitcnt lgkmcnt(2)
	v_add_f32_e32 v135, v135, v217
	s_waitcnt lgkmcnt(1)
	v_add_f32_e32 v136, v136, v218
	s_waitcnt lgkmcnt(0)
	v_add_f32_e32 v137, v137, v219
	ds_bpermute_b32 v212, v173, v130
	ds_bpermute_b32 v213, v173, v131
	ds_bpermute_b32 v214, v173, v132
	ds_bpermute_b32 v215, v173, v133
	ds_bpermute_b32 v216, v173, v134
	ds_bpermute_b32 v217, v173, v135
	ds_bpermute_b32 v218, v173, v136
	ds_bpermute_b32 v219, v173, v137
	s_waitcnt lgkmcnt(7)
	v_add_f32_e32 v130, v130, v212
	s_waitcnt lgkmcnt(6)
	v_add_f32_e32 v131, v131, v213
	s_waitcnt lgkmcnt(5)
	v_add_f32_e32 v132, v132, v214
	s_waitcnt lgkmcnt(4)
	v_add_f32_e32 v133, v133, v215
	s_waitcnt lgkmcnt(3)
	v_add_f32_e32 v134, v134, v216
	s_waitcnt lgkmcnt(2)
	v_add_f32_e32 v135, v135, v217
	s_waitcnt lgkmcnt(1)
	v_add_f32_e32 v136, v136, v218
	s_waitcnt lgkmcnt(0)
	v_add_f32_e32 v137, v137, v219
	ds_bpermute_b32 v220, v168, v138
	ds_bpermute_b32 v221, v168, v139
	ds_bpermute_b32 v222, v168, v140
	ds_bpermute_b32 v223, v168, v141
	ds_bpermute_b32 v224, v168, v142
	ds_bpermute_b32 v225, v168, v143
	ds_bpermute_b32 v226, v168, v144
	ds_bpermute_b32 v227, v168, v145
	s_waitcnt lgkmcnt(7)
	v_add_f32_e32 v138, v138, v220
	s_waitcnt lgkmcnt(6)
	v_add_f32_e32 v139, v139, v221
	s_waitcnt lgkmcnt(5)
	v_add_f32_e32 v140, v140, v222
	s_waitcnt lgkmcnt(4)
	v_add_f32_e32 v141, v141, v223
	s_waitcnt lgkmcnt(3)
	v_add_f32_e32 v142, v142, v224
	s_waitcnt lgkmcnt(2)
	v_add_f32_e32 v143, v143, v225
	s_waitcnt lgkmcnt(1)
	v_add_f32_e32 v144, v144, v226
	s_waitcnt lgkmcnt(0)
	v_add_f32_e32 v145, v145, v227
	ds_bpermute_b32 v220, v169, v138
	ds_bpermute_b32 v221, v169, v139
	ds_bpermute_b32 v222, v169, v140
	ds_bpermute_b32 v223, v169, v141
	ds_bpermute_b32 v224, v169, v142
	ds_bpermute_b32 v225, v169, v143
	ds_bpermute_b32 v226, v169, v144
	ds_bpermute_b32 v227, v169, v145
	s_waitcnt lgkmcnt(7)
	v_add_f32_e32 v138, v138, v220
	s_waitcnt lgkmcnt(6)
	v_add_f32_e32 v139, v139, v221
	s_waitcnt lgkmcnt(5)
	v_add_f32_e32 v140, v140, v222
	s_waitcnt lgkmcnt(4)
	v_add_f32_e32 v141, v141, v223
	s_waitcnt lgkmcnt(3)
	v_add_f32_e32 v142, v142, v224
	s_waitcnt lgkmcnt(2)
	v_add_f32_e32 v143, v143, v225
	s_waitcnt lgkmcnt(1)
	v_add_f32_e32 v144, v144, v226
	s_waitcnt lgkmcnt(0)
	v_add_f32_e32 v145, v145, v227
	ds_bpermute_b32 v220, v171, v138
	ds_bpermute_b32 v221, v171, v139
	ds_bpermute_b32 v222, v171, v140
	ds_bpermute_b32 v223, v171, v141
	ds_bpermute_b32 v224, v171, v142
	ds_bpermute_b32 v225, v171, v143
	ds_bpermute_b32 v226, v171, v144
	ds_bpermute_b32 v227, v171, v145
	s_waitcnt lgkmcnt(7)
	v_add_f32_e32 v138, v138, v220
	s_waitcnt lgkmcnt(6)
	v_add_f32_e32 v139, v139, v221
	s_waitcnt lgkmcnt(5)
	v_add_f32_e32 v140, v140, v222
	s_waitcnt lgkmcnt(4)
	v_add_f32_e32 v141, v141, v223
	s_waitcnt lgkmcnt(3)
	v_add_f32_e32 v142, v142, v224
	s_waitcnt lgkmcnt(2)
	v_add_f32_e32 v143, v143, v225
	s_waitcnt lgkmcnt(1)
	v_add_f32_e32 v144, v144, v226
	s_waitcnt lgkmcnt(0)
	v_add_f32_e32 v145, v145, v227
	ds_bpermute_b32 v220, v172, v138
	ds_bpermute_b32 v221, v172, v139
	ds_bpermute_b32 v222, v172, v140
	ds_bpermute_b32 v223, v172, v141
	ds_bpermute_b32 v224, v172, v142
	ds_bpermute_b32 v225, v172, v143
	ds_bpermute_b32 v226, v172, v144
	ds_bpermute_b32 v227, v172, v145
	s_waitcnt lgkmcnt(7)
	v_add_f32_e32 v138, v138, v220
	s_waitcnt lgkmcnt(6)
	v_add_f32_e32 v139, v139, v221
	s_waitcnt lgkmcnt(5)
	v_add_f32_e32 v140, v140, v222
	s_waitcnt lgkmcnt(4)
	v_add_f32_e32 v141, v141, v223
	s_waitcnt lgkmcnt(3)
	v_add_f32_e32 v142, v142, v224
	s_waitcnt lgkmcnt(2)
	v_add_f32_e32 v143, v143, v225
	s_waitcnt lgkmcnt(1)
	v_add_f32_e32 v144, v144, v226
	s_waitcnt lgkmcnt(0)
	v_add_f32_e32 v145, v145, v227
	ds_bpermute_b32 v220, v173, v138
	ds_bpermute_b32 v221, v173, v139
	ds_bpermute_b32 v222, v173, v140
	ds_bpermute_b32 v223, v173, v141
	ds_bpermute_b32 v224, v173, v142
	ds_bpermute_b32 v225, v173, v143
	ds_bpermute_b32 v226, v173, v144
	ds_bpermute_b32 v227, v173, v145
	s_waitcnt lgkmcnt(7)
	v_add_f32_e32 v138, v138, v220
	s_waitcnt lgkmcnt(6)
	v_add_f32_e32 v139, v139, v221
	s_waitcnt lgkmcnt(5)
	v_add_f32_e32 v140, v140, v222
	s_waitcnt lgkmcnt(4)
	v_add_f32_e32 v141, v141, v223
	s_waitcnt lgkmcnt(3)
	v_add_f32_e32 v142, v142, v224
	s_waitcnt lgkmcnt(2)
	v_add_f32_e32 v143, v143, v225
	s_waitcnt lgkmcnt(1)
	v_add_f32_e32 v144, v144, v226
	s_waitcnt lgkmcnt(0)
	v_add_f32_e32 v145, v145, v227
	v_cmp_eq_u32_e32 vcc, 0, v174
	s_and_saveexec_b64 s[58:59], vcc
	global_store_dword v167, v130, s[10:11]
	global_store_dword v167, v131, s[10:11] offset:4
	global_store_dword v167, v132, s[10:11] offset:8
	global_store_dword v167, v133, s[10:11] offset:12
	global_store_dword v167, v134, s[10:11] offset:32
	global_store_dword v167, v135, s[10:11] offset:36
	global_store_dword v167, v136, s[10:11] offset:40
	global_store_dword v167, v137, s[10:11] offset:44
	global_store_dword v167, v138, s[10:11] offset:64
	global_store_dword v167, v139, s[10:11] offset:68
	global_store_dword v167, v140, s[10:11] offset:72
	global_store_dword v167, v141, s[10:11] offset:76
	global_store_dword v167, v142, s[10:11] offset:96
	global_store_dword v167, v143, s[10:11] offset:100
	global_store_dword v167, v144, s[10:11] offset:104
	global_store_dword v167, v145, s[10:11] offset:108
	s_mov_b64 exec, -1
	s_add_u32 s48, s48, 0x20000
	s_addc_u32 s49, s49, 0
	global_load_dword v130, v162, s[48:49]
	global_load_dword v212, v162, s[48:49] offset:128
	global_load_dword v131, v163, s[48:49]
	global_load_dword v213, v163, s[48:49] offset:128
	global_load_dword v132, v164, s[48:49]
	global_load_dword v214, v164, s[48:49] offset:128
	global_load_dword v133, v165, s[48:49]
	global_load_dword v215, v165, s[48:49] offset:128
	s_add_u32 s48, s48, 0x8000
	s_addc_u32 s49, s49, 0
	global_load_dword v134, v162, s[48:49]
	global_load_dword v216, v162, s[48:49] offset:128
	global_load_dword v135, v163, s[48:49]
	global_load_dword v217, v163, s[48:49] offset:128
	global_load_dword v136, v164, s[48:49]
	global_load_dword v218, v164, s[48:49] offset:128
	global_load_dword v137, v165, s[48:49]
	global_load_dword v219, v165, s[48:49] offset:128
	s_add_u32 s48, s48, 0x8000
	s_addc_u32 s49, s49, 0
	global_load_dword v138, v162, s[48:49]
	global_load_dword v220, v162, s[48:49] offset:128
	global_load_dword v139, v163, s[48:49]
	global_load_dword v221, v163, s[48:49] offset:128
	global_load_dword v140, v164, s[48:49]
	global_load_dword v222, v164, s[48:49] offset:128
	global_load_dword v141, v165, s[48:49]
	global_load_dword v223, v165, s[48:49] offset:128
	s_add_u32 s48, s48, 0x8000
	s_addc_u32 s49, s49, 0
	global_load_dword v142, v162, s[48:49]
	global_load_dword v224, v162, s[48:49] offset:128
	global_load_dword v143, v163, s[48:49]
	global_load_dword v225, v163, s[48:49] offset:128
	global_load_dword v144, v164, s[48:49]
	global_load_dword v226, v164, s[48:49] offset:128
	global_load_dword v145, v165, s[48:49]
	global_load_dword v227, v165, s[48:49] offset:128
	s_sub_u32 s48, s48, 0x18000
	s_subb_u32 s49, s49, 0
	s_waitcnt vmcnt(30)
	v_fmac_f32_e32 v130, v98, v175
	v_fmac_f32_e32 v212, v114, v176
	global_store_dword v162, v130, s[48:49]
	global_store_dword v162, v212, s[48:49] offset:128
	s_waitcnt vmcnt(30)
	v_fmac_f32_e32 v131, v99, v175
	v_fmac_f32_e32 v213, v115, v176
	global_store_dword v163, v131, s[48:49]
	global_store_dword v163, v213, s[48:49] offset:128
	s_waitcnt vmcnt(30)
	v_fmac_f32_e32 v132, v100, v175
	v_fmac_f32_e32 v214, v116, v176
	global_store_dword v164, v132, s[48:49]
	global_store_dword v164, v214, s[48:49] offset:128
	s_waitcnt vmcnt(30)
	v_fmac_f32_e32 v133, v101, v175
	v_fmac_f32_e32 v215, v117, v176
	global_store_dword v165, v133, s[48:49]
	global_store_dword v165, v215, s[48:49] offset:128
	s_add_u32 s48, s48, 0x8000
	s_addc_u32 s49, s49, 0
	s_waitcnt vmcnt(30)
	v_fmac_f32_e32 v134, v102, v175
	v_fmac_f32_e32 v216, v118, v176
	global_store_dword v162, v134, s[48:49]
	global_store_dword v162, v216, s[48:49] offset:128
	s_waitcnt vmcnt(30)
	v_fmac_f32_e32 v135, v103, v175
	v_fmac_f32_e32 v217, v119, v176
	global_store_dword v163, v135, s[48:49]
	global_store_dword v163, v217, s[48:49] offset:128
	s_waitcnt vmcnt(30)
	v_fmac_f32_e32 v136, v104, v175
	v_fmac_f32_e32 v218, v120, v176
	global_store_dword v164, v136, s[48:49]
	global_store_dword v164, v218, s[48:49] offset:128
	s_waitcnt vmcnt(30)
	v_fmac_f32_e32 v137, v105, v175
	v_fmac_f32_e32 v219, v121, v176
	global_store_dword v165, v137, s[48:49]
	global_store_dword v165, v219, s[48:49] offset:128
	s_add_u32 s48, s48, 0x8000
	s_addc_u32 s49, s49, 0
	s_waitcnt vmcnt(30)
	v_fmac_f32_e32 v138, v106, v175
	v_fmac_f32_e32 v220, v122, v176
	global_store_dword v162, v138, s[48:49]
	global_store_dword v162, v220, s[48:49] offset:128
	s_waitcnt vmcnt(30)
	v_fmac_f32_e32 v139, v107, v175
	v_fmac_f32_e32 v221, v123, v176
	global_store_dword v163, v139, s[48:49]
	global_store_dword v163, v221, s[48:49] offset:128
	s_waitcnt vmcnt(30)
	v_fmac_f32_e32 v140, v108, v175
	v_fmac_f32_e32 v222, v124, v176
	global_store_dword v164, v140, s[48:49]
	global_store_dword v164, v222, s[48:49] offset:128
	s_waitcnt vmcnt(30)
	v_fmac_f32_e32 v141, v109, v175
	v_fmac_f32_e32 v223, v125, v176
	global_store_dword v165, v141, s[48:49]
	global_store_dword v165, v223, s[48:49] offset:128
	s_add_u32 s48, s48, 0x8000
	s_addc_u32 s49, s49, 0
	s_waitcnt vmcnt(30)
	v_fmac_f32_e32 v142, v110, v175
	v_fmac_f32_e32 v224, v126, v176
	global_store_dword v162, v142, s[48:49]
	global_store_dword v162, v224, s[48:49] offset:128
	s_waitcnt vmcnt(30)
	v_fmac_f32_e32 v143, v111, v175
	v_fmac_f32_e32 v225, v127, v176
	global_store_dword v163, v143, s[48:49]
	global_store_dword v163, v225, s[48:49] offset:128
	s_waitcnt vmcnt(30)
	v_fmac_f32_e32 v144, v112, v175
	v_fmac_f32_e32 v226, v128, v176
	global_store_dword v164, v144, s[48:49]
	global_store_dword v164, v226, s[48:49] offset:128
	s_waitcnt vmcnt(30)
	v_fmac_f32_e32 v145, v113, v175
	v_fmac_f32_e32 v227, v129, v176
	global_store_dword v165, v145, s[48:49]
	global_store_dword v165, v227, s[48:49] offset:128
	s_sub_u32 s48, s48, 0x18000
	s_subb_u32 s49, s49, 0
	v_mul_f32_e32 v130, v130, v130
	v_fmac_f32_e32 v130, v212, v212
	v_mul_f32_e32 v131, v131, v131
	v_fmac_f32_e32 v131, v213, v213
	v_mul_f32_e32 v132, v132, v132
	v_fmac_f32_e32 v132, v214, v214
	v_mul_f32_e32 v133, v133, v133
	v_fmac_f32_e32 v133, v215, v215
	v_mul_f32_e32 v134, v134, v134
	v_fmac_f32_e32 v134, v216, v216
	v_mul_f32_e32 v135, v135, v135
	v_fmac_f32_e32 v135, v217, v217
	v_mul_f32_e32 v136, v136, v136
	v_fmac_f32_e32 v136, v218, v218
	v_mul_f32_e32 v137, v137, v137
	v_fmac_f32_e32 v137, v219, v219
	v_mul_f32_e32 v138, v138, v138
	v_fmac_f32_e32 v138, v220, v220
	v_mul_f32_e32 v139, v139, v139
	v_fmac_f32_e32 v139, v221, v221
	v_mul_f32_e32 v140, v140, v140
	v_fmac_f32_e32 v140, v222, v222
	v_mul_f32_e32 v141, v141, v141
	v_fmac_f32_e32 v141, v223, v223
	v_mul_f32_e32 v142, v142, v142
	v_fmac_f32_e32 v142, v224, v224
	v_mul_f32_e32 v143, v143, v143
	v_fmac_f32_e32 v143, v225, v225
	v_mul_f32_e32 v144, v144, v144
	v_fmac_f32_e32 v144, v226, v226
	v_mul_f32_e32 v145, v145, v145
	v_fmac_f32_e32 v145, v227, v227
	s_waitcnt lgkmcnt(0)
	ds_bpermute_b32 v212, v168, v130
	ds_bpermute_b32 v213, v168, v131
	ds_bpermute_b32 v214, v168, v132
	ds_bpermute_b32 v215, v168, v133
	ds_bpermute_b32 v216, v168, v134
	ds_bpermute_b32 v217, v168, v135
	ds_bpermute_b32 v218, v168, v136
	ds_bpermute_b32 v219, v168, v137
	s_waitcnt lgkmcnt(7)
	v_add_f32_e32 v130, v130, v212
	s_waitcnt lgkmcnt(6)
	v_add_f32_e32 v131, v131, v213
	s_waitcnt lgkmcnt(5)
	v_add_f32_e32 v132, v132, v214
	s_waitcnt lgkmcnt(4)
	v_add_f32_e32 v133, v133, v215
	s_waitcnt lgkmcnt(3)
	v_add_f32_e32 v134, v134, v216
	s_waitcnt lgkmcnt(2)
	v_add_f32_e32 v135, v135, v217
	s_waitcnt lgkmcnt(1)
	v_add_f32_e32 v136, v136, v218
	s_waitcnt lgkmcnt(0)
	v_add_f32_e32 v137, v137, v219
	ds_bpermute_b32 v212, v169, v130
	ds_bpermute_b32 v213, v169, v131
	ds_bpermute_b32 v214, v169, v132
	ds_bpermute_b32 v215, v169, v133
	ds_bpermute_b32 v216, v169, v134
	ds_bpermute_b32 v217, v169, v135
	ds_bpermute_b32 v218, v169, v136
	ds_bpermute_b32 v219, v169, v137
	s_waitcnt lgkmcnt(7)
	v_add_f32_e32 v130, v130, v212
	s_waitcnt lgkmcnt(6)
	v_add_f32_e32 v131, v131, v213
	s_waitcnt lgkmcnt(5)
	v_add_f32_e32 v132, v132, v214
	s_waitcnt lgkmcnt(4)
	v_add_f32_e32 v133, v133, v215
	s_waitcnt lgkmcnt(3)
	v_add_f32_e32 v134, v134, v216
	s_waitcnt lgkmcnt(2)
	v_add_f32_e32 v135, v135, v217
	s_waitcnt lgkmcnt(1)
	v_add_f32_e32 v136, v136, v218
	s_waitcnt lgkmcnt(0)
	v_add_f32_e32 v137, v137, v219
	ds_bpermute_b32 v212, v171, v130
	ds_bpermute_b32 v213, v171, v131
	ds_bpermute_b32 v214, v171, v132
	ds_bpermute_b32 v215, v171, v133
	ds_bpermute_b32 v216, v171, v134
	ds_bpermute_b32 v217, v171, v135
	ds_bpermute_b32 v218, v171, v136
	ds_bpermute_b32 v219, v171, v137
	s_waitcnt lgkmcnt(7)
	v_add_f32_e32 v130, v130, v212
	s_waitcnt lgkmcnt(6)
	v_add_f32_e32 v131, v131, v213
	s_waitcnt lgkmcnt(5)
	v_add_f32_e32 v132, v132, v214
	s_waitcnt lgkmcnt(4)
	v_add_f32_e32 v133, v133, v215
	s_waitcnt lgkmcnt(3)
	v_add_f32_e32 v134, v134, v216
	s_waitcnt lgkmcnt(2)
	v_add_f32_e32 v135, v135, v217
	s_waitcnt lgkmcnt(1)
	v_add_f32_e32 v136, v136, v218
	s_waitcnt lgkmcnt(0)
	v_add_f32_e32 v137, v137, v219
	ds_bpermute_b32 v212, v172, v130
	ds_bpermute_b32 v213, v172, v131
	ds_bpermute_b32 v214, v172, v132
	ds_bpermute_b32 v215, v172, v133
	ds_bpermute_b32 v216, v172, v134
	ds_bpermute_b32 v217, v172, v135
	ds_bpermute_b32 v218, v172, v136
	ds_bpermute_b32 v219, v172, v137
	s_waitcnt lgkmcnt(7)
	v_add_f32_e32 v130, v130, v212
	s_waitcnt lgkmcnt(6)
	v_add_f32_e32 v131, v131, v213
	s_waitcnt lgkmcnt(5)
	v_add_f32_e32 v132, v132, v214
	s_waitcnt lgkmcnt(4)
	v_add_f32_e32 v133, v133, v215
	s_waitcnt lgkmcnt(3)
	v_add_f32_e32 v134, v134, v216
	s_waitcnt lgkmcnt(2)
	v_add_f32_e32 v135, v135, v217
	s_waitcnt lgkmcnt(1)
	v_add_f32_e32 v136, v136, v218
	s_waitcnt lgkmcnt(0)
	v_add_f32_e32 v137, v137, v219
	ds_bpermute_b32 v212, v173, v130
	ds_bpermute_b32 v213, v173, v131
	ds_bpermute_b32 v214, v173, v132
	ds_bpermute_b32 v215, v173, v133
	ds_bpermute_b32 v216, v173, v134
	ds_bpermute_b32 v217, v173, v135
	ds_bpermute_b32 v218, v173, v136
	ds_bpermute_b32 v219, v173, v137
	s_waitcnt lgkmcnt(7)
	v_add_f32_e32 v130, v130, v212
	s_waitcnt lgkmcnt(6)
	v_add_f32_e32 v131, v131, v213
	s_waitcnt lgkmcnt(5)
	v_add_f32_e32 v132, v132, v214
	s_waitcnt lgkmcnt(4)
	v_add_f32_e32 v133, v133, v215
	s_waitcnt lgkmcnt(3)
	v_add_f32_e32 v134, v134, v216
	s_waitcnt lgkmcnt(2)
	v_add_f32_e32 v135, v135, v217
	s_waitcnt lgkmcnt(1)
	v_add_f32_e32 v136, v136, v218
	s_waitcnt lgkmcnt(0)
	v_add_f32_e32 v137, v137, v219
	ds_bpermute_b32 v220, v168, v138
	ds_bpermute_b32 v221, v168, v139
	ds_bpermute_b32 v222, v168, v140
	ds_bpermute_b32 v223, v168, v141
	ds_bpermute_b32 v224, v168, v142
	ds_bpermute_b32 v225, v168, v143
	ds_bpermute_b32 v226, v168, v144
	ds_bpermute_b32 v227, v168, v145
	s_waitcnt lgkmcnt(7)
	v_add_f32_e32 v138, v138, v220
	s_waitcnt lgkmcnt(6)
	v_add_f32_e32 v139, v139, v221
	s_waitcnt lgkmcnt(5)
	v_add_f32_e32 v140, v140, v222
	s_waitcnt lgkmcnt(4)
	v_add_f32_e32 v141, v141, v223
	s_waitcnt lgkmcnt(3)
	v_add_f32_e32 v142, v142, v224
	s_waitcnt lgkmcnt(2)
	v_add_f32_e32 v143, v143, v225
	s_waitcnt lgkmcnt(1)
	v_add_f32_e32 v144, v144, v226
	s_waitcnt lgkmcnt(0)
	v_add_f32_e32 v145, v145, v227
	ds_bpermute_b32 v220, v169, v138
	ds_bpermute_b32 v221, v169, v139
	ds_bpermute_b32 v222, v169, v140
	ds_bpermute_b32 v223, v169, v141
	ds_bpermute_b32 v224, v169, v142
	ds_bpermute_b32 v225, v169, v143
	ds_bpermute_b32 v226, v169, v144
	ds_bpermute_b32 v227, v169, v145
	s_waitcnt lgkmcnt(7)
	v_add_f32_e32 v138, v138, v220
	s_waitcnt lgkmcnt(6)
	v_add_f32_e32 v139, v139, v221
	s_waitcnt lgkmcnt(5)
	v_add_f32_e32 v140, v140, v222
	s_waitcnt lgkmcnt(4)
	v_add_f32_e32 v141, v141, v223
	s_waitcnt lgkmcnt(3)
	v_add_f32_e32 v142, v142, v224
	s_waitcnt lgkmcnt(2)
	v_add_f32_e32 v143, v143, v225
	s_waitcnt lgkmcnt(1)
	v_add_f32_e32 v144, v144, v226
	s_waitcnt lgkmcnt(0)
	v_add_f32_e32 v145, v145, v227
	ds_bpermute_b32 v220, v171, v138
	ds_bpermute_b32 v221, v171, v139
	ds_bpermute_b32 v222, v171, v140
	ds_bpermute_b32 v223, v171, v141
	ds_bpermute_b32 v224, v171, v142
	ds_bpermute_b32 v225, v171, v143
	ds_bpermute_b32 v226, v171, v144
	ds_bpermute_b32 v227, v171, v145
	s_waitcnt lgkmcnt(7)
	v_add_f32_e32 v138, v138, v220
	s_waitcnt lgkmcnt(6)
	v_add_f32_e32 v139, v139, v221
	s_waitcnt lgkmcnt(5)
	v_add_f32_e32 v140, v140, v222
	s_waitcnt lgkmcnt(4)
	v_add_f32_e32 v141, v141, v223
	s_waitcnt lgkmcnt(3)
	v_add_f32_e32 v142, v142, v224
	s_waitcnt lgkmcnt(2)
	v_add_f32_e32 v143, v143, v225
	s_waitcnt lgkmcnt(1)
	v_add_f32_e32 v144, v144, v226
	s_waitcnt lgkmcnt(0)
	v_add_f32_e32 v145, v145, v227
	ds_bpermute_b32 v220, v172, v138
	ds_bpermute_b32 v221, v172, v139
	ds_bpermute_b32 v222, v172, v140
	ds_bpermute_b32 v223, v172, v141
	ds_bpermute_b32 v224, v172, v142
	ds_bpermute_b32 v225, v172, v143
	ds_bpermute_b32 v226, v172, v144
	ds_bpermute_b32 v227, v172, v145
	s_waitcnt lgkmcnt(7)
	v_add_f32_e32 v138, v138, v220
	s_waitcnt lgkmcnt(6)
	v_add_f32_e32 v139, v139, v221
	s_waitcnt lgkmcnt(5)
	v_add_f32_e32 v140, v140, v222
	s_waitcnt lgkmcnt(4)
	v_add_f32_e32 v141, v141, v223
	s_waitcnt lgkmcnt(3)
	v_add_f32_e32 v142, v142, v224
	s_waitcnt lgkmcnt(2)
	v_add_f32_e32 v143, v143, v225
	s_waitcnt lgkmcnt(1)
	v_add_f32_e32 v144, v144, v226
	s_waitcnt lgkmcnt(0)
	v_add_f32_e32 v145, v145, v227
	ds_bpermute_b32 v220, v173, v138
	ds_bpermute_b32 v221, v173, v139
	ds_bpermute_b32 v222, v173, v140
	ds_bpermute_b32 v223, v173, v141
	ds_bpermute_b32 v224, v173, v142
	ds_bpermute_b32 v225, v173, v143
	ds_bpermute_b32 v226, v173, v144
	ds_bpermute_b32 v227, v173, v145
	s_waitcnt lgkmcnt(7)
	v_add_f32_e32 v138, v138, v220
	s_waitcnt lgkmcnt(6)
	v_add_f32_e32 v139, v139, v221
	s_waitcnt lgkmcnt(5)
	v_add_f32_e32 v140, v140, v222
	s_waitcnt lgkmcnt(4)
	v_add_f32_e32 v141, v141, v223
	s_waitcnt lgkmcnt(3)
	v_add_f32_e32 v142, v142, v224
	s_waitcnt lgkmcnt(2)
	v_add_f32_e32 v143, v143, v225
	s_waitcnt lgkmcnt(1)
	v_add_f32_e32 v144, v144, v226
	s_waitcnt lgkmcnt(0)
	v_add_f32_e32 v145, v145, v227
	v_cmp_eq_u32_e32 vcc, 0, v174
	s_and_saveexec_b64 s[58:59], vcc
	global_store_dword v167, v130, s[10:11] offset:128
	global_store_dword v167, v131, s[10:11] offset:132
	global_store_dword v167, v132, s[10:11] offset:136
	global_store_dword v167, v133, s[10:11] offset:140
	global_store_dword v167, v134, s[10:11] offset:160
	global_store_dword v167, v135, s[10:11] offset:164
	global_store_dword v167, v136, s[10:11] offset:168
	global_store_dword v167, v137, s[10:11] offset:172
	global_store_dword v167, v138, s[10:11] offset:192
	global_store_dword v167, v139, s[10:11] offset:196
	global_store_dword v167, v140, s[10:11] offset:200
	global_store_dword v167, v141, s[10:11] offset:204
	global_store_dword v167, v142, s[10:11] offset:224
	global_store_dword v167, v143, s[10:11] offset:228
	global_store_dword v167, v144, s[10:11] offset:232
	global_store_dword v167, v145, s[10:11] offset:236
	s_mov_b64 exec, -1
	s_sub_u32 s48, s48, 0x20000
	s_subb_u32 s49, s49, 0
	v_readlane_b32 s2, v246, 14
	s_nop 0
	s_add_i32 s16, s16, s2
	s_branch .Lhw_ffndown_tloop

.Lhw_ffnup_dloop:
	s_cmp_ge_u32 s2, s64
	s_cbranch_scc1 .Lhw_ffnup_tail
	s_mul_i32 s6, s2, 745
	s_lshr_b32 s6, s6, 16
	s_mul_i32 s14, s6, 88
	s_sub_i32 s14, s2, s14
	v_readlane_b32 s13, v246, 16
	s_lshl_b32 s6, s6, 2
	s_and_b32 s12, s14, 3
	s_add_i32 s6, s6, s12
	s_add_i32 s6, s6, s13
	s_lshl_b32 s6, s6, 7
	s_lshr_b32 s14, s14, 2
	s_lshl_b32 s14, s14, 8
	s_lshl_b32 vcc_lo, s6, 11
	s_add_u32 s66, s10, vcc_lo
	s_addc_u32 s67, s11, 0
	s_lshl_b32 vcc_lo, s14, 11
	s_add_u32 s12, s0, vcc_lo
	s_addc_u32 s13, s1, 0
	s_add_u32 s62, s12, 0x40000
	s_addc_u32 s63, s13, 0
	s_barrier
	s_sub_u32 s66, s66, 64
	s_subb_u32 s67, s67, 0
	s_sub_u32 s12, s12, 64
	s_subb_u32 s13, s13, 0
	s_sub_u32 s62, s62, 64
	s_subb_u32 s63, s63, 0
	s_add_u32 m0, s65, 0x0
	s_nop 0
	global_load_lds_dwordx4 v166, s[66:67]
	s_add_u32 m0, s65, 0x1000
	s_nop 0
	global_load_lds_dwordx4 v167, s[66:67]
	s_add_u32 m0, s65, 0x2000
	s_nop 0
	global_load_lds_dwordx4 v166, s[12:13]
	s_add_u32 m0, s65, 0x3000
	s_nop 0
	global_load_lds_dwordx4 v167, s[12:13]
	s_add_u32 m0, s65, 0x4000
	s_nop 0
	global_load_lds_dwordx4 v166, s[62:63]
	s_add_u32 m0, s65, 0x5000
	s_nop 0
	global_load_lds_dwordx4 v167, s[62:63]
	s_add_u32 s66, s66, 64
	s_addc_u32 s67, s67, 0
	s_add_u32 s12, s12, 64
	s_addc_u32 s13, s13, 0
	s_add_u32 s62, s62, 64
	s_addc_u32 s63, s63, 0
	s_add_u32 m0, s65, 0x6000
	s_nop 0
	global_load_lds_dwordx4 v249, s[66:67]
	s_add_u32 m0, s65, 0x7000
	s_nop 0
	global_load_lds_dwordx4 v254, s[66:67]
	s_add_u32 m0, s65, 0x8000
	s_nop 0
	global_load_lds_dwordx4 v249, s[12:13]
	s_add_u32 m0, s65, 0x9000
	s_nop 0
	global_load_lds_dwordx4 v254, s[12:13]
	s_add_u32 m0, s65, 0xa000
	s_nop 0
	global_load_lds_dwordx4 v249, s[62:63]
	s_add_u32 m0, s65, 0xb000
	s_nop 0
	global_load_lds_dwordx4 v254, s[62:63]
	s_add_u32 s66, s66, 64
	s_addc_u32 s67, s67, 0
	s_add_u32 s12, s12, 64
	s_addc_u32 s13, s13, 0
	s_add_u32 s62, s62, 64
	s_addc_u32 s63, s63, 0
	s_add_u32 m0, s65, 0xc000
	s_nop 0
	global_load_lds_dwordx4 v166, s[66:67]
	s_add_u32 m0, s65, 0xd000
	s_nop 0
	global_load_lds_dwordx4 v167, s[66:67]
	s_add_u32 m0, s65, 0xe000
	s_nop 0
	global_load_lds_dwordx4 v166, s[12:13]
	s_add_u32 m0, s65, 0xf000
	s_nop 0
	global_load_lds_dwordx4 v167, s[12:13]
	s_add_u32 m0, s65, 0x10000
	s_nop 0
	global_load_lds_dwordx4 v166, s[62:63]
	s_add_u32 m0, s65, 0x11000
	s_nop 0
	global_load_lds_dwordx4 v167, s[62:63]
	s_add_u32 s66, s66, 64
	s_addc_u32 s67, s67, 0
	s_add_u32 s12, s12, 64
	s_addc_u32 s13, s13, 0
	s_add_u32 s62, s62, 64
	s_addc_u32 s63, s63, 0
	v_mov_b32_e32 v2, 0
	v_mov_b32_e32 v3, 0
	v_mov_b32_e32 v4, 0
	v_mov_b32_e32 v5, 0
	v_mov_b32_e32 v6, 0
	v_mov_b32_e32 v7, 0
	v_mov_b32_e32 v8, 0
	v_mov_b32_e32 v9, 0
	v_mov_b32_e32 v10, 0
	v_mov_b32_e32 v11, 0
	v_mov_b32_e32 v12, 0
	v_mov_b32_e32 v13, 0
	v_mov_b32_e32 v14, 0
	v_mov_b32_e32 v15, 0
	v_mov_b32_e32 v16, 0
	v_mov_b32_e32 v17, 0
	v_mov_b32_e32 v18, 0
	v_mov_b32_e32 v19, 0
	v_mov_b32_e32 v20, 0
	v_mov_b32_e32 v21, 0
	v_mov_b32_e32 v22, 0
	v_mov_b32_e32 v23, 0
	v_mov_b32_e32 v24, 0
	v_mov_b32_e32 v25, 0
	v_mov_b32_e32 v26, 0
	v_mov_b32_e32 v27, 0
	v_mov_b32_e32 v28, 0
	v_mov_b32_e32 v29, 0
	v_mov_b32_e32 v30, 0
	v_mov_b32_e32 v31, 0
	v_mov_b32_e32 v32, 0
	v_mov_b32_e32 v33, 0
	v_mov_b32_e32 v34, 0
	v_mov_b32_e32 v35, 0
	v_mov_b32_e32 v36, 0
	v_mov_b32_e32 v37, 0
	v_mov_b32_e32 v38, 0
	v_mov_b32_e32 v39, 0
	v_mov_b32_e32 v40, 0
	v_mov_b32_e32 v41, 0
	v_mov_b32_e32 v42, 0
	v_mov_b32_e32 v43, 0
	v_mov_b32_e32 v44, 0
	v_mov_b32_e32 v45, 0
	v_mov_b32_e32 v46, 0
	v_mov_b32_e32 v47, 0
	v_mov_b32_e32 v48, 0
	v_mov_b32_e32 v49, 0
	v_mov_b32_e32 v50, 0
	v_mov_b32_e32 v51, 0
	v_mov_b32_e32 v52, 0
	v_mov_b32_e32 v53, 0
	v_mov_b32_e32 v54, 0
	v_mov_b32_e32 v55, 0
	v_mov_b32_e32 v56, 0
	v_mov_b32_e32 v57, 0
	v_mov_b32_e32 v58, 0
	v_mov_b32_e32 v59, 0
	v_mov_b32_e32 v60, 0
	v_mov_b32_e32 v61, 0
	v_mov_b32_e32 v62, 0
	v_mov_b32_e32 v63, 0
	v_mov_b32_e32 v64, 0
	v_mov_b32_e32 v65, 0
	v_mov_b32_e32 v66, 0
	v_mov_b32_e32 v67, 0
	v_mov_b32_e32 v68, 0
	v_mov_b32_e32 v69, 0
	v_mov_b32_e32 v70, 0
	v_mov_b32_e32 v71, 0
	v_mov_b32_e32 v72, 0
	v_mov_b32_e32 v73, 0
	v_mov_b32_e32 v74, 0
	v_mov_b32_e32 v75, 0
	v_mov_b32_e32 v76, 0
	v_mov_b32_e32 v77, 0
	v_mov_b32_e32 v78, 0
	v_mov_b32_e32 v79, 0
	v_mov_b32_e32 v80, 0
	v_mov_b32_e32 v81, 0
	v_mov_b32_e32 v82, 0
	v_mov_b32_e32 v83, 0
	v_mov_b32_e32 v84, 0
	v_mov_b32_e32 v85, 0
	v_mov_b32_e32 v86, 0
	v_mov_b32_e32 v87, 0
	v_mov_b32_e32 v88, 0
	v_mov_b32_e32 v89, 0
	v_mov_b32_e32 v90, 0
	v_mov_b32_e32 v91, 0
	v_mov_b32_e32 v92, 0
	v_mov_b32_e32 v93, 0
	v_mov_b32_e32 v94, 0
	v_mov_b32_e32 v95, 0
	v_mov_b32_e32 v96, 0
	v_mov_b32_e32 v97, 0
	v_mov_b32_e32 v98, 0
	v_mov_b32_e32 v99, 0
	v_mov_b32_e32 v100, 0
	v_mov_b32_e32 v101, 0
	v_mov_b32_e32 v102, 0
	v_mov_b32_e32 v103, 0
	v_mov_b32_e32 v104, 0
	v_mov_b32_e32 v105, 0
	v_mov_b32_e32 v106, 0
	v_mov_b32_e32 v107, 0
	v_mov_b32_e32 v108, 0
	v_mov_b32_e32 v109, 0
	v_mov_b32_e32 v110, 0
	v_mov_b32_e32 v111, 0
	v_mov_b32_e32 v112, 0
	v_mov_b32_e32 v113, 0
	v_mov_b32_e32 v114, 0
	v_mov_b32_e32 v115, 0
	v_mov_b32_e32 v116, 0
	v_mov_b32_e32 v117, 0
	v_mov_b32_e32 v118, 0
	v_mov_b32_e32 v119, 0
	v_mov_b32_e32 v120, 0
	v_mov_b32_e32 v121, 0
	v_mov_b32_e32 v122, 0
	v_mov_b32_e32 v123, 0
	v_mov_b32_e32 v124, 0
	v_mov_b32_e32 v125, 0
	v_mov_b32_e32 v126, 0
	v_mov_b32_e32 v127, 0
	v_mov_b32_e32 v128, 0
	v_mov_b32_e32 v129, 0
	s_waitcnt vmcnt(6)
	s_barrier
	ds_read_b128 v[130:133], v168 offset:24592
	ds_read_b128 v[138:141], v238 offset:32784
	ds_read_b128 v[146:149], v242 offset:24592
	ds_read_b128 v[134:137], v169 offset:16
	ds_read_b128 v[142:145], v239 offset:8208
	ds_read_b128 v[150:153], v243 offset:16
	s_mov_b32 s59, 5
.Lhw_ffnup_d_loop:
	s_waitcnt lgkmcnt(4)
	v_mfma_f32_32x32x16_bf16 v[2:17], v[130:133], v[138:141], v[2:17]
	ds_read_b128 v[212:215], v236 offset:24592
	s_waitcnt lgkmcnt(2)
	v_mfma_f32_32x32x16_bf16 v[18:33], v[130:133], v[142:145], v[18:33]
	ds_read_b128 v[220:223], v240 offset:32784
	v_mfma_f32_32x32x16_bf16 v[34:49], v[134:137], v[138:141], v[34:49]
	ds_read_b128 v[228:231], v244 offset:24592
	v_mfma_f32_32x32x16_bf16 v[50:65], v[134:137], v[142:145], v[50:65]
	ds_read_b128 v[216:219], v237 offset:16
	v_mfma_f32_32x32x16_bf16 v[66:81], v[130:133], v[146:149], v[66:81]
	ds_read_b128 v[224:227], v241 offset:8208
	s_waitcnt lgkmcnt(5)
	v_mfma_f32_32x32x16_bf16 v[82:97], v[130:133], v[150:153], v[82:97]
	ds_read_b128 v[232:235], v245 offset:16
	v_mfma_f32_32x32x16_bf16 v[98:113], v[134:137], v[146:149], v[98:113]
	v_mfma_f32_32x32x16_bf16 v[114:129], v[134:137], v[150:153], v[114:129]
	s_waitcnt vmcnt(0) lgkmcnt(0)
	s_barrier
	v_mfma_f32_32x32x16_bf16 v[2:17], v[212:215], v[220:223], v[2:17]
	s_add_u32 m0, s65, 0x0
	ds_read_b128 v[130:133], v169 offset:24592
	global_load_lds_dwordx4 v249, s[66:67]
	v_mfma_f32_32x32x16_bf16 v[18:33], v[212:215], v[224:227], v[18:33]
	s_add_u32 m0, s65, 0x1000
	ds_read_b128 v[138:141], v239 offset:32784
	global_load_lds_dwordx4 v254, s[66:67]
	v_mfma_f32_32x32x16_bf16 v[34:49], v[216:219], v[220:223], v[34:49]
	s_add_u32 m0, s65, 0x2000
	ds_read_b128 v[146:149], v243 offset:24592
	global_load_lds_dwordx4 v249, s[12:13]
	v_mfma_f32_32x32x16_bf16 v[50:65], v[216:219], v[224:227], v[50:65]
	s_add_u32 m0, s65, 0x3000
	ds_read_b128 v[134:137], v168 offset:49168
	global_load_lds_dwordx4 v254, s[12:13]
	v_mfma_f32_32x32x16_bf16 v[66:81], v[212:215], v[228:231], v[66:81]
	s_add_u32 m0, s65, 0x4000
	ds_read_b128 v[142:145], v238 offset:57360
	global_load_lds_dwordx4 v249, s[62:63]
	v_mfma_f32_32x32x16_bf16 v[82:97], v[212:215], v[232:235], v[82:97]
	s_add_u32 m0, s65, 0x5000
	ds_read_b128 v[150:153], v242 offset:49168
	global_load_lds_dwordx4 v254, s[62:63]
	v_mfma_f32_32x32x16_bf16 v[98:113], v[216:219], v[228:231], v[98:113]
	s_add_u32 s66, s66, 64
	s_addc_u32 s67, s67, 0
	s_add_u32 s12, s12, 64
	s_addc_u32 s13, s13, 0
	v_mfma_f32_32x32x16_bf16 v[114:129], v[216:219], v[232:235], v[114:129]
	s_add_u32 s62, s62, 64
	s_addc_u32 s63, s63, 0
	s_waitcnt lgkmcnt(4)
	v_mfma_f32_32x32x16_bf16 v[2:17], v[130:133], v[138:141], v[2:17]
	ds_read_b128 v[212:215], v237 offset:24592
	s_waitcnt lgkmcnt(2)
	v_mfma_f32_32x32x16_bf16 v[18:33], v[130:133], v[142:145], v[18:33]
	ds_read_b128 v[220:223], v241 offset:32784
	v_mfma_f32_32x32x16_bf16 v[34:49], v[134:137], v[138:141], v[34:49]
	ds_read_b128 v[228:231], v245 offset:24592
	v_mfma_f32_32x32x16_bf16 v[50:65], v[134:137], v[142:145], v[50:65]
	ds_read_b128 v[216:219], v236 offset:49168
	v_mfma_f32_32x32x16_bf16 v[66:81], v[130:133], v[146:149], v[66:81]
	ds_read_b128 v[224:227], v240 offset:57360
	s_waitcnt lgkmcnt(5)
	v_mfma_f32_32x32x16_bf16 v[82:97], v[130:133], v[150:153], v[82:97]
	ds_read_b128 v[232:235], v244 offset:49168
	v_mfma_f32_32x32x16_bf16 v[98:113], v[134:137], v[146:149], v[98:113]
	v_mfma_f32_32x32x16_bf16 v[114:129], v[134:137], v[150:153], v[114:129]
	s_waitcnt vmcnt(0) lgkmcnt(0)
	s_barrier
	v_mfma_f32_32x32x16_bf16 v[2:17], v[212:215], v[220:223], v[2:17]
	s_add_u32 m0, s65, 0x6000
	ds_read_b128 v[130:133], v168 offset:16
	global_load_lds_dwordx4 v166, s[66:67]
	v_mfma_f32_32x32x16_bf16 v[18:33], v[212:215], v[224:227], v[18:33]
	s_add_u32 m0, s65, 0x7000
	ds_read_b128 v[138:141], v238 offset:8208
	global_load_lds_dwordx4 v167, s[66:67]
	v_mfma_f32_32x32x16_bf16 v[34:49], v[216:219], v[220:223], v[34:49]
	s_add_u32 m0, s65, 0x8000
	ds_read_b128 v[146:149], v242 offset:16
	global_load_lds_dwordx4 v166, s[12:13]
	v_mfma_f32_32x32x16_bf16 v[50:65], v[216:219], v[224:227], v[50:65]
	s_add_u32 m0, s65, 0x9000
	ds_read_b128 v[134:137], v169 offset:49168
	global_load_lds_dwordx4 v167, s[12:13]
	v_mfma_f32_32x32x16_bf16 v[66:81], v[212:215], v[228:231], v[66:81]
	s_add_u32 m0, s65, 0xa000
	ds_read_b128 v[142:145], v239 offset:57360
	global_load_lds_dwordx4 v166, s[62:63]
	v_mfma_f32_32x32x16_bf16 v[82:97], v[212:215], v[232:235], v[82:97]
	s_add_u32 m0, s65, 0xb000
	ds_read_b128 v[150:153], v243 offset:49168
	global_load_lds_dwordx4 v167, s[62:63]
	v_mfma_f32_32x32x16_bf16 v[98:113], v[216:219], v[228:231], v[98:113]
	s_add_u32 s66, s66, 64
	s_addc_u32 s67, s67, 0
	s_add_u32 s12, s12, 64
	s_addc_u32 s13, s13, 0
	v_mfma_f32_32x32x16_bf16 v[114:129], v[216:219], v[232:235], v[114:129]
	s_add_u32 s62, s62, 64
	s_addc_u32 s63, s63, 0
	s_waitcnt lgkmcnt(4)
	v_mfma_f32_32x32x16_bf16 v[2:17], v[130:133], v[138:141], v[2:17]
	ds_read_b128 v[212:215], v236 offset:16
	s_waitcnt lgkmcnt(2)
	v_mfma_f32_32x32x16_bf16 v[18:33], v[130:133], v[142:145], v[18:33]
	ds_read_b128 v[220:223], v240 offset:8208
	v_mfma_f32_32x32x16_bf16 v[34:49], v[134:137], v[138:141], v[34:49]
	ds_read_b128 v[228:231], v244 offset:16
	v_mfma_f32_32x32x16_bf16 v[50:65], v[134:137], v[142:145], v[50:65]
	ds_read_b128 v[216:219], v237 offset:49168
	v_mfma_f32_32x32x16_bf16 v[66:81], v[130:133], v[146:149], v[66:81]
	ds_read_b128 v[224:227], v241 offset:57360
	s_waitcnt lgkmcnt(5)
	v_mfma_f32_32x32x16_bf16 v[82:97], v[130:133], v[150:153], v[82:97]
	ds_read_b128 v[232:235], v245 offset:49168
	v_mfma_f32_32x32x16_bf16 v[98:113], v[134:137], v[146:149], v[98:113]
	v_mfma_f32_32x32x16_bf16 v[114:129], v[134:137], v[150:153], v[114:129]
	s_waitcnt vmcnt(0) lgkmcnt(0)
	s_barrier
	v_mfma_f32_32x32x16_bf16 v[2:17], v[212:215], v[220:223], v[2:17]
	s_add_u32 m0, s65, 0xc000
	ds_read_b128 v[130:133], v169 offset:16
	global_load_lds_dwordx4 v249, s[66:67]
	v_mfma_f32_32x32x16_bf16 v[18:33], v[212:215], v[224:227], v[18:33]
	s_add_u32 m0, s65, 0xd000
	ds_read_b128 v[138:141], v239 offset:8208
	global_load_lds_dwordx4 v254, s[66:67]
	v_mfma_f32_32x32x16_bf16 v[34:49], v[216:219], v[220:223], v[34:49]
	s_add_u32 m0, s65, 0xe000
	ds_read_b128 v[146:149], v243 offset:16
	global_load_lds_dwordx4 v249, s[12:13]
	v_mfma_f32_32x32x16_bf16 v[50:65], v[216:219], v[224:227], v[50:65]
	s_add_u32 m0, s65, 0xf000
	ds_read_b128 v[134:137], v168 offset:24592
	global_load_lds_dwordx4 v254, s[12:13]
	v_mfma_f32_32x32x16_bf16 v[66:81], v[212:215], v[228:231], v[66:81]
	s_add_u32 m0, s65, 0x10000
	ds_read_b128 v[142:145], v238 offset:32784
	global_load_lds_dwordx4 v249, s[62:63]
	v_mfma_f32_32x32x16_bf16 v[82:97], v[212:215], v[232:235], v[82:97]
	s_add_u32 m0, s65, 0x11000
	ds_read_b128 v[150:153], v242 offset:24592
	global_load_lds_dwordx4 v254, s[62:63]
	v_mfma_f32_32x32x16_bf16 v[98:113], v[216:219], v[228:231], v[98:113]
	s_add_u32 s66, s66, 64
	s_addc_u32 s67, s67, 0
	s_add_u32 s12, s12, 64
	s_addc_u32 s13, s13, 0
	v_mfma_f32_32x32x16_bf16 v[114:129], v[216:219], v[232:235], v[114:129]
	s_add_u32 s62, s62, 64
	s_addc_u32 s63, s63, 0
	s_waitcnt lgkmcnt(4)
	v_mfma_f32_32x32x16_bf16 v[2:17], v[130:133], v[138:141], v[2:17]
	ds_read_b128 v[212:215], v237 offset:16
	s_waitcnt lgkmcnt(2)
	v_mfma_f32_32x32x16_bf16 v[18:33], v[130:133], v[142:145], v[18:33]
	ds_read_b128 v[220:223], v241 offset:8208
	v_mfma_f32_32x32x16_bf16 v[34:49], v[134:137], v[138:141], v[34:49]
	ds_read_b128 v[228:231], v245 offset:16
	v_mfma_f32_32x32x16_bf16 v[50:65], v[134:137], v[142:145], v[50:65]
	ds_read_b128 v[216:219], v236 offset:24592
	v_mfma_f32_32x32x16_bf16 v[66:81], v[130:133], v[146:149], v[66:81]
	ds_read_b128 v[224:227], v240 offset:32784
	s_waitcnt lgkmcnt(5)
	v_mfma_f32_32x32x16_bf16 v[82:97], v[130:133], v[150:153], v[82:97]
	ds_read_b128 v[232:235], v244 offset:24592
	v_mfma_f32_32x32x16_bf16 v[98:113], v[134:137], v[146:149], v[98:113]
	v_mfma_f32_32x32x16_bf16 v[114:129], v[134:137], v[150:153], v[114:129]
	s_waitcnt vmcnt(0) lgkmcnt(0)
	s_barrier
	v_mfma_f32_32x32x16_bf16 v[2:17], v[212:215], v[220:223], v[2:17]
	s_add_u32 m0, s65, 0x0
	ds_read_b128 v[130:133], v168 offset:49168
	global_load_lds_dwordx4 v166, s[66:67]
	v_mfma_f32_32x32x16_bf16 v[18:33], v[212:215], v[224:227], v[18:33]
	s_add_u32 m0, s65, 0x1000
	ds_read_b128 v[138:141], v238 offset:57360
	global_load_lds_dwordx4 v167, s[66:67]
	v_mfma_f32_32x32x16_bf16 v[34:49], v[216:219], v[220:223], v[34:49]
	s_add_u32 m0, s65, 0x2000
	ds_read_b128 v[146:149], v242 offset:49168
	global_load_lds_dwordx4 v166, s[12:13]
	v_mfma_f32_32x32x16_bf16 v[50:65], v[216:219], v[224:227], v[50:65]
	s_add_u32 m0, s65, 0x3000
	ds_read_b128 v[134:137], v169 offset:24592
	global_load_lds_dwordx4 v167, s[12:13]
	v_mfma_f32_32x32x16_bf16 v[66:81], v[212:215], v[228:231], v[66:81]
	s_add_u32 m0, s65, 0x4000
	ds_read_b128 v[142:145], v239 offset:32784
	global_load_lds_dwordx4 v166, s[62:63]
	v_mfma_f32_32x32x16_bf16 v[82:97], v[212:215], v[232:235], v[82:97]
	s_add_u32 m0, s65, 0x5000
	ds_read_b128 v[150:153], v243 offset:24592
	global_load_lds_dwordx4 v167, s[62:63]
	v_mfma_f32_32x32x16_bf16 v[98:113], v[216:219], v[228:231], v[98:113]
	s_add_u32 s66, s66, 64
	s_addc_u32 s67, s67, 0
	s_add_u32 s12, s12, 64
	s_addc_u32 s13, s13, 0
	v_mfma_f32_32x32x16_bf16 v[114:129], v[216:219], v[232:235], v[114:129]
	s_add_u32 s62, s62, 64
	s_addc_u32 s63, s63, 0
	s_waitcnt lgkmcnt(4)
	v_mfma_f32_32x32x16_bf16 v[2:17], v[130:133], v[138:141], v[2:17]
	ds_read_b128 v[212:215], v236 offset:49168
	s_waitcnt lgkmcnt(2)
	v_mfma_f32_32x32x16_bf16 v[18:33], v[130:133], v[142:145], v[18:33]
	ds_read_b128 v[220:223], v240 offset:57360
	v_mfma_f32_32x32x16_bf16 v[34:49], v[134:137], v[138:141], v[34:49]
	ds_read_b128 v[228:231], v244 offset:49168
	v_mfma_f32_32x32x16_bf16 v[50:65], v[134:137], v[142:145], v[50:65]
	ds_read_b128 v[216:219], v237 offset:24592
	v_mfma_f32_32x32x16_bf16 v[66:81], v[130:133], v[146:149], v[66:81]
	ds_read_b128 v[224:227], v241 offset:32784
	s_waitcnt lgkmcnt(5)
	v_mfma_f32_32x32x16_bf16 v[82:97], v[130:133], v[150:153], v[82:97]
	ds_read_b128 v[232:235], v245 offset:24592
	v_mfma_f32_32x32x16_bf16 v[98:113], v[134:137], v[146:149], v[98:113]
	v_mfma_f32_32x32x16_bf16 v[114:129], v[134:137], v[150:153], v[114:129]
	s_waitcnt vmcnt(0) lgkmcnt(0)
	s_barrier
	v_mfma_f32_32x32x16_bf16 v[2:17], v[212:215], v[220:223], v[2:17]
	s_add_u32 m0, s65, 0x6000
	ds_read_b128 v[130:133], v169 offset:49168
	global_load_lds_dwordx4 v249, s[66:67]
	v_mfma_f32_32x32x16_bf16 v[18:33], v[212:215], v[224:227], v[18:33]
	s_add_u32 m0, s65, 0x7000
	ds_read_b128 v[138:141], v239 offset:57360
	global_load_lds_dwordx4 v254, s[66:67]
	v_mfma_f32_32x32x16_bf16 v[34:49], v[216:219], v[220:223], v[34:49]
	s_add_u32 m0, s65, 0x8000
	ds_read_b128 v[146:149], v243 offset:49168
	global_load_lds_dwordx4 v249, s[12:13]
	v_mfma_f32_32x32x16_bf16 v[50:65], v[216:219], v[224:227], v[50:65]
	s_add_u32 m0, s65, 0x9000
	ds_read_b128 v[134:137], v168 offset:16
	global_load_lds_dwordx4 v254, s[12:13]
	v_mfma_f32_32x32x16_bf16 v[66:81], v[212:215], v[228:231], v[66:81]
	s_add_u32 m0, s65, 0xa000
	ds_read_b128 v[142:145], v238 offset:8208
	global_load_lds_dwordx4 v249, s[62:63]
	v_mfma_f32_32x32x16_bf16 v[82:97], v[212:215], v[232:235], v[82:97]
	s_add_u32 m0, s65, 0xb000
	ds_read_b128 v[150:153], v242 offset:16
	global_load_lds_dwordx4 v254, s[62:63]
	v_mfma_f32_32x32x16_bf16 v[98:113], v[216:219], v[228:231], v[98:113]
	s_add_u32 s66, s66, 64
	s_addc_u32 s67, s67, 0
	s_add_u32 s12, s12, 64
	s_addc_u32 s13, s13, 0
	v_mfma_f32_32x32x16_bf16 v[114:129], v[216:219], v[232:235], v[114:129]
	s_add_u32 s62, s62, 64
	s_addc_u32 s63, s63, 0
	s_waitcnt lgkmcnt(4)
	v_mfma_f32_32x32x16_bf16 v[2:17], v[130:133], v[138:141], v[2:17]
	ds_read_b128 v[212:215], v237 offset:49168
	s_waitcnt lgkmcnt(2)
	v_mfma_f32_32x32x16_bf16 v[18:33], v[130:133], v[142:145], v[18:33]
	ds_read_b128 v[220:223], v241 offset:57360
	v_mfma_f32_32x32x16_bf16 v[34:49], v[134:137], v[138:141], v[34:49]
	ds_read_b128 v[228:231], v245 offset:49168
	v_mfma_f32_32x32x16_bf16 v[50:65], v[134:137], v[142:145], v[50:65]
	ds_read_b128 v[216:219], v236 offset:16
	v_mfma_f32_32x32x16_bf16 v[66:81], v[130:133], v[146:149], v[66:81]
	ds_read_b128 v[224:227], v240 offset:8208
	s_waitcnt lgkmcnt(5)
	v_mfma_f32_32x32x16_bf16 v[82:97], v[130:133], v[150:153], v[82:97]
	ds_read_b128 v[232:235], v244 offset:16
	v_mfma_f32_32x32x16_bf16 v[98:113], v[134:137], v[146:149], v[98:113]
	v_mfma_f32_32x32x16_bf16 v[114:129], v[134:137], v[150:153], v[114:129]
	s_waitcnt vmcnt(0) lgkmcnt(0)
	s_barrier
	v_mfma_f32_32x32x16_bf16 v[2:17], v[212:215], v[220:223], v[2:17]
	s_add_u32 m0, s65, 0xc000
	ds_read_b128 v[130:133], v168 offset:24592
	global_load_lds_dwordx4 v166, s[66:67]
	v_mfma_f32_32x32x16_bf16 v[18:33], v[212:215], v[224:227], v[18:33]
	s_add_u32 m0, s65, 0xd000
	ds_read_b128 v[138:141], v238 offset:32784
	global_load_lds_dwordx4 v167, s[66:67]
	v_mfma_f32_32x32x16_bf16 v[34:49], v[216:219], v[220:223], v[34:49]
	s_add_u32 m0, s65, 0xe000
	ds_read_b128 v[146:149], v242 offset:24592
	global_load_lds_dwordx4 v166, s[12:13]
	v_mfma_f32_32x32x16_bf16 v[50:65], v[216:219], v[224:227], v[50:65]
	s_add_u32 m0, s65, 0xf000
	ds_read_b128 v[134:137], v169 offset:16
	global_load_lds_dwordx4 v167, s[12:13]
	v_mfma_f32_32x32x16_bf16 v[66:81], v[212:215], v[228:231], v[66:81]
	s_add_u32 m0, s65, 0x10000
	ds_read_b128 v[142:145], v239 offset:8208
	global_load_lds_dwordx4 v166, s[62:63]
	v_mfma_f32_32x32x16_bf16 v[82:97], v[212:215], v[232:235], v[82:97]
	s_add_u32 m0, s65, 0x11000
	ds_read_b128 v[150:153], v243 offset:16
	global_load_lds_dwordx4 v167, s[62:63]
	v_mfma_f32_32x32x16_bf16 v[98:113], v[216:219], v[228:231], v[98:113]
	s_add_u32 s66, s66, 64
	s_addc_u32 s67, s67, 0
	s_add_u32 s12, s12, 64
	s_addc_u32 s13, s13, 0
	v_mfma_f32_32x32x16_bf16 v[114:129], v[216:219], v[232:235], v[114:129]
	s_add_u32 s62, s62, 64
	s_addc_u32 s63, s63, 0
	s_sub_u32 s59, s59, 1
	s_cmp_lg_u32 s59, 0
	s_cbranch_scc1 .Lhw_ffnup_d_loop
	s_waitcnt lgkmcnt(4)
	v_mfma_f32_32x32x16_bf16 v[2:17], v[130:133], v[138:141], v[2:17]
	ds_read_b128 v[212:215], v236 offset:24592
	s_waitcnt lgkmcnt(2)
	v_mfma_f32_32x32x16_bf16 v[18:33], v[130:133], v[142:145], v[18:33]
	ds_read_b128 v[220:223], v240 offset:32784
	v_mfma_f32_32x32x16_bf16 v[34:49], v[134:137], v[138:141], v[34:49]
	ds_read_b128 v[228:231], v244 offset:24592
	v_mfma_f32_32x32x16_bf16 v[50:65], v[134:137], v[142:145], v[50:65]
	ds_read_b128 v[216:219], v237 offset:16
	v_mfma_f32_32x32x16_bf16 v[66:81], v[130:133], v[146:149], v[66:81]
	ds_read_b128 v[224:227], v241 offset:8208
	s_waitcnt lgkmcnt(5)
	v_mfma_f32_32x32x16_bf16 v[82:97], v[130:133], v[150:153], v[82:97]
	ds_read_b128 v[232:235], v245 offset:16
	v_mfma_f32_32x32x16_bf16 v[98:113], v[134:137], v[146:149], v[98:113]
	v_mfma_f32_32x32x16_bf16 v[114:129], v[134:137], v[150:153], v[114:129]
	s_waitcnt vmcnt(0) lgkmcnt(0)
	s_barrier
	v_mfma_f32_32x32x16_bf16 v[2:17], v[212:215], v[220:223], v[2:17]
	ds_read_b128 v[130:133], v169 offset:24592
	v_mfma_f32_32x32x16_bf16 v[18:33], v[212:215], v[224:227], v[18:33]
	ds_read_b128 v[138:141], v239 offset:32784
	v_mfma_f32_32x32x16_bf16 v[34:49], v[216:219], v[220:223], v[34:49]
	ds_read_b128 v[146:149], v243 offset:24592
	v_mfma_f32_32x32x16_bf16 v[50:65], v[216:219], v[224:227], v[50:65]
	ds_read_b128 v[134:137], v168 offset:49168
	v_mfma_f32_32x32x16_bf16 v[66:81], v[212:215], v[228:231], v[66:81]
	ds_read_b128 v[142:145], v238 offset:57360
	v_mfma_f32_32x32x16_bf16 v[82:97], v[212:215], v[232:235], v[82:97]
	ds_read_b128 v[150:153], v242 offset:49168
	v_mfma_f32_32x32x16_bf16 v[98:113], v[216:219], v[228:231], v[98:113]
	v_mfma_f32_32x32x16_bf16 v[114:129], v[216:219], v[232:235], v[114:129]
	s_waitcnt lgkmcnt(4)
	v_mfma_f32_32x32x16_bf16 v[2:17], v[130:133], v[138:141], v[2:17]
	ds_read_b128 v[212:215], v237 offset:24592
	s_waitcnt lgkmcnt(2)
	v_mfma_f32_32x32x16_bf16 v[18:33], v[130:133], v[142:145], v[18:33]
	ds_read_b128 v[220:223], v241 offset:32784
	v_mfma_f32_32x32x16_bf16 v[34:49], v[134:137], v[138:141], v[34:49]
	ds_read_b128 v[228:231], v245 offset:24592
	v_mfma_f32_32x32x16_bf16 v[50:65], v[134:137], v[142:145], v[50:65]
	ds_read_b128 v[216:219], v236 offset:49168
	v_mfma_f32_32x32x16_bf16 v[66:81], v[130:133], v[146:149], v[66:81]
	ds_read_b128 v[224:227], v240 offset:57360
	s_waitcnt lgkmcnt(5)
	v_mfma_f32_32x32x16_bf16 v[82:97], v[130:133], v[150:153], v[82:97]
	ds_read_b128 v[232:235], v244 offset:49168
	v_mfma_f32_32x32x16_bf16 v[98:113], v[134:137], v[146:149], v[98:113]
	v_mfma_f32_32x32x16_bf16 v[114:129], v[134:137], v[150:153], v[114:129]
	s_waitcnt lgkmcnt(0)
	v_mfma_f32_32x32x16_bf16 v[2:17], v[212:215], v[220:223], v[2:17]
	v_mfma_f32_32x32x16_bf16 v[18:33], v[212:215], v[224:227], v[18:33]
	v_mfma_f32_32x32x16_bf16 v[34:49], v[216:219], v[220:223], v[34:49]
	v_mfma_f32_32x32x16_bf16 v[50:65], v[216:219], v[224:227], v[50:65]
	v_mfma_f32_32x32x16_bf16 v[66:81], v[212:215], v[228:231], v[66:81]
	v_mfma_f32_32x32x16_bf16 v[82:97], v[212:215], v[232:235], v[82:97]
	v_mfma_f32_32x32x16_bf16 v[98:113], v[216:219], v[228:231], v[98:113]
	v_mfma_f32_32x32x16_bf16 v[114:129], v[216:219], v[232:235], v[114:129]
	s_nop 7
	s_nop 7
	s_mul_i32 vcc_lo, s6, 0x1600
	s_add_u32 s66, s8, vcc_lo
	s_addc_u32 s67, s9, 0
	s_add_u32 s66, s66, s14
	s_addc_u32 s67, s67, 0
	v_mul_f32_e32 v171, 0xbfb8aa3b, v2
	v_mul_f32_e32 v172, 0xbfb8aa3b, v3
	v_mul_f32_e32 v173, 0xbfb8aa3b, v4
	v_mul_f32_e32 v174, 0xbfb8aa3b, v5
	v_exp_f32_e32 v171, v171
	v_exp_f32_e32 v172, v172
	v_exp_f32_e32 v173, v173
	v_exp_f32_e32 v174, v174
	s_nop 0
	v_add_f32_e32 v171, 1.0, v171
	v_add_f32_e32 v172, 1.0, v172
	v_add_f32_e32 v173, 1.0, v173
	v_add_f32_e32 v174, 1.0, v174
	v_rcp_f32_e32 v171, v171
	v_rcp_f32_e32 v172, v172
	v_rcp_f32_e32 v173, v173
	v_rcp_f32_e32 v174, v174
	s_nop 0
	v_mul_f32_e32 v171, v2, v171
	v_mul_f32_e32 v172, v3, v172
	v_mul_f32_e32 v173, v4, v173
	v_mul_f32_e32 v174, v5, v174
	v_mul_f32_e32 v171, v18, v171
	v_mul_f32_e32 v172, v19, v172
	v_mul_f32_e32 v173, v20, v173
	v_mul_f32_e32 v174, v21, v174
	v_cvt_pk_bf16_f32 v179, v171, v171
	v_cvt_pk_bf16_f32 v180, v172, v172
	v_cvt_pk_bf16_f32 v181, v173, v173
	v_cvt_pk_bf16_f32 v182, v174, v174
	global_store_short v162, v179, s[66:67]
	global_store_short v163, v180, s[66:67]
	global_store_short v164, v181, s[66:67]
	global_store_short v165, v182, s[66:67]
	s_add_u32 s66, s66, 0xb000
	s_addc_u32 s67, s67, 0
	v_mul_f32_e32 v171, 0xbfb8aa3b, v6
	v_mul_f32_e32 v172, 0xbfb8aa3b, v7
	v_mul_f32_e32 v173, 0xbfb8aa3b, v8
	v_mul_f32_e32 v174, 0xbfb8aa3b, v9
	v_exp_f32_e32 v171, v171
	v_exp_f32_e32 v172, v172
	v_exp_f32_e32 v173, v173
	v_exp_f32_e32 v174, v174
	s_nop 0
	v_add_f32_e32 v171, 1.0, v171
	v_add_f32_e32 v172, 1.0, v172
	v_add_f32_e32 v173, 1.0, v173
	v_add_f32_e32 v174, 1.0, v174
	v_rcp_f32_e32 v171, v171
	v_rcp_f32_e32 v172, v172
	v_rcp_f32_e32 v173, v173
	v_rcp_f32_e32 v174, v174
	s_nop 0
	v_mul_f32_e32 v171, v6, v171
	v_mul_f32_e32 v172, v7, v172
	v_mul_f32_e32 v173, v8, v173
	v_mul_f32_e32 v174, v9, v174
	v_mul_f32_e32 v171, v22, v171
	v_mul_f32_e32 v172, v23, v172
	v_mul_f32_e32 v173, v24, v173
	v_mul_f32_e32 v174, v25, v174
	v_cvt_pk_bf16_f32 v179, v171, v171
	v_cvt_pk_bf16_f32 v180, v172, v172
	v_cvt_pk_bf16_f32 v181, v173, v173
	v_cvt_pk_bf16_f32 v182, v174, v174
	global_store_short v162, v179, s[66:67]
	global_store_short v163, v180, s[66:67]
	global_store_short v164, v181, s[66:67]
	global_store_short v165, v182, s[66:67]
	s_add_u32 s66, s66, 0xb000
	s_addc_u32 s67, s67, 0
	v_mul_f32_e32 v171, 0xbfb8aa3b, v10
	v_mul_f32_e32 v172, 0xbfb8aa3b, v11
	v_mul_f32_e32 v173, 0xbfb8aa3b, v12
	v_mul_f32_e32 v174, 0xbfb8aa3b, v13
	v_exp_f32_e32 v171, v171
	v_exp_f32_e32 v172, v172
	v_exp_f32_e32 v173, v173
	v_exp_f32_e32 v174, v174
	s_nop 0
	v_add_f32_e32 v171, 1.0, v171
	v_add_f32_e32 v172, 1.0, v172
	v_add_f32_e32 v173, 1.0, v173
	v_add_f32_e32 v174, 1.0, v174
	v_rcp_f32_e32 v171, v171
	v_rcp_f32_e32 v172, v172
	v_rcp_f32_e32 v173, v173
	v_rcp_f32_e32 v174, v174
	s_nop 0
	v_mul_f32_e32 v171, v10, v171
	v_mul_f32_e32 v172, v11, v172
	v_mul_f32_e32 v173, v12, v173
	v_mul_f32_e32 v174, v13, v174
	v_mul_f32_e32 v171, v26, v171
	v_mul_f32_e32 v172, v27, v172
	v_mul_f32_e32 v173, v28, v173
	v_mul_f32_e32 v174, v29, v174
	v_cvt_pk_bf16_f32 v179, v171, v171
	v_cvt_pk_bf16_f32 v180, v172, v172
	v_cvt_pk_bf16_f32 v181, v173, v173
	v_cvt_pk_bf16_f32 v182, v174, v174
	global_store_short v162, v179, s[66:67]
	global_store_short v163, v180, s[66:67]
	global_store_short v164, v181, s[66:67]
	global_store_short v165, v182, s[66:67]
	s_add_u32 s66, s66, 0xb000
	s_addc_u32 s67, s67, 0
	v_mul_f32_e32 v171, 0xbfb8aa3b, v14
	v_mul_f32_e32 v172, 0xbfb8aa3b, v15
	v_mul_f32_e32 v173, 0xbfb8aa3b, v16
	v_mul_f32_e32 v174, 0xbfb8aa3b, v17
	v_exp_f32_e32 v171, v171
	v_exp_f32_e32 v172, v172
	v_exp_f32_e32 v173, v173
	v_exp_f32_e32 v174, v174
	s_nop 0
	v_add_f32_e32 v171, 1.0, v171
	v_add_f32_e32 v172, 1.0, v172
	v_add_f32_e32 v173, 1.0, v173
	v_add_f32_e32 v174, 1.0, v174
	v_rcp_f32_e32 v171, v171
	v_rcp_f32_e32 v172, v172
	v_rcp_f32_e32 v173, v173
	v_rcp_f32_e32 v174, v174
	s_nop 0
	v_mul_f32_e32 v171, v14, v171
	v_mul_f32_e32 v172, v15, v172
	v_mul_f32_e32 v173, v16, v173
	v_mul_f32_e32 v174, v17, v174
	v_mul_f32_e32 v171, v30, v171
	v_mul_f32_e32 v172, v31, v172
	v_mul_f32_e32 v173, v32, v173
	v_mul_f32_e32 v174, v33, v174
	v_cvt_pk_bf16_f32 v179, v171, v171
	v_cvt_pk_bf16_f32 v180, v172, v172
	v_cvt_pk_bf16_f32 v181, v173, v173
	v_cvt_pk_bf16_f32 v182, v174, v174
	global_store_short v162, v179, s[66:67]
	global_store_short v163, v180, s[66:67]
	global_store_short v164, v181, s[66:67]
	global_store_short v165, v182, s[66:67]
	s_add_u32 s66, s66, 0xb000
	s_addc_u32 s67, s67, 0
	v_mul_f32_e32 v171, 0xbfb8aa3b, v34
	v_mul_f32_e32 v172, 0xbfb8aa3b, v35
	v_mul_f32_e32 v173, 0xbfb8aa3b, v36
	v_mul_f32_e32 v174, 0xbfb8aa3b, v37
	v_exp_f32_e32 v171, v171
	v_exp_f32_e32 v172, v172
	v_exp_f32_e32 v173, v173
	v_exp_f32_e32 v174, v174
	s_nop 0
	v_add_f32_e32 v171, 1.0, v171
	v_add_f32_e32 v172, 1.0, v172
	v_add_f32_e32 v173, 1.0, v173
	v_add_f32_e32 v174, 1.0, v174
	v_rcp_f32_e32 v171, v171
	v_rcp_f32_e32 v172, v172
	v_rcp_f32_e32 v173, v173
	v_rcp_f32_e32 v174, v174
	s_nop 0
	v_mul_f32_e32 v171, v34, v171
	v_mul_f32_e32 v172, v35, v172
	v_mul_f32_e32 v173, v36, v173
	v_mul_f32_e32 v174, v37, v174
	v_mul_f32_e32 v171, v50, v171
	v_mul_f32_e32 v172, v51, v172
	v_mul_f32_e32 v173, v52, v173
	v_mul_f32_e32 v174, v53, v174
	v_cvt_pk_bf16_f32 v179, v171, v171
	v_cvt_pk_bf16_f32 v180, v172, v172
	v_cvt_pk_bf16_f32 v181, v173, v173
	v_cvt_pk_bf16_f32 v182, v174, v174
	global_store_short v162, v179, s[66:67]
	global_store_short v163, v180, s[66:67]
	global_store_short v164, v181, s[66:67]
	global_store_short v165, v182, s[66:67]
	s_add_u32 s66, s66, 0xb000
	s_addc_u32 s67, s67, 0
	v_mul_f32_e32 v171, 0xbfb8aa3b, v38
	v_mul_f32_e32 v172, 0xbfb8aa3b, v39
	v_mul_f32_e32 v173, 0xbfb8aa3b, v40
	v_mul_f32_e32 v174, 0xbfb8aa3b, v41
	v_exp_f32_e32 v171, v171
	v_exp_f32_e32 v172, v172
	v_exp_f32_e32 v173, v173
	v_exp_f32_e32 v174, v174
	s_nop 0
	v_add_f32_e32 v171, 1.0, v171
	v_add_f32_e32 v172, 1.0, v172
	v_add_f32_e32 v173, 1.0, v173
	v_add_f32_e32 v174, 1.0, v174
	v_rcp_f32_e32 v171, v171
	v_rcp_f32_e32 v172, v172
	v_rcp_f32_e32 v173, v173
	v_rcp_f32_e32 v174, v174
	s_nop 0
	v_mul_f32_e32 v171, v38, v171
	v_mul_f32_e32 v172, v39, v172
	v_mul_f32_e32 v173, v40, v173
	v_mul_f32_e32 v174, v41, v174
	v_mul_f32_e32 v171, v54, v171
	v_mul_f32_e32 v172, v55, v172
	v_mul_f32_e32 v173, v56, v173
	v_mul_f32_e32 v174, v57, v174
	v_cvt_pk_bf16_f32 v179, v171, v171
	v_cvt_pk_bf16_f32 v180, v172, v172
	v_cvt_pk_bf16_f32 v181, v173, v173
	v_cvt_pk_bf16_f32 v182, v174, v174
	global_store_short v162, v179, s[66:67]
	global_store_short v163, v180, s[66:67]
	global_store_short v164, v181, s[66:67]
	global_store_short v165, v182, s[66:67]
	s_add_u32 s66, s66, 0xb000
	s_addc_u32 s67, s67, 0
	v_mul_f32_e32 v171, 0xbfb8aa3b, v42
	v_mul_f32_e32 v172, 0xbfb8aa3b, v43
	v_mul_f32_e32 v173, 0xbfb8aa3b, v44
	v_mul_f32_e32 v174, 0xbfb8aa3b, v45
	v_exp_f32_e32 v171, v171
	v_exp_f32_e32 v172, v172
	v_exp_f32_e32 v173, v173
	v_exp_f32_e32 v174, v174
	s_nop 0
	v_add_f32_e32 v171, 1.0, v171
	v_add_f32_e32 v172, 1.0, v172
	v_add_f32_e32 v173, 1.0, v173
	v_add_f32_e32 v174, 1.0, v174
	v_rcp_f32_e32 v171, v171
	v_rcp_f32_e32 v172, v172
	v_rcp_f32_e32 v173, v173
	v_rcp_f32_e32 v174, v174
	s_nop 0
	v_mul_f32_e32 v171, v42, v171
	v_mul_f32_e32 v172, v43, v172
	v_mul_f32_e32 v173, v44, v173
	v_mul_f32_e32 v174, v45, v174
	v_mul_f32_e32 v171, v58, v171
	v_mul_f32_e32 v172, v59, v172
	v_mul_f32_e32 v173, v60, v173
	v_mul_f32_e32 v174, v61, v174
	v_cvt_pk_bf16_f32 v179, v171, v171
	v_cvt_pk_bf16_f32 v180, v172, v172
	v_cvt_pk_bf16_f32 v181, v173, v173
	v_cvt_pk_bf16_f32 v182, v174, v174
	global_store_short v162, v179, s[66:67]
	global_store_short v163, v180, s[66:67]
	global_store_short v164, v181, s[66:67]
	global_store_short v165, v182, s[66:67]
	s_add_u32 s66, s66, 0xb000
	s_addc_u32 s67, s67, 0
	v_mul_f32_e32 v171, 0xbfb8aa3b, v46
	v_mul_f32_e32 v172, 0xbfb8aa3b, v47
	v_mul_f32_e32 v173, 0xbfb8aa3b, v48
	v_mul_f32_e32 v174, 0xbfb8aa3b, v49
	v_exp_f32_e32 v171, v171
	v_exp_f32_e32 v172, v172
	v_exp_f32_e32 v173, v173
	v_exp_f32_e32 v174, v174
	s_nop 0
	v_add_f32_e32 v171, 1.0, v171
	v_add_f32_e32 v172, 1.0, v172
	v_add_f32_e32 v173, 1.0, v173
	v_add_f32_e32 v174, 1.0, v174
	v_rcp_f32_e32 v171, v171
	v_rcp_f32_e32 v172, v172
	v_rcp_f32_e32 v173, v173
	v_rcp_f32_e32 v174, v174
	s_nop 0
	v_mul_f32_e32 v171, v46, v171
	v_mul_f32_e32 v172, v47, v172
	v_mul_f32_e32 v173, v48, v173
	v_mul_f32_e32 v174, v49, v174
	v_mul_f32_e32 v171, v62, v171
	v_mul_f32_e32 v172, v63, v172
	v_mul_f32_e32 v173, v64, v173
	v_mul_f32_e32 v174, v65, v174
	v_cvt_pk_bf16_f32 v179, v171, v171
	v_cvt_pk_bf16_f32 v180, v172, v172
	v_cvt_pk_bf16_f32 v181, v173, v173
	v_cvt_pk_bf16_f32 v182, v174, v174
	global_store_short v162, v179, s[66:67]
	global_store_short v163, v180, s[66:67]
	global_store_short v164, v181, s[66:67]
	global_store_short v165, v182, s[66:67]
	s_sub_u32 s66, s66, 0x4cf80
	s_subb_u32 s67, s67, 0
	v_mul_f32_e32 v171, 0xbfb8aa3b, v66
	v_mul_f32_e32 v172, 0xbfb8aa3b, v67
	v_mul_f32_e32 v173, 0xbfb8aa3b, v68
	v_mul_f32_e32 v174, 0xbfb8aa3b, v69
	v_exp_f32_e32 v171, v171
	v_exp_f32_e32 v172, v172
	v_exp_f32_e32 v173, v173
	v_exp_f32_e32 v174, v174
	s_nop 0
	v_add_f32_e32 v171, 1.0, v171
	v_add_f32_e32 v172, 1.0, v172
	v_add_f32_e32 v173, 1.0, v173
	v_add_f32_e32 v174, 1.0, v174
	v_rcp_f32_e32 v171, v171
	v_rcp_f32_e32 v172, v172
	v_rcp_f32_e32 v173, v173
	v_rcp_f32_e32 v174, v174
	s_nop 0
	v_mul_f32_e32 v171, v66, v171
	v_mul_f32_e32 v172, v67, v172
	v_mul_f32_e32 v173, v68, v173
	v_mul_f32_e32 v174, v69, v174
	v_mul_f32_e32 v171, v82, v171
	v_mul_f32_e32 v172, v83, v172
	v_mul_f32_e32 v173, v84, v173
	v_mul_f32_e32 v174, v85, v174
	v_cvt_pk_bf16_f32 v179, v171, v171
	v_cvt_pk_bf16_f32 v180, v172, v172
	v_cvt_pk_bf16_f32 v181, v173, v173
	v_cvt_pk_bf16_f32 v182, v174, v174
	global_store_short v162, v179, s[66:67]
	global_store_short v163, v180, s[66:67]
	global_store_short v164, v181, s[66:67]
	global_store_short v165, v182, s[66:67]
	s_add_u32 s66, s66, 0xb000
	s_addc_u32 s67, s67, 0
	v_mul_f32_e32 v171, 0xbfb8aa3b, v70
	v_mul_f32_e32 v172, 0xbfb8aa3b, v71
	v_mul_f32_e32 v173, 0xbfb8aa3b, v72
	v_mul_f32_e32 v174, 0xbfb8aa3b, v73
	v_exp_f32_e32 v171, v171
	v_exp_f32_e32 v172, v172
	v_exp_f32_e32 v173, v173
	v_exp_f32_e32 v174, v174
	s_nop 0
	v_add_f32_e32 v171, 1.0, v171
	v_add_f32_e32 v172, 1.0, v172
	v_add_f32_e32 v173, 1.0, v173
	v_add_f32_e32 v174, 1.0, v174
	v_rcp_f32_e32 v171, v171
	v_rcp_f32_e32 v172, v172
	v_rcp_f32_e32 v173, v173
	v_rcp_f32_e32 v174, v174
	s_nop 0
	v_mul_f32_e32 v171, v70, v171
	v_mul_f32_e32 v172, v71, v172
	v_mul_f32_e32 v173, v72, v173
	v_mul_f32_e32 v174, v73, v174
	v_mul_f32_e32 v171, v86, v171
	v_mul_f32_e32 v172, v87, v172
	v_mul_f32_e32 v173, v88, v173
	v_mul_f32_e32 v174, v89, v174
	v_cvt_pk_bf16_f32 v179, v171, v171
	v_cvt_pk_bf16_f32 v180, v172, v172
	v_cvt_pk_bf16_f32 v181, v173, v173
	v_cvt_pk_bf16_f32 v182, v174, v174
	global_store_short v162, v179, s[66:67]
	global_store_short v163, v180, s[66:67]
	global_store_short v164, v181, s[66:67]
	global_store_short v165, v182, s[66:67]
	s_add_u32 s66, s66, 0xb000
	s_addc_u32 s67, s67, 0
	v_mul_f32_e32 v171, 0xbfb8aa3b, v74
	v_mul_f32_e32 v172, 0xbfb8aa3b, v75
	v_mul_f32_e32 v173, 0xbfb8aa3b, v76
	v_mul_f32_e32 v174, 0xbfb8aa3b, v77
	v_exp_f32_e32 v171, v171
	v_exp_f32_e32 v172, v172
	v_exp_f32_e32 v173, v173
	v_exp_f32_e32 v174, v174
	s_nop 0
	v_add_f32_e32 v171, 1.0, v171
	v_add_f32_e32 v172, 1.0, v172
	v_add_f32_e32 v173, 1.0, v173
	v_add_f32_e32 v174, 1.0, v174
	v_rcp_f32_e32 v171, v171
	v_rcp_f32_e32 v172, v172
	v_rcp_f32_e32 v173, v173
	v_rcp_f32_e32 v174, v174
	s_nop 0
	v_mul_f32_e32 v171, v74, v171
	v_mul_f32_e32 v172, v75, v172
	v_mul_f32_e32 v173, v76, v173
	v_mul_f32_e32 v174, v77, v174
	v_mul_f32_e32 v171, v90, v171
	v_mul_f32_e32 v172, v91, v172
	v_mul_f32_e32 v173, v92, v173
	v_mul_f32_e32 v174, v93, v174
	v_cvt_pk_bf16_f32 v179, v171, v171
	v_cvt_pk_bf16_f32 v180, v172, v172
	v_cvt_pk_bf16_f32 v181, v173, v173
	v_cvt_pk_bf16_f32 v182, v174, v174
	global_store_short v162, v179, s[66:67]
	global_store_short v163, v180, s[66:67]
	global_store_short v164, v181, s[66:67]
	global_store_short v165, v182, s[66:67]
	s_add_u32 s66, s66, 0xb000
	s_addc_u32 s67, s67, 0
	v_mul_f32_e32 v171, 0xbfb8aa3b, v78
	v_mul_f32_e32 v172, 0xbfb8aa3b, v79
	v_mul_f32_e32 v173, 0xbfb8aa3b, v80
	v_mul_f32_e32 v174, 0xbfb8aa3b, v81
	v_exp_f32_e32 v171, v171
	v_exp_f32_e32 v172, v172
	v_exp_f32_e32 v173, v173
	v_exp_f32_e32 v174, v174
	s_nop 0
	v_add_f32_e32 v171, 1.0, v171
	v_add_f32_e32 v172, 1.0, v172
	v_add_f32_e32 v173, 1.0, v173
	v_add_f32_e32 v174, 1.0, v174
	v_rcp_f32_e32 v171, v171
	v_rcp_f32_e32 v172, v172
	v_rcp_f32_e32 v173, v173
	v_rcp_f32_e32 v174, v174
	s_nop 0
	v_mul_f32_e32 v171, v78, v171
	v_mul_f32_e32 v172, v79, v172
	v_mul_f32_e32 v173, v80, v173
	v_mul_f32_e32 v174, v81, v174
	v_mul_f32_e32 v171, v94, v171
	v_mul_f32_e32 v172, v95, v172
	v_mul_f32_e32 v173, v96, v173
	v_mul_f32_e32 v174, v97, v174
	v_cvt_pk_bf16_f32 v179, v171, v171
	v_cvt_pk_bf16_f32 v180, v172, v172
	v_cvt_pk_bf16_f32 v181, v173, v173
	v_cvt_pk_bf16_f32 v182, v174, v174
	global_store_short v162, v179, s[66:67]
	global_store_short v163, v180, s[66:67]
	global_store_short v164, v181, s[66:67]
	global_store_short v165, v182, s[66:67]
	s_add_u32 s66, s66, 0xb000
	s_addc_u32 s67, s67, 0
	v_mul_f32_e32 v171, 0xbfb8aa3b, v98
	v_mul_f32_e32 v172, 0xbfb8aa3b, v99
	v_mul_f32_e32 v173, 0xbfb8aa3b, v100
	v_mul_f32_e32 v174, 0xbfb8aa3b, v101
	v_exp_f32_e32 v171, v171
	v_exp_f32_e32 v172, v172
	v_exp_f32_e32 v173, v173
	v_exp_f32_e32 v174, v174
	s_nop 0
	v_add_f32_e32 v171, 1.0, v171
	v_add_f32_e32 v172, 1.0, v172
	v_add_f32_e32 v173, 1.0, v173
	v_add_f32_e32 v174, 1.0, v174
	v_rcp_f32_e32 v171, v171
	v_rcp_f32_e32 v172, v172
	v_rcp_f32_e32 v173, v173
	v_rcp_f32_e32 v174, v174
	s_nop 0
	v_mul_f32_e32 v171, v98, v171
	v_mul_f32_e32 v172, v99, v172
	v_mul_f32_e32 v173, v100, v173
	v_mul_f32_e32 v174, v101, v174
	v_mul_f32_e32 v171, v114, v171
	v_mul_f32_e32 v172, v115, v172
	v_mul_f32_e32 v173, v116, v173
	v_mul_f32_e32 v174, v117, v174
	v_cvt_pk_bf16_f32 v179, v171, v171
	v_cvt_pk_bf16_f32 v180, v172, v172
	v_cvt_pk_bf16_f32 v181, v173, v173
	v_cvt_pk_bf16_f32 v182, v174, v174
	global_store_short v162, v179, s[66:67]
	global_store_short v163, v180, s[66:67]
	global_store_short v164, v181, s[66:67]
	global_store_short v165, v182, s[66:67]
	s_add_u32 s66, s66, 0xb000
	s_addc_u32 s67, s67, 0
	v_mul_f32_e32 v171, 0xbfb8aa3b, v102
	v_mul_f32_e32 v172, 0xbfb8aa3b, v103
	v_mul_f32_e32 v173, 0xbfb8aa3b, v104
	v_mul_f32_e32 v174, 0xbfb8aa3b, v105
	v_exp_f32_e32 v171, v171
	v_exp_f32_e32 v172, v172
	v_exp_f32_e32 v173, v173
	v_exp_f32_e32 v174, v174
	s_nop 0
	v_add_f32_e32 v171, 1.0, v171
	v_add_f32_e32 v172, 1.0, v172
	v_add_f32_e32 v173, 1.0, v173
	v_add_f32_e32 v174, 1.0, v174
	v_rcp_f32_e32 v171, v171
	v_rcp_f32_e32 v172, v172
	v_rcp_f32_e32 v173, v173
	v_rcp_f32_e32 v174, v174
	s_nop 0
	v_mul_f32_e32 v171, v102, v171
	v_mul_f32_e32 v172, v103, v172
	v_mul_f32_e32 v173, v104, v173
	v_mul_f32_e32 v174, v105, v174
	v_mul_f32_e32 v171, v118, v171
	v_mul_f32_e32 v172, v119, v172
	v_mul_f32_e32 v173, v120, v173
	v_mul_f32_e32 v174, v121, v174
	v_cvt_pk_bf16_f32 v179, v171, v171
	v_cvt_pk_bf16_f32 v180, v172, v172
	v_cvt_pk_bf16_f32 v181, v173, v173
	v_cvt_pk_bf16_f32 v182, v174, v174
	global_store_short v162, v179, s[66:67]
	global_store_short v163, v180, s[66:67]
	global_store_short v164, v181, s[66:67]
	global_store_short v165, v182, s[66:67]
	s_add_u32 s66, s66, 0xb000
	s_addc_u32 s67, s67, 0
	v_mul_f32_e32 v171, 0xbfb8aa3b, v106
	v_mul_f32_e32 v172, 0xbfb8aa3b, v107
	v_mul_f32_e32 v173, 0xbfb8aa3b, v108
	v_mul_f32_e32 v174, 0xbfb8aa3b, v109
	v_exp_f32_e32 v171, v171
	v_exp_f32_e32 v172, v172
	v_exp_f32_e32 v173, v173
	v_exp_f32_e32 v174, v174
	s_nop 0
	v_add_f32_e32 v171, 1.0, v171
	v_add_f32_e32 v172, 1.0, v172
	v_add_f32_e32 v173, 1.0, v173
	v_add_f32_e32 v174, 1.0, v174
	v_rcp_f32_e32 v171, v171
	v_rcp_f32_e32 v172, v172
	v_rcp_f32_e32 v173, v173
	v_rcp_f32_e32 v174, v174
	s_nop 0
	v_mul_f32_e32 v171, v106, v171
	v_mul_f32_e32 v172, v107, v172
	v_mul_f32_e32 v173, v108, v173
	v_mul_f32_e32 v174, v109, v174
	v_mul_f32_e32 v171, v122, v171
	v_mul_f32_e32 v172, v123, v172
	v_mul_f32_e32 v173, v124, v173
	v_mul_f32_e32 v174, v125, v174
	v_cvt_pk_bf16_f32 v179, v171, v171
	v_cvt_pk_bf16_f32 v180, v172, v172
	v_cvt_pk_bf16_f32 v181, v173, v173
	v_cvt_pk_bf16_f32 v182, v174, v174
	global_store_short v162, v179, s[66:67]
	global_store_short v163, v180, s[66:67]
	global_store_short v164, v181, s[66:67]
	global_store_short v165, v182, s[66:67]
	s_add_u32 s66, s66, 0xb000
	s_addc_u32 s67, s67, 0
	v_mul_f32_e32 v171, 0xbfb8aa3b, v110
	v_mul_f32_e32 v172, 0xbfb8aa3b, v111
	v_mul_f32_e32 v173, 0xbfb8aa3b, v112
	v_mul_f32_e32 v174, 0xbfb8aa3b, v113
	v_exp_f32_e32 v171, v171
	v_exp_f32_e32 v172, v172
	v_exp_f32_e32 v173, v173
	v_exp_f32_e32 v174, v174
	s_nop 0
	v_add_f32_e32 v171, 1.0, v171
	v_add_f32_e32 v172, 1.0, v172
	v_add_f32_e32 v173, 1.0, v173
	v_add_f32_e32 v174, 1.0, v174
	v_rcp_f32_e32 v171, v171
	v_rcp_f32_e32 v172, v172
	v_rcp_f32_e32 v173, v173
	v_rcp_f32_e32 v174, v174
	s_nop 0
	v_mul_f32_e32 v171, v110, v171
	v_mul_f32_e32 v172, v111, v172
	v_mul_f32_e32 v173, v112, v173
	v_mul_f32_e32 v174, v113, v174
	v_mul_f32_e32 v171, v126, v171
	v_mul_f32_e32 v172, v127, v172
	v_mul_f32_e32 v173, v128, v173
	v_mul_f32_e32 v174, v129, v174
	v_cvt_pk_bf16_f32 v179, v171, v171
	v_cvt_pk_bf16_f32 v180, v172, v172
	v_cvt_pk_bf16_f32 v181, v173, v173
	v_cvt_pk_bf16_f32 v182, v174, v174
	global_store_short v162, v179, s[66:67]
	global_store_short v163, v180, s[66:67]
	global_store_short v164, v181, s[66:67]
	global_store_short v165, v182, s[66:67]
	v_readlane_b32 s62, v246, 14
	s_nop 0
	s_add_i32 s2, s2, s62
	s_branch .Lhw_ffnup_dloop
